# GEMM K-loops: LDS-DMA loads use SGPR base + 32-bit VGPR offset (saddr form) instead of per-lane 64-bit VALU address adds, all 6 loops
# speedup vs baseline: 1.0127x; 1.0127x over previous
.LBB0_131:
	ds_read_b128 v[152:155], v149
	ds_read_b128 v[156:159], v149 offset:1024
	ds_read_b128 v[160:163], v149 offset:2048
	ds_read_b128 v[164:167], v149 offset:3072
	s_add_u32 s26, s20, 0xfffc0080
	s_addc_u32 s27, s21, -1
	s_cmp_eq_u32 s57, 12
	s_cselect_b32 s29, s13, s27
	s_cselect_b32 s28, s53, s26
	s_cselect_b32 s27, s11, s56
	s_cselect_b32 s26, s54, s55
	s_add_i32 m0, s19, 0xc000
	ds_read_b128 v[168:171], v150
	ds_read_b128 v[172:175], v150 offset:1024
	ds_read_b128 v[176:179], v150 offset:2048
	ds_read_b128 v[180:183], v150 offset:3072
	ds_read_b128 v[184:187], v150 offset:4096
	ds_read_b128 v[188:191], v150 offset:5120
	ds_read_b128 v[192:195], v150 offset:6144
	ds_read_b128 v[196:199], v150 offset:7168
	global_load_lds_dwordx4 v136, s[20:21]
	s_add_i32 m0, s19, 0xe000
	s_nop 0
	global_load_lds_dwordx4 v138, s[20:21]
	s_waitcnt lgkmcnt(8)
	s_barrier
	s_waitcnt lgkmcnt(0)
	s_setprio 1
	s_waitcnt lgkmcnt(0)
	v_mfma_f32_16x16x32_bf16 v[124:127], v[152:155], v[168:171], v[124:127]
	v_mfma_f32_16x16x32_bf16 v[120:123], v[160:163], v[168:171], v[120:123]
	v_mfma_f32_16x16x32_bf16 v[108:111], v[152:155], v[176:179], v[108:111]
	v_mfma_f32_16x16x32_bf16 v[104:107], v[160:163], v[176:179], v[104:107]
	v_mfma_f32_16x16x32_bf16 v[92:95], v[152:155], v[184:187], v[92:95]
	v_mfma_f32_16x16x32_bf16 v[88:91], v[160:163], v[184:187], v[88:91]
	v_mfma_f32_16x16x32_bf16 v[76:79], v[152:155], v[192:195], v[76:79]
	v_mfma_f32_16x16x32_bf16 v[72:75], v[160:163], v[192:195], v[72:75]
	v_mfma_f32_16x16x32_bf16 v[124:127], v[156:159], v[172:175], v[124:127]
	v_mfma_f32_16x16x32_bf16 v[120:123], v[164:167], v[172:175], v[120:123]
	v_mfma_f32_16x16x32_bf16 v[108:111], v[156:159], v[180:183], v[108:111]
	v_mfma_f32_16x16x32_bf16 v[104:107], v[164:167], v[180:183], v[104:107]
	v_mfma_f32_16x16x32_bf16 v[92:95], v[156:159], v[188:191], v[92:95]
	v_mfma_f32_16x16x32_bf16 v[88:91], v[164:167], v[188:191], v[88:91]
	v_mfma_f32_16x16x32_bf16 v[76:79], v[156:159], v[196:199], v[76:79]
	v_mfma_f32_16x16x32_bf16 v[72:75], v[164:167], v[196:199], v[72:75]
	s_setprio 0
	s_barrier
	s_add_i32 s58, s47, s38
	s_add_u32 s80, s26, 0x80
	s_addc_u32 s81, s27, 0
	s_mov_b32 m0, s58
	ds_read_b128 v[200:203], v151
	ds_read_b128 v[204:207], v151 offset:1024
	ds_read_b128 v[208:211], v151 offset:2048
	ds_read_b128 v[212:215], v151 offset:3072
	global_load_lds_dwordx4 v132, s[26:27]
	s_add_i32 m0, s58, 0x2000
	s_nop 0
	global_load_lds_dwordx4 v128, s[26:27]
	s_barrier
	s_waitcnt lgkmcnt(0)
	s_setprio 1
	s_waitcnt lgkmcnt(0)
	v_mfma_f32_16x16x32_bf16 v[116:119], v[200:203], v[168:171], v[116:119]
	v_mfma_f32_16x16x32_bf16 v[112:115], v[208:211], v[168:171], v[112:115]
	v_mfma_f32_16x16x32_bf16 v[100:103], v[200:203], v[176:179], v[100:103]
	v_mfma_f32_16x16x32_bf16 v[96:99], v[208:211], v[176:179], v[96:99]
	v_mfma_f32_16x16x32_bf16 v[84:87], v[200:203], v[184:187], v[84:87]
	v_mfma_f32_16x16x32_bf16 v[80:83], v[208:211], v[184:187], v[80:83]
	v_mfma_f32_16x16x32_bf16 v[68:71], v[200:203], v[192:195], v[68:71]
	v_mfma_f32_16x16x32_bf16 v[64:67], v[208:211], v[192:195], v[64:67]
	v_mfma_f32_16x16x32_bf16 v[116:119], v[204:207], v[172:175], v[116:119]
	v_mfma_f32_16x16x32_bf16 v[112:115], v[212:215], v[172:175], v[112:115]
	v_mfma_f32_16x16x32_bf16 v[100:103], v[204:207], v[180:183], v[100:103]
	v_mfma_f32_16x16x32_bf16 v[96:99], v[212:215], v[180:183], v[96:99]
	v_mfma_f32_16x16x32_bf16 v[84:87], v[204:207], v[188:191], v[84:87]
	v_mfma_f32_16x16x32_bf16 v[80:83], v[212:215], v[188:191], v[80:83]
	v_mfma_f32_16x16x32_bf16 v[68:71], v[204:207], v[196:199], v[68:71]
	v_mfma_f32_16x16x32_bf16 v[64:67], v[212:215], v[196:199], v[64:67]
	s_setprio 0
	s_mov_b32 m0, s19
	s_add_u32 s82, s28, 0x80
	s_addc_u32 s83, s29, 0
	s_barrier
	ds_read_b128 v[168:171], v150 offset:16384
	ds_read_b128 v[172:175], v150 offset:17408
	ds_read_b128 v[176:179], v150 offset:18432
	ds_read_b128 v[180:183], v150 offset:19456
	ds_read_b128 v[184:187], v150 offset:20480
	ds_read_b128 v[188:191], v150 offset:21504
	ds_read_b128 v[192:195], v150 offset:22528
	ds_read_b128 v[196:199], v150 offset:23552
	global_load_lds_dwordx4 v134, s[28:29]
	s_mov_b32 m0, s42
	s_nop 0
	global_load_lds_dwordx4 v130, s[28:29]
	s_barrier
	s_waitcnt lgkmcnt(0)
	s_setprio 1
	s_waitcnt lgkmcnt(0)
	v_mfma_f32_16x16x32_bf16 v[60:63], v[152:155], v[168:171], v[60:63]
	v_mfma_f32_16x16x32_bf16 v[56:59], v[160:163], v[168:171], v[56:59]
	v_mfma_f32_16x16x32_bf16 v[44:47], v[152:155], v[176:179], v[44:47]
	v_mfma_f32_16x16x32_bf16 v[40:43], v[160:163], v[176:179], v[40:43]
	v_mfma_f32_16x16x32_bf16 v[28:31], v[152:155], v[184:187], v[28:31]
	v_mfma_f32_16x16x32_bf16 v[24:27], v[160:163], v[184:187], v[24:27]
	v_mfma_f32_16x16x32_bf16 v[12:15], v[152:155], v[192:195], v[12:15]
	v_mfma_f32_16x16x32_bf16 v[8:11], v[160:163], v[192:195], v[8:11]
	v_mfma_f32_16x16x32_bf16 v[60:63], v[156:159], v[172:175], v[60:63]
	v_mfma_f32_16x16x32_bf16 v[56:59], v[164:167], v[172:175], v[56:59]
	v_mfma_f32_16x16x32_bf16 v[44:47], v[156:159], v[180:183], v[44:47]
	v_mfma_f32_16x16x32_bf16 v[40:43], v[164:167], v[180:183], v[40:43]
	v_mfma_f32_16x16x32_bf16 v[28:31], v[156:159], v[188:191], v[28:31]
	v_mfma_f32_16x16x32_bf16 v[24:27], v[164:167], v[188:191], v[24:27]
	v_mfma_f32_16x16x32_bf16 v[12:15], v[156:159], v[196:199], v[12:15]
	v_mfma_f32_16x16x32_bf16 v[8:11], v[164:167], v[196:199], v[8:11]
	s_setprio 0
	s_barrier
	s_add_u32 s58, s26, 0x40000
	s_addc_u32 s59, s27, 0
	s_add_i32 s60, s48, s38
	s_mov_b32 m0, s60
	s_nop 0
	global_load_lds_dwordx4 v132, s[58:59]
	s_add_i32 m0, s60, 0x2000
	s_nop 0
	global_load_lds_dwordx4 v128, s[58:59]
	s_waitcnt vmcnt(6)
	s_barrier
	s_setprio 1
	v_mfma_f32_16x16x32_bf16 v[52:55], v[200:203], v[168:171], v[52:55]
	v_mfma_f32_16x16x32_bf16 v[48:51], v[208:211], v[168:171], v[48:51]
	v_mfma_f32_16x16x32_bf16 v[36:39], v[200:203], v[176:179], v[36:39]
	v_mfma_f32_16x16x32_bf16 v[32:35], v[208:211], v[176:179], v[32:35]
	v_mfma_f32_16x16x32_bf16 v[20:23], v[200:203], v[184:187], v[20:23]
	v_mfma_f32_16x16x32_bf16 v[16:19], v[208:211], v[184:187], v[16:19]
	v_mfma_f32_16x16x32_bf16 v[4:7], v[200:203], v[192:195], v[4:7]
	v_mfma_f32_16x16x32_bf16 v[0:3], v[208:211], v[192:195], v[0:3]
	v_mfma_f32_16x16x32_bf16 v[52:55], v[204:207], v[172:175], v[52:55]
	v_mfma_f32_16x16x32_bf16 v[48:51], v[212:215], v[172:175], v[48:51]
	v_mfma_f32_16x16x32_bf16 v[36:39], v[204:207], v[180:183], v[36:39]
	v_mfma_f32_16x16x32_bf16 v[32:35], v[212:215], v[180:183], v[32:35]
	v_mfma_f32_16x16x32_bf16 v[20:23], v[204:207], v[188:191], v[20:23]
	v_mfma_f32_16x16x32_bf16 v[16:19], v[212:215], v[188:191], v[16:19]
	v_mfma_f32_16x16x32_bf16 v[4:7], v[204:207], v[196:199], v[4:7]
	v_mfma_f32_16x16x32_bf16 v[0:3], v[212:215], v[196:199], v[0:3]
	s_setprio 0
	s_add_i32 s58, 0, 0x18000
	v_add_u32_e32 v164, s58, v145
	s_barrier
	ds_read_b128 v[152:155], v164
	ds_read_b128 v[156:159], v164 offset:1024
	ds_read_b128 v[160:163], v164 offset:2048
	ds_read_b128 v[164:167], v164 offset:3072
	s_add_u32 s28, s28, 0x40000
	s_addc_u32 s29, s29, 0
	s_mov_b32 m0, s43
	ds_read_b128 v[168:171], v150 offset:32768
	ds_read_b128 v[172:175], v150 offset:33792
	ds_read_b128 v[176:179], v150 offset:34816
	ds_read_b128 v[180:183], v150 offset:35840
	ds_read_b128 v[184:187], v150 offset:36864
	ds_read_b128 v[188:191], v150 offset:37888
	ds_read_b128 v[192:195], v150 offset:38912
	ds_read_b128 v[196:199], v150 offset:39936
	global_load_lds_dwordx4 v134, s[28:29]
	s_mov_b32 m0, s44
	s_nop 0
	global_load_lds_dwordx4 v130, s[28:29]
	s_waitcnt lgkmcnt(8)
	s_barrier
	s_waitcnt lgkmcnt(0)
	s_setprio 1
	s_waitcnt lgkmcnt(0)
	v_mfma_f32_16x16x32_bf16 v[124:127], v[152:155], v[168:171], v[124:127]
	v_mfma_f32_16x16x32_bf16 v[120:123], v[160:163], v[168:171], v[120:123]
	v_mfma_f32_16x16x32_bf16 v[108:111], v[152:155], v[176:179], v[108:111]
	v_mfma_f32_16x16x32_bf16 v[104:107], v[160:163], v[176:179], v[104:107]
	v_mfma_f32_16x16x32_bf16 v[92:95], v[152:155], v[184:187], v[92:95]
	v_mfma_f32_16x16x32_bf16 v[88:91], v[160:163], v[184:187], v[88:91]
	v_mfma_f32_16x16x32_bf16 v[76:79], v[152:155], v[192:195], v[76:79]
	v_mfma_f32_16x16x32_bf16 v[72:75], v[160:163], v[192:195], v[72:75]
	v_mfma_f32_16x16x32_bf16 v[124:127], v[156:159], v[172:175], v[124:127]
	v_mfma_f32_16x16x32_bf16 v[120:123], v[164:167], v[172:175], v[120:123]
	v_mfma_f32_16x16x32_bf16 v[108:111], v[156:159], v[180:183], v[108:111]
	v_mfma_f32_16x16x32_bf16 v[104:107], v[164:167], v[180:183], v[104:107]
	v_mfma_f32_16x16x32_bf16 v[92:95], v[156:159], v[188:191], v[92:95]
	v_mfma_f32_16x16x32_bf16 v[88:91], v[164:167], v[188:191], v[88:91]
	v_mfma_f32_16x16x32_bf16 v[76:79], v[156:159], v[196:199], v[76:79]
	v_mfma_f32_16x16x32_bf16 v[72:75], v[164:167], v[196:199], v[72:75]
	s_setprio 0
	s_barrier
	s_add_i32 s28, 0, 0x1c000
	s_add_i32 s29, s58, s38
	v_add_u32_e32 v212, s28, v145
	s_mov_b32 m0, s29
	ds_read_b128 v[200:203], v212
	ds_read_b128 v[204:207], v212 offset:1024
	ds_read_b128 v[208:211], v212 offset:2048
	ds_read_b128 v[212:215], v212 offset:3072
	global_load_lds_dwordx4 v132, s[80:81]
	s_add_i32 m0, s29, 0x2000
	s_nop 0
	global_load_lds_dwordx4 v128, s[80:81]
	s_barrier
	s_waitcnt lgkmcnt(0)
	s_setprio 1
	s_waitcnt lgkmcnt(0)
	v_mfma_f32_16x16x32_bf16 v[116:119], v[200:203], v[168:171], v[116:119]
	v_mfma_f32_16x16x32_bf16 v[112:115], v[208:211], v[168:171], v[112:115]
	v_mfma_f32_16x16x32_bf16 v[100:103], v[200:203], v[176:179], v[100:103]
	v_mfma_f32_16x16x32_bf16 v[96:99], v[208:211], v[176:179], v[96:99]
	v_mfma_f32_16x16x32_bf16 v[84:87], v[200:203], v[184:187], v[84:87]
	v_mfma_f32_16x16x32_bf16 v[80:83], v[208:211], v[184:187], v[80:83]
	v_mfma_f32_16x16x32_bf16 v[68:71], v[200:203], v[192:195], v[68:71]
	v_mfma_f32_16x16x32_bf16 v[64:67], v[208:211], v[192:195], v[64:67]
	v_mfma_f32_16x16x32_bf16 v[116:119], v[204:207], v[172:175], v[116:119]
	v_mfma_f32_16x16x32_bf16 v[112:115], v[212:215], v[172:175], v[112:115]
	v_mfma_f32_16x16x32_bf16 v[100:103], v[204:207], v[180:183], v[100:103]
	v_mfma_f32_16x16x32_bf16 v[96:99], v[212:215], v[180:183], v[96:99]
	v_mfma_f32_16x16x32_bf16 v[84:87], v[204:207], v[188:191], v[84:87]
	v_mfma_f32_16x16x32_bf16 v[80:83], v[212:215], v[188:191], v[80:83]
	v_mfma_f32_16x16x32_bf16 v[68:71], v[204:207], v[196:199], v[68:71]
	v_mfma_f32_16x16x32_bf16 v[64:67], v[212:215], v[196:199], v[64:67]
	s_setprio 0
	s_mov_b32 m0, s45
	s_barrier
	ds_read_b128 v[168:171], v150 offset:49152
	ds_read_b128 v[172:175], v150 offset:50176
	ds_read_b128 v[176:179], v150 offset:51200
	ds_read_b128 v[180:183], v150 offset:52224
	ds_read_b128 v[184:187], v150 offset:53248
	ds_read_b128 v[188:191], v150 offset:54272
	ds_read_b128 v[192:195], v150 offset:55296
	ds_read_b128 v[196:199], v150 offset:56320
	global_load_lds_dwordx4 v134, s[82:83]
	s_mov_b32 m0, s46
	s_nop 0
	global_load_lds_dwordx4 v130, s[82:83]
	s_barrier
	s_waitcnt lgkmcnt(0)
	s_setprio 1
	s_waitcnt lgkmcnt(0)
	v_mfma_f32_16x16x32_bf16 v[60:63], v[152:155], v[168:171], v[60:63]
	v_mfma_f32_16x16x32_bf16 v[56:59], v[160:163], v[168:171], v[56:59]
	v_mfma_f32_16x16x32_bf16 v[44:47], v[152:155], v[176:179], v[44:47]
	v_mfma_f32_16x16x32_bf16 v[40:43], v[160:163], v[176:179], v[40:43]
	v_mfma_f32_16x16x32_bf16 v[28:31], v[152:155], v[184:187], v[28:31]
	v_mfma_f32_16x16x32_bf16 v[24:27], v[160:163], v[184:187], v[24:27]
	v_mfma_f32_16x16x32_bf16 v[12:15], v[152:155], v[192:195], v[12:15]
	v_mfma_f32_16x16x32_bf16 v[8:11], v[160:163], v[192:195], v[8:11]
	v_mfma_f32_16x16x32_bf16 v[60:63], v[156:159], v[172:175], v[60:63]
	v_mfma_f32_16x16x32_bf16 v[56:59], v[164:167], v[172:175], v[56:59]
	v_mfma_f32_16x16x32_bf16 v[44:47], v[156:159], v[180:183], v[44:47]
	v_mfma_f32_16x16x32_bf16 v[40:43], v[164:167], v[180:183], v[40:43]
	v_mfma_f32_16x16x32_bf16 v[28:31], v[156:159], v[188:191], v[28:31]
	v_mfma_f32_16x16x32_bf16 v[24:27], v[164:167], v[188:191], v[24:27]
	v_mfma_f32_16x16x32_bf16 v[12:15], v[156:159], v[196:199], v[12:15]
	v_mfma_f32_16x16x32_bf16 v[8:11], v[164:167], v[196:199], v[8:11]
	s_setprio 0
	s_barrier
	s_add_u32 s26, s26, 0x40080
	s_addc_u32 s27, s27, 0
	s_add_i32 s28, s28, s38
	s_mov_b32 m0, s28
	s_nop 0
	global_load_lds_dwordx4 v132, s[26:27]
	s_add_i32 m0, s28, 0x2000
	s_nop 0
	global_load_lds_dwordx4 v128, s[26:27]
	s_waitcnt vmcnt(6)
	s_barrier
	s_setprio 1
	v_mfma_f32_16x16x32_bf16 v[52:55], v[200:203], v[168:171], v[52:55]
	v_mfma_f32_16x16x32_bf16 v[48:51], v[208:211], v[168:171], v[48:51]
	v_mfma_f32_16x16x32_bf16 v[36:39], v[200:203], v[176:179], v[36:39]
	v_mfma_f32_16x16x32_bf16 v[32:35], v[208:211], v[176:179], v[32:35]
	v_mfma_f32_16x16x32_bf16 v[20:23], v[200:203], v[184:187], v[20:23]
	v_mfma_f32_16x16x32_bf16 v[16:19], v[208:211], v[184:187], v[16:19]
	v_mfma_f32_16x16x32_bf16 v[4:7], v[200:203], v[192:195], v[4:7]
	v_mfma_f32_16x16x32_bf16 v[0:3], v[208:211], v[192:195], v[0:3]
	v_mfma_f32_16x16x32_bf16 v[52:55], v[204:207], v[172:175], v[52:55]
	v_mfma_f32_16x16x32_bf16 v[48:51], v[212:215], v[172:175], v[48:51]
	v_mfma_f32_16x16x32_bf16 v[36:39], v[204:207], v[180:183], v[36:39]
	v_mfma_f32_16x16x32_bf16 v[32:35], v[212:215], v[180:183], v[32:35]
	v_mfma_f32_16x16x32_bf16 v[20:23], v[204:207], v[188:191], v[20:23]
	v_mfma_f32_16x16x32_bf16 v[16:19], v[212:215], v[188:191], v[16:19]
	v_mfma_f32_16x16x32_bf16 v[4:7], v[204:207], v[196:199], v[4:7]
	v_mfma_f32_16x16x32_bf16 v[0:3], v[212:215], v[196:199], v[0:3]
	s_setprio 0
	s_add_i32 s57, s57, 2
	s_add_u32 s20, s20, 0x100
	s_addc_u32 s21, s21, 0
	s_add_u32 s55, s55, 0x100
	s_addc_u32 s56, s56, 0
	s_cmp_gt_u32 s57, 13
	s_barrier
	s_cbranch_scc0 .LBB0_131
	v_lshl_add_u32 v153, s51, 10, v147
	ds_read2_b32 v[154:155], v153 offset1:16
	v_lshl_or_b32 v156, s52, 7, v148
	v_lshl_add_u32 v152, s18, 8, v144
	s_and_b64 vcc, exec, s[4:5]
	s_mov_b32 s52, s10
	s_waitcnt lgkmcnt(0)
	v_pk_mul_f32 v[124:125], v[124:125], v[154:155] op_sel_hi:[1,0]
	v_pk_mul_f32 v[126:127], v[126:127], v[154:155] op_sel_hi:[1,0]
	v_mul_f32_e32 v157, 0xbfb8aa3b, v124
	v_mul_f32_e32 v158, 0xbfb8aa3b, v125
	v_exp_f32_e32 v159, v157
	v_exp_f32_e32 v158, v158
	v_pk_mul_f32 v[116:117], v[116:117], v[154:155] op_sel_hi:[1,0]
	v_pk_mul_f32 v[120:121], v[120:121], v[154:155] op_sel_hi:[1,0]
	v_add_f32_e32 v159, 1.0, v159
	v_add_f32_e32 v160, 1.0, v158
	v_rcp_f32_e32 v158, v159
	v_mul_f32_e32 v159, 0xbfb8aa3b, v126
	v_exp_f32_e32 v161, v159
	v_mul_f32_e32 v159, 0xbfb8aa3b, v127
	v_exp_f32_e32 v162, v159
	v_rcp_f32_e32 v159, v160
	v_add_f32_e32 v160, 1.0, v161
	v_rcp_f32_e32 v160, v160
	v_add_f32_e32 v161, 1.0, v162
	v_rcp_f32_e32 v161, v161
	v_pk_mul_f32 v[124:125], v[124:125], v[158:159]
	v_pk_mul_f32 v[118:119], v[118:119], v[154:155] op_sel_hi:[1,0]
	v_pk_mul_f32 v[116:117], v[116:117], v[124:125]
	v_pk_mul_f32 v[124:125], v[126:127], v[160:161]
	v_mul_f32_e32 v126, 0xbfb8aa3b, v120
	v_exp_f32_e32 v126, v126
	v_pk_mul_f32 v[118:119], v[118:119], v[124:125]
	v_mul_f32_e32 v124, 0xbfb8aa3b, v121
	v_pk_mul_f32 v[122:123], v[122:123], v[154:155] op_sel_hi:[1,0]
	v_exp_f32_e32 v125, v124
	v_add_f32_e32 v124, 1.0, v126
	v_mul_f32_e32 v126, 0xbfb8aa3b, v122
	v_mul_f32_e32 v127, 0xbfb8aa3b, v123
	v_exp_f32_e32 v126, v126
	v_exp_f32_e32 v127, v127
	v_add_f32_e32 v125, 1.0, v125
	v_rcp_f32_e32 v124, v124
	v_rcp_f32_e32 v125, v125
	v_add_f32_e32 v126, 1.0, v126
	v_add_f32_e32 v127, 1.0, v127
	v_rcp_f32_e32 v126, v126
	v_rcp_f32_e32 v127, v127
	v_pk_mul_f32 v[112:113], v[112:113], v[154:155] op_sel_hi:[1,0]
	v_pk_mul_f32 v[120:121], v[120:121], v[124:125]
	v_pk_mul_f32 v[114:115], v[114:115], v[154:155] op_sel_hi:[1,0]
	v_pk_mul_f32 v[112:113], v[112:113], v[120:121]
	v_pk_mul_f32 v[120:121], v[122:123], v[126:127]
	v_mov_b32_e32 v122, v155
	v_pk_mul_f32 v[108:109], v[108:109], v[122:123] op_sel_hi:[1,0]
	v_ashrrev_i32_e32 v157, 31, v156
	v_mul_f32_e32 v123, 0xbfb8aa3b, v108
	v_exp_f32_e32 v123, v123
	v_pk_mul_f32 v[114:115], v[114:115], v[120:121]
	v_cvt_pk_bf16_f32 v116, v116, v117
	v_cvt_pk_bf16_f32 v117, v118, v119
	v_cvt_pk_bf16_f32 v118, v112, v113
	v_mov_b64_e32 v[112:113], s[6:7]
	v_cvt_pk_bf16_f32 v119, v114, v115
	v_mad_i64_i32 v[120:121], s[20:21], v152, s49, v[112:113]
	v_lshlrev_b64 v[114:115], 1, v[156:157]
	v_lshl_add_u64 v[120:121], v[120:121], 0, v[114:115]
	global_store_dwordx4 v[120:121], v[116:119], off nt
	v_pk_mul_f32 v[110:111], v[110:111], v[122:123] op_sel_hi:[1,0]
	v_pk_mul_f32 v[100:101], v[100:101], v[122:123] op_sel_hi:[1,0]
	v_mul_f32_e32 v116, 0xbfb8aa3b, v109
	v_exp_f32_e32 v117, v116
	v_mul_f32_e32 v118, 0xbfb8aa3b, v110
	v_mul_f32_e32 v119, 0xbfb8aa3b, v111
	v_exp_f32_e32 v118, v118
	v_exp_f32_e32 v119, v119
	v_add_f32_e32 v116, 1.0, v123
	v_add_f32_e32 v117, 1.0, v117
	v_rcp_f32_e32 v116, v116
	v_rcp_f32_e32 v117, v117
	v_add_f32_e32 v118, 1.0, v118
	v_add_f32_e32 v119, 1.0, v119
	v_rcp_f32_e32 v118, v118
	v_rcp_f32_e32 v119, v119
	v_pk_mul_f32 v[108:109], v[108:109], v[116:117]
	v_pk_mul_f32 v[104:105], v[104:105], v[122:123] op_sel_hi:[1,0]
	v_pk_mul_f32 v[100:101], v[100:101], v[108:109]
	v_pk_mul_f32 v[108:109], v[110:111], v[118:119]
	v_mul_f32_e32 v110, 0xbfb8aa3b, v104
	v_exp_f32_e32 v110, v110
	v_pk_mul_f32 v[102:103], v[102:103], v[122:123] op_sel_hi:[1,0]
	v_pk_mul_f32 v[106:107], v[106:107], v[122:123] op_sel_hi:[1,0]
	v_pk_mul_f32 v[102:103], v[102:103], v[108:109]
	v_mul_f32_e32 v108, 0xbfb8aa3b, v105
	v_exp_f32_e32 v109, v108
	v_add_f32_e32 v108, 1.0, v110
	v_mul_f32_e32 v110, 0xbfb8aa3b, v106
	v_mul_f32_e32 v111, 0xbfb8aa3b, v107
	v_exp_f32_e32 v110, v110
	v_exp_f32_e32 v111, v111
	v_add_f32_e32 v109, 1.0, v109
	v_rcp_f32_e32 v108, v108
	v_rcp_f32_e32 v109, v109
	v_add_f32_e32 v110, 1.0, v110
	v_add_f32_e32 v111, 1.0, v111
	v_rcp_f32_e32 v110, v110
	v_rcp_f32_e32 v111, v111
	v_pk_mul_f32 v[96:97], v[96:97], v[122:123] op_sel_hi:[1,0]
	v_pk_mul_f32 v[104:105], v[104:105], v[108:109]
	v_or_b32_e32 v108, 16, v152
	v_pk_mul_f32 v[104:105], v[96:97], v[104:105]
	v_pk_mul_f32 v[96:97], v[98:99], v[122:123] op_sel_hi:[1,0]
	v_pk_mul_f32 v[98:99], v[106:107], v[110:111]
	s_mov_b32 s18, s12
	v_pk_mul_f32 v[106:107], v[96:97], v[98:99]
	v_cvt_pk_bf16_f32 v96, v100, v101
	ds_read2_b32 v[100:101], v153 offset0:32 offset1:48
	v_cvt_pk_bf16_f32 v97, v102, v103
	v_mad_i64_i32 v[102:103], s[20:21], v108, s49, v[112:113]
	v_cvt_pk_bf16_f32 v98, v104, v105
	v_cvt_pk_bf16_f32 v99, v106, v107
	v_lshl_add_u64 v[102:103], v[102:103], 0, v[114:115]
	s_waitcnt lgkmcnt(0)
	v_pk_mul_f32 v[92:93], v[92:93], v[100:101] op_sel_hi:[1,0]
	global_store_dwordx4 v[102:103], v[96:99], off nt
	v_mul_f32_e32 v104, 0xbfb8aa3b, v92
	v_pk_mul_f32 v[94:95], v[94:95], v[100:101] op_sel_hi:[1,0]
	v_mul_f32_e32 v96, 0xbfb8aa3b, v93
	v_exp_f32_e32 v104, v104
	v_exp_f32_e32 v97, v96
	v_mul_f32_e32 v98, 0xbfb8aa3b, v94
	v_mul_f32_e32 v99, 0xbfb8aa3b, v95
	v_exp_f32_e32 v98, v98
	v_exp_f32_e32 v99, v99
	v_add_f32_e32 v96, 1.0, v104
	v_add_f32_e32 v97, 1.0, v97
	v_rcp_f32_e32 v96, v96
	v_rcp_f32_e32 v97, v97
	v_add_f32_e32 v98, 1.0, v98
	v_add_f32_e32 v99, 1.0, v99
	v_rcp_f32_e32 v98, v98
	v_rcp_f32_e32 v99, v99
	v_pk_mul_f32 v[84:85], v[84:85], v[100:101] op_sel_hi:[1,0]
	v_pk_mul_f32 v[92:93], v[92:93], v[96:97]
	v_pk_mul_f32 v[88:89], v[88:89], v[100:101] op_sel_hi:[1,0]
	v_pk_mul_f32 v[84:85], v[84:85], v[92:93]
	v_pk_mul_f32 v[92:93], v[94:95], v[98:99]
	v_mul_f32_e32 v94, 0xbfb8aa3b, v88
	v_exp_f32_e32 v94, v94
	v_pk_mul_f32 v[86:87], v[86:87], v[100:101] op_sel_hi:[1,0]
	v_pk_mul_f32 v[90:91], v[90:91], v[100:101] op_sel_hi:[1,0]
	v_pk_mul_f32 v[86:87], v[86:87], v[92:93]
	v_mul_f32_e32 v92, 0xbfb8aa3b, v89
	v_exp_f32_e32 v93, v92
	v_add_f32_e32 v92, 1.0, v94
	v_mul_f32_e32 v94, 0xbfb8aa3b, v90
	v_mul_f32_e32 v95, 0xbfb8aa3b, v91
	v_exp_f32_e32 v94, v94
	v_exp_f32_e32 v95, v95
	v_add_f32_e32 v93, 1.0, v93
	v_rcp_f32_e32 v92, v92
	v_rcp_f32_e32 v93, v93
	v_add_f32_e32 v94, 1.0, v94
	v_add_f32_e32 v95, 1.0, v95
	v_rcp_f32_e32 v94, v94
	v_rcp_f32_e32 v95, v95
	v_pk_mul_f32 v[80:81], v[80:81], v[100:101] op_sel_hi:[1,0]
	v_pk_mul_f32 v[88:89], v[88:89], v[92:93]
	v_or_b32_e32 v92, 32, v152
	v_pk_mul_f32 v[88:89], v[80:81], v[88:89]
	v_pk_mul_f32 v[80:81], v[82:83], v[100:101] op_sel_hi:[1,0]
	v_pk_mul_f32 v[82:83], v[90:91], v[94:95]
	s_mov_b64 s[26:27], s[16:17]
	v_pk_mul_f32 v[90:91], v[80:81], v[82:83]
	v_cvt_pk_bf16_f32 v81, v86, v87
	v_mov_b32_e32 v86, v101
	v_pk_mul_f32 v[76:77], v[76:77], v[86:87] op_sel_hi:[1,0]
	v_cvt_pk_bf16_f32 v80, v84, v85
	v_mul_f32_e32 v87, 0xbfb8aa3b, v76
	v_exp_f32_e32 v87, v87
	v_mad_i64_i32 v[84:85], s[20:21], v92, s49, v[112:113]
	v_cvt_pk_bf16_f32 v82, v88, v89
	v_cvt_pk_bf16_f32 v83, v90, v91
	v_lshl_add_u64 v[84:85], v[84:85], 0, v[114:115]
	global_store_dwordx4 v[84:85], v[80:83], off nt
	v_pk_mul_f32 v[78:79], v[78:79], v[86:87] op_sel_hi:[1,0]
	v_pk_mul_f32 v[68:69], v[68:69], v[86:87] op_sel_hi:[1,0]
	v_mul_f32_e32 v80, 0xbfb8aa3b, v77
	v_exp_f32_e32 v81, v80
	v_mul_f32_e32 v82, 0xbfb8aa3b, v78
	v_mul_f32_e32 v83, 0xbfb8aa3b, v79
	v_exp_f32_e32 v82, v82
	v_exp_f32_e32 v83, v83
	v_add_f32_e32 v80, 1.0, v87
	v_add_f32_e32 v81, 1.0, v81
	v_rcp_f32_e32 v80, v80
	v_rcp_f32_e32 v81, v81
	v_add_f32_e32 v82, 1.0, v82
	v_add_f32_e32 v83, 1.0, v83
	v_rcp_f32_e32 v82, v82
	v_rcp_f32_e32 v83, v83
	v_pk_mul_f32 v[76:77], v[76:77], v[80:81]
	v_pk_mul_f32 v[72:73], v[72:73], v[86:87] op_sel_hi:[1,0]
	v_pk_mul_f32 v[68:69], v[68:69], v[76:77]
	v_pk_mul_f32 v[76:77], v[78:79], v[82:83]
	v_mul_f32_e32 v78, 0xbfb8aa3b, v72
	v_exp_f32_e32 v78, v78
	v_pk_mul_f32 v[70:71], v[70:71], v[86:87] op_sel_hi:[1,0]
	v_pk_mul_f32 v[74:75], v[74:75], v[86:87] op_sel_hi:[1,0]
	v_pk_mul_f32 v[70:71], v[70:71], v[76:77]
	v_mul_f32_e32 v76, 0xbfb8aa3b, v73
	v_exp_f32_e32 v77, v76
	v_add_f32_e32 v76, 1.0, v78
	v_mul_f32_e32 v78, 0xbfb8aa3b, v74
	v_mul_f32_e32 v79, 0xbfb8aa3b, v75
	v_exp_f32_e32 v78, v78
	v_exp_f32_e32 v79, v79
	v_add_f32_e32 v77, 1.0, v77
	v_rcp_f32_e32 v76, v76
	v_rcp_f32_e32 v77, v77
	v_add_f32_e32 v78, 1.0, v78
	v_add_f32_e32 v79, 1.0, v79
	v_rcp_f32_e32 v78, v78
	v_rcp_f32_e32 v79, v79
	v_pk_mul_f32 v[64:65], v[64:65], v[86:87] op_sel_hi:[1,0]
	v_pk_mul_f32 v[72:73], v[72:73], v[76:77]
	v_or_b32_e32 v76, 48, v152
	v_pk_mul_f32 v[72:73], v[64:65], v[72:73]
	v_pk_mul_f32 v[64:65], v[66:67], v[86:87] op_sel_hi:[1,0]
	v_pk_mul_f32 v[66:67], v[74:75], v[78:79]
	s_mov_b32 s51, s50
	v_pk_mul_f32 v[74:75], v[64:65], v[66:67]
	v_cvt_pk_bf16_f32 v64, v68, v69
	ds_read2_b32 v[68:69], v153 offset0:128 offset1:144
	v_cvt_pk_bf16_f32 v65, v70, v71
	v_mad_i64_i32 v[70:71], s[20:21], v76, s49, v[112:113]
	v_cvt_pk_bf16_f32 v66, v72, v73
	v_cvt_pk_bf16_f32 v67, v74, v75
	v_lshl_add_u64 v[70:71], v[70:71], 0, v[114:115]
	s_waitcnt lgkmcnt(0)
	v_pk_mul_f32 v[60:61], v[60:61], v[68:69] op_sel_hi:[1,0]
	global_store_dwordx4 v[70:71], v[64:67], off nt
	v_pk_mul_f32 v[62:63], v[62:63], v[68:69] op_sel_hi:[1,0]
	v_pk_mul_f32 v[52:53], v[52:53], v[68:69] op_sel_hi:[1,0]
	v_mul_f32_e32 v64, 0xbfb8aa3b, v60
	v_mul_f32_e32 v65, 0xbfb8aa3b, v61
	v_exp_f32_e32 v64, v64
	v_exp_f32_e32 v65, v65
	v_mul_f32_e32 v66, 0xbfb8aa3b, v62
	v_mul_f32_e32 v67, 0xbfb8aa3b, v63
	v_exp_f32_e32 v66, v66
	v_exp_f32_e32 v67, v67
	v_add_f32_e32 v64, 1.0, v64
	v_add_f32_e32 v65, 1.0, v65
	v_rcp_f32_e32 v64, v64
	v_rcp_f32_e32 v65, v65
	v_add_f32_e32 v66, 1.0, v66
	v_add_f32_e32 v67, 1.0, v67
	v_rcp_f32_e32 v66, v66
	v_rcp_f32_e32 v67, v67
	v_pk_mul_f32 v[60:61], v[60:61], v[64:65]
	v_pk_mul_f32 v[56:57], v[56:57], v[68:69] op_sel_hi:[1,0]
	v_pk_mul_f32 v[52:53], v[52:53], v[60:61]
	v_pk_mul_f32 v[60:61], v[62:63], v[66:67]
	v_mul_f32_e32 v62, 0xbfb8aa3b, v56
	v_exp_f32_e32 v62, v62
	v_pk_mul_f32 v[54:55], v[54:55], v[68:69] op_sel_hi:[1,0]
	v_pk_mul_f32 v[58:59], v[58:59], v[68:69] op_sel_hi:[1,0]
	v_pk_mul_f32 v[54:55], v[54:55], v[60:61]
	v_mul_f32_e32 v60, 0xbfb8aa3b, v57
	v_exp_f32_e32 v61, v60
	v_add_f32_e32 v60, 1.0, v62
	v_mul_f32_e32 v62, 0xbfb8aa3b, v58
	v_mul_f32_e32 v63, 0xbfb8aa3b, v59
	v_exp_f32_e32 v62, v62
	v_exp_f32_e32 v63, v63
	v_add_f32_e32 v61, 1.0, v61
	v_rcp_f32_e32 v60, v60
	v_rcp_f32_e32 v61, v61
	v_add_f32_e32 v62, 1.0, v62
	v_add_f32_e32 v63, 1.0, v63
	v_rcp_f32_e32 v62, v62
	v_rcp_f32_e32 v63, v63
	v_pk_mul_f32 v[48:49], v[48:49], v[68:69] op_sel_hi:[1,0]
	v_pk_mul_f32 v[56:57], v[56:57], v[60:61]
	v_add_u32_e32 v70, 0x80, v152
	v_pk_mul_f32 v[56:57], v[48:49], v[56:57]
	v_pk_mul_f32 v[48:49], v[50:51], v[68:69] op_sel_hi:[1,0]
	v_pk_mul_f32 v[50:51], v[58:59], v[62:63]
	s_nop 0
	v_pk_mul_f32 v[58:59], v[48:49], v[50:51]
	v_cvt_pk_bf16_f32 v49, v54, v55
	v_mov_b32_e32 v54, v69
	v_pk_mul_f32 v[44:45], v[44:45], v[54:55] op_sel_hi:[1,0]
	v_cvt_pk_bf16_f32 v48, v52, v53
	v_mul_f32_e32 v55, 0xbfb8aa3b, v44
	v_exp_f32_e32 v55, v55
	v_mad_i64_i32 v[52:53], s[20:21], v70, s49, v[112:113]
	v_cvt_pk_bf16_f32 v50, v56, v57
	v_cvt_pk_bf16_f32 v51, v58, v59
	v_lshl_add_u64 v[52:53], v[52:53], 0, v[114:115]
	global_store_dwordx4 v[52:53], v[48:51], off nt
	v_pk_mul_f32 v[46:47], v[46:47], v[54:55] op_sel_hi:[1,0]
	v_pk_mul_f32 v[36:37], v[36:37], v[54:55] op_sel_hi:[1,0]
	v_mul_f32_e32 v48, 0xbfb8aa3b, v45
	v_exp_f32_e32 v49, v48
	v_mul_f32_e32 v50, 0xbfb8aa3b, v46
	v_mul_f32_e32 v51, 0xbfb8aa3b, v47
	v_exp_f32_e32 v50, v50
	v_exp_f32_e32 v51, v51
	v_add_f32_e32 v48, 1.0, v55
	v_add_f32_e32 v49, 1.0, v49
	v_rcp_f32_e32 v48, v48
	v_rcp_f32_e32 v49, v49
	v_add_f32_e32 v50, 1.0, v50
	v_add_f32_e32 v51, 1.0, v51
	v_rcp_f32_e32 v50, v50
	v_rcp_f32_e32 v51, v51
	v_pk_mul_f32 v[44:45], v[44:45], v[48:49]
	v_pk_mul_f32 v[40:41], v[40:41], v[54:55] op_sel_hi:[1,0]
	v_pk_mul_f32 v[36:37], v[36:37], v[44:45]
	v_pk_mul_f32 v[44:45], v[46:47], v[50:51]
	v_mul_f32_e32 v46, 0xbfb8aa3b, v40
	v_exp_f32_e32 v46, v46
	v_pk_mul_f32 v[38:39], v[38:39], v[54:55] op_sel_hi:[1,0]
	v_pk_mul_f32 v[42:43], v[42:43], v[54:55] op_sel_hi:[1,0]
	v_pk_mul_f32 v[38:39], v[38:39], v[44:45]
	v_mul_f32_e32 v44, 0xbfb8aa3b, v41
	v_exp_f32_e32 v45, v44
	v_add_f32_e32 v44, 1.0, v46
	v_mul_f32_e32 v46, 0xbfb8aa3b, v42
	v_mul_f32_e32 v47, 0xbfb8aa3b, v43
	v_exp_f32_e32 v46, v46
	v_exp_f32_e32 v47, v47
	v_add_f32_e32 v45, 1.0, v45
	v_rcp_f32_e32 v44, v44
	v_rcp_f32_e32 v45, v45
	v_add_f32_e32 v46, 1.0, v46
	v_add_f32_e32 v47, 1.0, v47
	v_rcp_f32_e32 v46, v46
	v_rcp_f32_e32 v47, v47
	v_pk_mul_f32 v[32:33], v[32:33], v[54:55] op_sel_hi:[1,0]
	v_pk_mul_f32 v[40:41], v[40:41], v[44:45]
	v_add_u32_e32 v44, 0x90, v152
	v_pk_mul_f32 v[40:41], v[32:33], v[40:41]
	v_pk_mul_f32 v[32:33], v[34:35], v[54:55] op_sel_hi:[1,0]
	v_pk_mul_f32 v[34:35], v[42:43], v[46:47]
	s_nop 0
	v_pk_mul_f32 v[42:43], v[32:33], v[34:35]
	v_cvt_pk_bf16_f32 v32, v36, v37
	ds_read2_b32 v[36:37], v153 offset0:160 offset1:176
	v_cvt_pk_bf16_f32 v33, v38, v39
	v_mad_i64_i32 v[38:39], s[20:21], v44, s49, v[112:113]
	v_cvt_pk_bf16_f32 v34, v40, v41
	v_cvt_pk_bf16_f32 v35, v42, v43
	v_lshl_add_u64 v[38:39], v[38:39], 0, v[114:115]
	s_waitcnt lgkmcnt(0)
	v_pk_mul_f32 v[28:29], v[28:29], v[36:37] op_sel_hi:[1,0]
	global_store_dwordx4 v[38:39], v[32:35], off nt
	v_mul_f32_e32 v40, 0xbfb8aa3b, v28
	v_pk_mul_f32 v[30:31], v[30:31], v[36:37] op_sel_hi:[1,0]
	v_mul_f32_e32 v32, 0xbfb8aa3b, v29
	v_exp_f32_e32 v40, v40
	v_exp_f32_e32 v33, v32
	v_mul_f32_e32 v34, 0xbfb8aa3b, v30
	v_mul_f32_e32 v35, 0xbfb8aa3b, v31
	v_exp_f32_e32 v34, v34
	v_exp_f32_e32 v35, v35
	v_add_f32_e32 v32, 1.0, v40
	v_add_f32_e32 v33, 1.0, v33
	v_rcp_f32_e32 v32, v32
	v_rcp_f32_e32 v33, v33
	v_add_f32_e32 v34, 1.0, v34
	v_add_f32_e32 v35, 1.0, v35
	v_rcp_f32_e32 v34, v34
	v_rcp_f32_e32 v35, v35
	v_pk_mul_f32 v[20:21], v[20:21], v[36:37] op_sel_hi:[1,0]
	v_pk_mul_f32 v[28:29], v[28:29], v[32:33]
	v_pk_mul_f32 v[24:25], v[24:25], v[36:37] op_sel_hi:[1,0]
	v_pk_mul_f32 v[20:21], v[20:21], v[28:29]
	v_pk_mul_f32 v[28:29], v[30:31], v[34:35]
	v_mul_f32_e32 v30, 0xbfb8aa3b, v24
	v_exp_f32_e32 v30, v30
	v_pk_mul_f32 v[22:23], v[22:23], v[36:37] op_sel_hi:[1,0]
	v_pk_mul_f32 v[26:27], v[26:27], v[36:37] op_sel_hi:[1,0]
	v_pk_mul_f32 v[22:23], v[22:23], v[28:29]
	v_mul_f32_e32 v28, 0xbfb8aa3b, v25
	v_exp_f32_e32 v29, v28
	v_add_f32_e32 v28, 1.0, v30
	v_mul_f32_e32 v30, 0xbfb8aa3b, v26
	v_mul_f32_e32 v31, 0xbfb8aa3b, v27
	v_exp_f32_e32 v30, v30
	v_exp_f32_e32 v31, v31
	v_add_f32_e32 v29, 1.0, v29
	v_rcp_f32_e32 v28, v28
	v_rcp_f32_e32 v29, v29
	v_add_f32_e32 v30, 1.0, v30
	v_add_f32_e32 v31, 1.0, v31
	v_rcp_f32_e32 v30, v30
	v_rcp_f32_e32 v31, v31
	v_pk_mul_f32 v[16:17], v[16:17], v[36:37] op_sel_hi:[1,0]
	v_pk_mul_f32 v[24:25], v[24:25], v[28:29]
	v_add_u32_e32 v28, 0xa0, v152
	v_pk_mul_f32 v[24:25], v[16:17], v[24:25]
	v_pk_mul_f32 v[16:17], v[18:19], v[36:37] op_sel_hi:[1,0]
	v_pk_mul_f32 v[18:19], v[26:27], v[30:31]
	s_nop 0
	v_pk_mul_f32 v[26:27], v[16:17], v[18:19]
	v_cvt_pk_bf16_f32 v17, v22, v23
	v_mov_b32_e32 v22, v37
	v_pk_mul_f32 v[12:13], v[12:13], v[22:23] op_sel_hi:[1,0]
	v_cvt_pk_bf16_f32 v16, v20, v21
	v_mul_f32_e32 v23, 0xbfb8aa3b, v12
	v_exp_f32_e32 v23, v23
	v_mad_i64_i32 v[20:21], s[20:21], v28, s49, v[112:113]
	v_cvt_pk_bf16_f32 v18, v24, v25
	v_cvt_pk_bf16_f32 v19, v26, v27
	v_lshl_add_u64 v[20:21], v[20:21], 0, v[114:115]
	global_store_dwordx4 v[20:21], v[16:19], off nt
	v_pk_mul_f32 v[14:15], v[14:15], v[22:23] op_sel_hi:[1,0]
	v_pk_mul_f32 v[4:5], v[4:5], v[22:23] op_sel_hi:[1,0]
	v_mul_f32_e32 v16, 0xbfb8aa3b, v13
	v_exp_f32_e32 v17, v16
	v_mul_f32_e32 v18, 0xbfb8aa3b, v14
	v_mul_f32_e32 v19, 0xbfb8aa3b, v15
	v_exp_f32_e32 v18, v18
	v_exp_f32_e32 v19, v19
	v_add_f32_e32 v16, 1.0, v23
	v_add_f32_e32 v17, 1.0, v17
	v_rcp_f32_e32 v16, v16
	v_rcp_f32_e32 v17, v17
	v_add_f32_e32 v18, 1.0, v18
	v_add_f32_e32 v19, 1.0, v19
	v_rcp_f32_e32 v18, v18
	v_rcp_f32_e32 v19, v19
	v_pk_mul_f32 v[12:13], v[12:13], v[16:17]
	v_pk_mul_f32 v[8:9], v[8:9], v[22:23] op_sel_hi:[1,0]
	v_pk_mul_f32 v[4:5], v[4:5], v[12:13]
	v_pk_mul_f32 v[12:13], v[14:15], v[18:19]
	v_mul_f32_e32 v14, 0xbfb8aa3b, v8
	v_exp_f32_e32 v14, v14
	v_pk_mul_f32 v[6:7], v[6:7], v[22:23] op_sel_hi:[1,0]
	v_pk_mul_f32 v[10:11], v[10:11], v[22:23] op_sel_hi:[1,0]
	v_pk_mul_f32 v[6:7], v[6:7], v[12:13]
	v_mul_f32_e32 v12, 0xbfb8aa3b, v9
	v_exp_f32_e32 v13, v12
	v_add_f32_e32 v12, 1.0, v14
	v_mul_f32_e32 v14, 0xbfb8aa3b, v10
	v_mul_f32_e32 v15, 0xbfb8aa3b, v11
	v_exp_f32_e32 v14, v14
	v_exp_f32_e32 v15, v15
	v_add_f32_e32 v13, 1.0, v13
	v_rcp_f32_e32 v12, v12
	v_rcp_f32_e32 v13, v13
	v_add_f32_e32 v14, 1.0, v14
	v_add_f32_e32 v15, 1.0, v15
	v_rcp_f32_e32 v14, v14
	v_rcp_f32_e32 v15, v15
	v_pk_mul_f32 v[0:1], v[0:1], v[22:23] op_sel_hi:[1,0]
	v_pk_mul_f32 v[8:9], v[8:9], v[12:13]
	v_add_u32_e32 v12, 0xb0, v152
	v_pk_mul_f32 v[8:9], v[0:1], v[8:9]
	v_pk_mul_f32 v[0:1], v[2:3], v[22:23] op_sel_hi:[1,0]
	v_pk_mul_f32 v[2:3], v[10:11], v[14:15]
	s_nop 0
	v_pk_mul_f32 v[10:11], v[0:1], v[2:3]
	v_cvt_pk_bf16_f32 v0, v4, v5
	v_mad_i64_i32 v[4:5], s[20:21], v12, s49, v[112:113]
	v_cvt_pk_bf16_f32 v1, v6, v7
	v_cvt_pk_bf16_f32 v2, v8, v9
	v_cvt_pk_bf16_f32 v3, v10, v11
	v_lshl_add_u64 v[4:5], v[4:5], 0, v[114:115]
	s_mov_b64 s[20:21], s[14:15]
	global_store_dwordx4 v[4:5], v[0:3], off nt
	s_cbranch_vccz .LBB0_128
	s_waitcnt vmcnt(0)
	s_cmpk_gt_u32 s37, 0xff
	s_cbranch_scc1 .LBB0_135
	s_barrier

.LBB0_248:
	ds_read_b128 v[144:147], v151
	ds_read_b128 v[156:159], v151 offset:1024
	ds_read_b128 v[160:163], v151 offset:2048
	ds_read_b128 v[164:167], v151 offset:3072
	s_add_u32 s26, s20, 0x100
	s_addc_u32 s27, s21, 0
	s_cmp_eq_u32 s59, 40
	s_cselect_b32 s31, s9, s27
	s_cselect_b32 s30, s8, s26
	s_cselect_b32 s29, s11, s58
	s_cselect_b32 s28, s10, s57
	s_add_i32 m0, s41, 0xc000
	ds_read_b128 v[168:171], v152
	ds_read_b128 v[172:175], v152 offset:1024
	ds_read_b128 v[176:179], v152 offset:2048
	ds_read_b128 v[180:183], v152 offset:3072
	ds_read_b128 v[184:187], v152 offset:4096
	ds_read_b128 v[188:191], v152 offset:5120
	ds_read_b128 v[192:195], v152 offset:6144
	ds_read_b128 v[196:199], v152 offset:7168
	global_load_lds_dwordx4 v136, s[20:21]
	s_add_i32 m0, s41, 0xe000
	s_nop 0
	global_load_lds_dwordx4 v138, s[20:21]
	s_waitcnt lgkmcnt(8)
	s_barrier
	s_waitcnt lgkmcnt(0)
	s_setprio 1
	s_waitcnt lgkmcnt(0)
	v_mfma_f32_16x16x32_bf16 v[124:127], v[144:147], v[168:171], v[124:127]
	v_mfma_f32_16x16x32_bf16 v[120:123], v[160:163], v[168:171], v[120:123]
	v_mfma_f32_16x16x32_bf16 v[108:111], v[144:147], v[176:179], v[108:111]
	v_mfma_f32_16x16x32_bf16 v[104:107], v[160:163], v[176:179], v[104:107]
	v_mfma_f32_16x16x32_bf16 v[92:95], v[144:147], v[184:187], v[92:95]
	v_mfma_f32_16x16x32_bf16 v[88:91], v[160:163], v[184:187], v[88:91]
	v_mfma_f32_16x16x32_bf16 v[76:79], v[144:147], v[192:195], v[76:79]
	v_mfma_f32_16x16x32_bf16 v[72:75], v[160:163], v[192:195], v[72:75]
	v_mfma_f32_16x16x32_bf16 v[124:127], v[156:159], v[172:175], v[124:127]
	v_mfma_f32_16x16x32_bf16 v[120:123], v[164:167], v[172:175], v[120:123]
	v_mfma_f32_16x16x32_bf16 v[108:111], v[156:159], v[180:183], v[108:111]
	v_mfma_f32_16x16x32_bf16 v[104:107], v[164:167], v[180:183], v[104:107]
	v_mfma_f32_16x16x32_bf16 v[92:95], v[156:159], v[188:191], v[92:95]
	v_mfma_f32_16x16x32_bf16 v[88:91], v[164:167], v[188:191], v[88:91]
	v_mfma_f32_16x16x32_bf16 v[76:79], v[156:159], v[196:199], v[76:79]
	v_mfma_f32_16x16x32_bf16 v[72:75], v[164:167], v[196:199], v[72:75]
	s_setprio 0
	s_barrier
	s_add_i32 s20, s51, s40
	s_add_u32 s80, s28, 0x80
	s_addc_u32 s81, s29, 0
	s_mov_b32 m0, s20
	ds_read_b128 v[200:203], v153
	ds_read_b128 v[204:207], v153 offset:1024
	ds_read_b128 v[208:211], v153 offset:2048
	ds_read_b128 v[212:215], v153 offset:3072
	global_load_lds_dwordx4 v130, s[28:29]
	s_add_i32 m0, s20, 0x2000
	s_nop 0
	global_load_lds_dwordx4 v134, s[28:29]
	s_barrier
	s_waitcnt lgkmcnt(0)
	s_setprio 1
	s_waitcnt lgkmcnt(0)
	v_mfma_f32_16x16x32_bf16 v[116:119], v[200:203], v[168:171], v[116:119]
	v_mfma_f32_16x16x32_bf16 v[112:115], v[208:211], v[168:171], v[112:115]
	v_mfma_f32_16x16x32_bf16 v[100:103], v[200:203], v[176:179], v[100:103]
	v_mfma_f32_16x16x32_bf16 v[96:99], v[208:211], v[176:179], v[96:99]
	v_mfma_f32_16x16x32_bf16 v[84:87], v[200:203], v[184:187], v[84:87]
	v_mfma_f32_16x16x32_bf16 v[80:83], v[208:211], v[184:187], v[80:83]
	v_mfma_f32_16x16x32_bf16 v[68:71], v[200:203], v[192:195], v[68:71]
	v_mfma_f32_16x16x32_bf16 v[64:67], v[208:211], v[192:195], v[64:67]
	v_mfma_f32_16x16x32_bf16 v[116:119], v[204:207], v[172:175], v[116:119]
	v_mfma_f32_16x16x32_bf16 v[112:115], v[212:215], v[172:175], v[112:115]
	v_mfma_f32_16x16x32_bf16 v[100:103], v[204:207], v[180:183], v[100:103]
	v_mfma_f32_16x16x32_bf16 v[96:99], v[212:215], v[180:183], v[96:99]
	v_mfma_f32_16x16x32_bf16 v[84:87], v[204:207], v[188:191], v[84:87]
	v_mfma_f32_16x16x32_bf16 v[80:83], v[212:215], v[188:191], v[80:83]
	v_mfma_f32_16x16x32_bf16 v[68:71], v[204:207], v[196:199], v[68:71]
	v_mfma_f32_16x16x32_bf16 v[64:67], v[212:215], v[196:199], v[64:67]
	s_setprio 0
	s_mov_b32 m0, s41
	s_add_u32 s82, s30, 0x80
	s_addc_u32 s83, s31, 0
	s_barrier
	ds_read_b128 v[168:171], v152 offset:16384
	ds_read_b128 v[172:175], v152 offset:17408
	ds_read_b128 v[176:179], v152 offset:18432
	ds_read_b128 v[180:183], v152 offset:19456
	ds_read_b128 v[184:187], v152 offset:20480
	ds_read_b128 v[188:191], v152 offset:21504
	ds_read_b128 v[192:195], v152 offset:22528
	ds_read_b128 v[196:199], v152 offset:23552
	global_load_lds_dwordx4 v128, s[30:31]
	s_mov_b32 m0, s42
	s_nop 0
	global_load_lds_dwordx4 v132, s[30:31]
	s_barrier
	s_waitcnt lgkmcnt(0)
	s_setprio 1
	s_waitcnt lgkmcnt(0)
	v_mfma_f32_16x16x32_bf16 v[60:63], v[144:147], v[168:171], v[60:63]
	v_mfma_f32_16x16x32_bf16 v[56:59], v[160:163], v[168:171], v[56:59]
	v_mfma_f32_16x16x32_bf16 v[44:47], v[144:147], v[176:179], v[44:47]
	v_mfma_f32_16x16x32_bf16 v[40:43], v[160:163], v[176:179], v[40:43]
	v_mfma_f32_16x16x32_bf16 v[28:31], v[144:147], v[184:187], v[28:31]
	v_mfma_f32_16x16x32_bf16 v[24:27], v[160:163], v[184:187], v[24:27]
	v_mfma_f32_16x16x32_bf16 v[12:15], v[144:147], v[192:195], v[12:15]
	v_mfma_f32_16x16x32_bf16 v[8:11], v[160:163], v[192:195], v[8:11]
	v_mfma_f32_16x16x32_bf16 v[60:63], v[156:159], v[172:175], v[60:63]
	v_mfma_f32_16x16x32_bf16 v[56:59], v[164:167], v[172:175], v[56:59]
	v_mfma_f32_16x16x32_bf16 v[44:47], v[156:159], v[180:183], v[44:47]
	v_mfma_f32_16x16x32_bf16 v[40:43], v[164:167], v[180:183], v[40:43]
	v_mfma_f32_16x16x32_bf16 v[28:31], v[156:159], v[188:191], v[28:31]
	v_mfma_f32_16x16x32_bf16 v[24:27], v[164:167], v[188:191], v[24:27]
	v_mfma_f32_16x16x32_bf16 v[12:15], v[156:159], v[196:199], v[12:15]
	v_mfma_f32_16x16x32_bf16 v[8:11], v[164:167], v[196:199], v[8:11]
	s_setprio 0
	s_barrier
	s_add_u32 s20, s28, 0xb0000
	s_addc_u32 s21, s29, 0
	s_add_i32 s60, s52, s40
	s_mov_b32 m0, s60
	s_nop 0
	global_load_lds_dwordx4 v130, s[20:21]
	s_add_i32 m0, s60, 0x2000
	s_nop 0
	global_load_lds_dwordx4 v134, s[20:21]
	s_waitcnt vmcnt(6)
	s_barrier
	s_setprio 1
	v_mfma_f32_16x16x32_bf16 v[52:55], v[200:203], v[168:171], v[52:55]
	v_mfma_f32_16x16x32_bf16 v[48:51], v[208:211], v[168:171], v[48:51]
	v_mfma_f32_16x16x32_bf16 v[36:39], v[200:203], v[176:179], v[36:39]
	v_mfma_f32_16x16x32_bf16 v[32:35], v[208:211], v[176:179], v[32:35]
	v_mfma_f32_16x16x32_bf16 v[20:23], v[200:203], v[184:187], v[20:23]
	v_mfma_f32_16x16x32_bf16 v[16:19], v[208:211], v[184:187], v[16:19]
	v_mfma_f32_16x16x32_bf16 v[4:7], v[200:203], v[192:195], v[4:7]
	v_mfma_f32_16x16x32_bf16 v[0:3], v[208:211], v[192:195], v[0:3]
	v_mfma_f32_16x16x32_bf16 v[52:55], v[204:207], v[172:175], v[52:55]
	v_mfma_f32_16x16x32_bf16 v[48:51], v[212:215], v[172:175], v[48:51]
	v_mfma_f32_16x16x32_bf16 v[36:39], v[204:207], v[180:183], v[36:39]
	v_mfma_f32_16x16x32_bf16 v[32:35], v[212:215], v[180:183], v[32:35]
	v_mfma_f32_16x16x32_bf16 v[20:23], v[204:207], v[188:191], v[20:23]
	v_mfma_f32_16x16x32_bf16 v[16:19], v[212:215], v[188:191], v[16:19]
	v_mfma_f32_16x16x32_bf16 v[4:7], v[204:207], v[196:199], v[4:7]
	v_mfma_f32_16x16x32_bf16 v[0:3], v[212:215], v[196:199], v[0:3]
	s_setprio 0
	s_add_i32 s60, 0, 0x18000
	v_add_u32_e32 v155, s60, v149
	s_barrier
	ds_read_b128 v[144:147], v155
	ds_read_b128 v[156:159], v155 offset:1024
	ds_read_b128 v[160:163], v155 offset:2048
	ds_read_b128 v[164:167], v155 offset:3072
	s_add_u32 s20, s30, 0xb0000
	s_addc_u32 s21, s31, 0
	s_mov_b32 m0, s43
	ds_read_b128 v[168:171], v152 offset:32768
	ds_read_b128 v[172:175], v152 offset:33792
	ds_read_b128 v[176:179], v152 offset:34816
	ds_read_b128 v[180:183], v152 offset:35840
	ds_read_b128 v[184:187], v152 offset:36864
	ds_read_b128 v[188:191], v152 offset:37888
	ds_read_b128 v[192:195], v152 offset:38912
	ds_read_b128 v[196:199], v152 offset:39936
	global_load_lds_dwordx4 v128, s[20:21]
	s_mov_b32 m0, s44
	s_nop 0
	global_load_lds_dwordx4 v132, s[20:21]
	s_waitcnt lgkmcnt(8)
	s_barrier
	s_waitcnt lgkmcnt(0)
	s_setprio 1
	s_waitcnt lgkmcnt(0)
	v_mfma_f32_16x16x32_bf16 v[124:127], v[144:147], v[168:171], v[124:127]
	v_mfma_f32_16x16x32_bf16 v[120:123], v[160:163], v[168:171], v[120:123]
	v_mfma_f32_16x16x32_bf16 v[108:111], v[144:147], v[176:179], v[108:111]
	v_mfma_f32_16x16x32_bf16 v[104:107], v[160:163], v[176:179], v[104:107]
	v_mfma_f32_16x16x32_bf16 v[92:95], v[144:147], v[184:187], v[92:95]
	v_mfma_f32_16x16x32_bf16 v[88:91], v[160:163], v[184:187], v[88:91]
	v_mfma_f32_16x16x32_bf16 v[76:79], v[144:147], v[192:195], v[76:79]
	v_mfma_f32_16x16x32_bf16 v[72:75], v[160:163], v[192:195], v[72:75]
	v_mfma_f32_16x16x32_bf16 v[124:127], v[156:159], v[172:175], v[124:127]
	v_mfma_f32_16x16x32_bf16 v[120:123], v[164:167], v[172:175], v[120:123]
	v_mfma_f32_16x16x32_bf16 v[108:111], v[156:159], v[180:183], v[108:111]
	v_mfma_f32_16x16x32_bf16 v[104:107], v[164:167], v[180:183], v[104:107]
	v_mfma_f32_16x16x32_bf16 v[92:95], v[156:159], v[188:191], v[92:95]
	v_mfma_f32_16x16x32_bf16 v[88:91], v[164:167], v[188:191], v[88:91]
	v_mfma_f32_16x16x32_bf16 v[76:79], v[156:159], v[196:199], v[76:79]
	v_mfma_f32_16x16x32_bf16 v[72:75], v[164:167], v[196:199], v[72:75]
	s_setprio 0
	s_barrier
	s_add_i32 s30, 0, 0x1c000
	s_add_i32 s20, s60, s40
	v_add_u32_e32 v155, s30, v149
	s_mov_b32 m0, s20
	ds_read_b128 v[200:203], v155
	ds_read_b128 v[204:207], v155 offset:1024
	ds_read_b128 v[208:211], v155 offset:2048
	ds_read_b128 v[212:215], v155 offset:3072
	global_load_lds_dwordx4 v130, s[80:81]
	s_add_i32 m0, s20, 0x2000
	s_nop 0
	global_load_lds_dwordx4 v134, s[80:81]
	s_barrier
	s_waitcnt lgkmcnt(0)
	s_setprio 1
	s_waitcnt lgkmcnt(0)
	v_mfma_f32_16x16x32_bf16 v[116:119], v[200:203], v[168:171], v[116:119]
	v_mfma_f32_16x16x32_bf16 v[112:115], v[208:211], v[168:171], v[112:115]
	v_mfma_f32_16x16x32_bf16 v[100:103], v[200:203], v[176:179], v[100:103]
	v_mfma_f32_16x16x32_bf16 v[96:99], v[208:211], v[176:179], v[96:99]
	v_mfma_f32_16x16x32_bf16 v[84:87], v[200:203], v[184:187], v[84:87]
	v_mfma_f32_16x16x32_bf16 v[80:83], v[208:211], v[184:187], v[80:83]
	v_mfma_f32_16x16x32_bf16 v[68:71], v[200:203], v[192:195], v[68:71]
	v_mfma_f32_16x16x32_bf16 v[64:67], v[208:211], v[192:195], v[64:67]
	v_mfma_f32_16x16x32_bf16 v[116:119], v[204:207], v[172:175], v[116:119]
	v_mfma_f32_16x16x32_bf16 v[112:115], v[212:215], v[172:175], v[112:115]
	v_mfma_f32_16x16x32_bf16 v[100:103], v[204:207], v[180:183], v[100:103]
	v_mfma_f32_16x16x32_bf16 v[96:99], v[212:215], v[180:183], v[96:99]
	v_mfma_f32_16x16x32_bf16 v[84:87], v[204:207], v[188:191], v[84:87]
	v_mfma_f32_16x16x32_bf16 v[80:83], v[212:215], v[188:191], v[80:83]
	v_mfma_f32_16x16x32_bf16 v[68:71], v[204:207], v[196:199], v[68:71]
	v_mfma_f32_16x16x32_bf16 v[64:67], v[212:215], v[196:199], v[64:67]
	s_setprio 0
	s_mov_b32 m0, s46
	s_barrier
	ds_read_b128 v[168:171], v152 offset:49152
	ds_read_b128 v[172:175], v152 offset:50176
	ds_read_b128 v[176:179], v152 offset:51200
	ds_read_b128 v[180:183], v152 offset:52224
	ds_read_b128 v[184:187], v152 offset:53248
	ds_read_b128 v[188:191], v152 offset:54272
	ds_read_b128 v[192:195], v152 offset:55296
	ds_read_b128 v[196:199], v152 offset:56320
	global_load_lds_dwordx4 v128, s[82:83]
	s_mov_b32 m0, s47
	s_nop 0
	global_load_lds_dwordx4 v132, s[82:83]
	s_barrier
	s_waitcnt lgkmcnt(0)
	s_setprio 1
	s_waitcnt lgkmcnt(0)
	v_mfma_f32_16x16x32_bf16 v[60:63], v[144:147], v[168:171], v[60:63]
	v_mfma_f32_16x16x32_bf16 v[56:59], v[160:163], v[168:171], v[56:59]
	v_mfma_f32_16x16x32_bf16 v[44:47], v[144:147], v[176:179], v[44:47]
	v_mfma_f32_16x16x32_bf16 v[40:43], v[160:163], v[176:179], v[40:43]
	v_mfma_f32_16x16x32_bf16 v[28:31], v[144:147], v[184:187], v[28:31]
	v_mfma_f32_16x16x32_bf16 v[24:27], v[160:163], v[184:187], v[24:27]
	v_mfma_f32_16x16x32_bf16 v[12:15], v[144:147], v[192:195], v[12:15]
	v_mfma_f32_16x16x32_bf16 v[8:11], v[160:163], v[192:195], v[8:11]
	v_mfma_f32_16x16x32_bf16 v[60:63], v[156:159], v[172:175], v[60:63]
	v_mfma_f32_16x16x32_bf16 v[56:59], v[164:167], v[172:175], v[56:59]
	v_mfma_f32_16x16x32_bf16 v[44:47], v[156:159], v[180:183], v[44:47]
	v_mfma_f32_16x16x32_bf16 v[40:43], v[164:167], v[180:183], v[40:43]
	v_mfma_f32_16x16x32_bf16 v[28:31], v[156:159], v[188:191], v[28:31]
	v_mfma_f32_16x16x32_bf16 v[24:27], v[164:167], v[188:191], v[24:27]
	v_mfma_f32_16x16x32_bf16 v[12:15], v[156:159], v[196:199], v[12:15]
	v_mfma_f32_16x16x32_bf16 v[8:11], v[164:167], v[196:199], v[8:11]
	s_setprio 0
	s_barrier
	s_add_u32 s20, s28, 0xb0080
	s_addc_u32 s21, s29, 0
	s_add_i32 s28, s30, s40
	s_mov_b32 m0, s28
	s_nop 0
	global_load_lds_dwordx4 v130, s[20:21]
	s_add_i32 m0, s28, 0x2000
	s_nop 0
	global_load_lds_dwordx4 v134, s[20:21]
	s_waitcnt vmcnt(6)
	s_barrier
	s_setprio 1
	v_mfma_f32_16x16x32_bf16 v[52:55], v[200:203], v[168:171], v[52:55]
	v_mfma_f32_16x16x32_bf16 v[48:51], v[208:211], v[168:171], v[48:51]
	v_mfma_f32_16x16x32_bf16 v[36:39], v[200:203], v[176:179], v[36:39]
	v_mfma_f32_16x16x32_bf16 v[32:35], v[208:211], v[176:179], v[32:35]
	v_mfma_f32_16x16x32_bf16 v[20:23], v[200:203], v[184:187], v[20:23]
	v_mfma_f32_16x16x32_bf16 v[16:19], v[208:211], v[184:187], v[16:19]
	v_mfma_f32_16x16x32_bf16 v[4:7], v[200:203], v[192:195], v[4:7]
	v_mfma_f32_16x16x32_bf16 v[0:3], v[208:211], v[192:195], v[0:3]
	v_mfma_f32_16x16x32_bf16 v[52:55], v[204:207], v[172:175], v[52:55]
	v_mfma_f32_16x16x32_bf16 v[48:51], v[212:215], v[172:175], v[48:51]
	v_mfma_f32_16x16x32_bf16 v[36:39], v[204:207], v[180:183], v[36:39]
	v_mfma_f32_16x16x32_bf16 v[32:35], v[212:215], v[180:183], v[32:35]
	v_mfma_f32_16x16x32_bf16 v[20:23], v[204:207], v[188:191], v[20:23]
	v_mfma_f32_16x16x32_bf16 v[16:19], v[212:215], v[188:191], v[16:19]
	v_mfma_f32_16x16x32_bf16 v[4:7], v[204:207], v[196:199], v[4:7]
	v_mfma_f32_16x16x32_bf16 v[0:3], v[212:215], v[196:199], v[0:3]
	s_setprio 0
	s_add_i32 s59, s59, 2
	s_add_u32 s57, s57, 0x100
	s_addc_u32 s58, s58, 0
	s_cmp_gt_u32 s59, 41
	s_mov_b64 s[20:21], s[26:27]
	s_barrier
	s_cbranch_scc0 .LBB0_248
	v_lshl_add_u32 v146, s56, 8, v148
	v_ashrrev_i32_e32 v147, 31, v146
	v_lshl_or_b32 v144, s12, 8, v150
	v_lshlrev_b64 v[156:157], 11, v[146:147]
	v_ashrrev_i32_e32 v145, 31, v144
	v_lshl_add_u64 v[156:157], s[14:15], 0, v[156:157]
	v_lshl_add_u64 v[166:167], v[144:145], 1, v[156:157]
	global_load_dwordx4 v[158:161], v[166:167], off
	global_load_dwordx4 v[162:165], v[166:167], off offset:256
	v_and_b32_e32 v156, 64, v154
	v_xor_b32_e32 v155, 16, v154
	v_add_u32_e32 v156, 64, v156
	v_xor_b32_e32 v157, 32, v154
	v_cmp_lt_i32_e32 vcc, v155, v156
	s_lshl_b32 s20, s12, 2
	s_ashr_i32 s21, s20, 31
	v_cndmask_b32_e32 v155, v154, v155, vcc
	v_cmp_lt_i32_e32 vcc, v157, v156
	v_lshlrev_b32_e32 v156, 2, v155
	s_waitcnt vmcnt(0)
	v_lshlrev_b32_e32 v168, 16, v158
	v_and_b32_e32 v169, 0xffff0000, v158
	v_lshlrev_b32_e32 v158, 16, v159
	v_and_b32_e32 v159, 0xffff0000, v159
	v_lshlrev_b32_e32 v172, 16, v162
	v_and_b32_e32 v173, 0xffff0000, v162
	v_lshlrev_b32_e32 v162, 16, v163
	v_and_b32_e32 v163, 0xffff0000, v163
	v_cndmask_b32_e32 v157, v154, v157, vcc
	v_lshlrev_b32_e32 v170, 16, v160
	v_and_b32_e32 v171, 0xffff0000, v160
	v_lshlrev_b32_e32 v160, 16, v161
	v_and_b32_e32 v161, 0xffff0000, v161
	v_lshlrev_b32_e32 v174, 16, v164
	v_and_b32_e32 v175, 0xffff0000, v164
	v_lshlrev_b32_e32 v164, 16, v165
	v_and_b32_e32 v165, 0xffff0000, v165
	v_pk_fma_f32 v[126:127], v[126:127], 0.5, v[158:159] op_sel_hi:[1,0,1]
	v_pk_fma_f32 v[124:125], v[124:125], 0.5, v[168:169] op_sel_hi:[1,0,1]
	v_pk_fma_f32 v[118:119], v[118:119], 0.5, v[162:163] op_sel_hi:[1,0,1]
	v_pk_fma_f32 v[116:117], v[116:117], 0.5, v[172:173] op_sel_hi:[1,0,1]
	v_lshlrev_b32_e32 v155, 2, v157
	v_pk_fma_f32 v[122:123], v[122:123], 0.5, v[160:161] op_sel_hi:[1,0,1]
	v_pk_fma_f32 v[120:121], v[120:121], 0.5, v[170:171] op_sel_hi:[1,0,1]
	v_pk_fma_f32 v[158:159], v[114:115], 0.5, v[164:165] op_sel_hi:[1,0,1]
	v_pk_fma_f32 v[160:161], v[112:113], 0.5, v[174:175] op_sel_hi:[1,0,1]
	v_mul_f32_e32 v114, v125, v125
	v_mul_f32_e32 v115, v127, v127
	v_mul_f32_e32 v157, v117, v117
	v_mul_f32_e32 v162, v119, v119
	v_cvt_pk_bf16_f32 v112, v124, v125
	v_mul_f32_e32 v125, v121, v121
	v_mul_f32_e32 v163, v161, v161
	v_fmac_f32_e32 v114, v124, v124
	v_fmac_f32_e32 v115, v126, v126
	v_fmac_f32_e32 v157, v116, v116
	v_fmac_f32_e32 v162, v118, v118
	v_cvt_pk_bf16_f32 v113, v126, v127
	v_mul_f32_e32 v127, v123, v123
	v_mul_f32_e32 v164, v159, v159
	v_fmac_f32_e32 v125, v120, v120
	v_fmac_f32_e32 v163, v160, v160
	v_add_f32_e32 v114, v114, v115
	v_add_f32_e32 v115, v157, v162
	v_fmac_f32_e32 v127, v122, v122
	v_fmac_f32_e32 v164, v158, v158
	v_add_f32_e32 v114, v125, v114
	v_add_f32_e32 v115, v163, v115
	v_add_f32_e32 v114, v127, v114
	v_add_f32_e32 v115, v164, v115
	v_add_f32_e32 v124, v114, v115
	ds_bpermute_b32 v125, v156, v124
	v_cvt_pk_bf16_f32 v114, v120, v121
	v_cvt_pk_bf16_f32 v115, v122, v123
	global_store_dwordx4 v[166:167], v[112:115], off
	s_waitcnt lgkmcnt(0)
	s_nop 0
	v_add_f32_e32 v112, v124, v125
	ds_bpermute_b32 v113, v155, v112
	v_cvt_pk_bf16_f32 v114, v116, v117
	v_cvt_pk_bf16_f32 v115, v118, v119
	v_cvt_pk_bf16_f32 v116, v160, v161
	v_cvt_pk_bf16_f32 v117, v158, v159
	global_store_dwordx4 v[166:167], v[114:117], off offset:256
	s_and_saveexec_b64 s[26:27], s[4:5]
	s_cbranch_execz .LBB0_251
	v_lshlrev_b64 v[114:115], 6, v[146:147]
	v_lshl_add_u64 v[114:115], s[16:17], 0, v[114:115]
	v_lshl_add_u64 v[114:115], s[20:21], 2, v[114:115]
	s_lshl_b32 s12, s45, 2
	v_lshl_add_u64 v[114:115], v[114:115], 0, s[12:13]
	s_waitcnt lgkmcnt(0)
	v_add_f32_e32 v112, v112, v113
	global_store_dword v[114:115], v112, off

.LBB0_359:
	ds_read_b128 v[128:131], v181
	ds_read_b128 v[132:135], v181 offset:1024
	ds_read_b128 v[136:139], v181 offset:2048
	ds_read_b128 v[166:169], v181 offset:3072
	s_add_u32 s38, s8, 0xfffc0080
	s_addc_u32 s39, s9, -1
	s_cmp_eq_u32 s75, 12
	s_cselect_b32 s41, s21, s39
	s_cselect_b32 s40, s71, s38
	s_cselect_b32 s39, s19, s74
	s_cselect_b32 s38, s72, s73
	s_add_i32 m0, s37, 0xc000
	ds_read_b128 v[170:173], v182
	ds_read_b128 v[174:177], v182 offset:1024
	ds_read_b128 v[192:195], v182 offset:2048
	ds_read_b128 v[196:199], v182 offset:3072
	ds_read_b128 v[200:203], v182 offset:4096
	ds_read_b128 v[204:207], v182 offset:5120
	ds_read_b128 v[208:211], v182 offset:6144
	ds_read_b128 v[212:215], v182 offset:7168
	global_load_lds_dwordx4 v158, s[8:9]
	s_add_i32 m0, s37, 0xe000
	s_nop 0
	global_load_lds_dwordx4 v160, s[8:9]
	s_waitcnt lgkmcnt(8)
	s_barrier
	s_waitcnt lgkmcnt(0)
	s_setprio 1
	s_waitcnt lgkmcnt(0)
	v_mfma_f32_16x16x32_bf16 v[124:127], v[128:131], v[170:173], v[124:127]
	v_mfma_f32_16x16x32_bf16 v[116:119], v[136:139], v[170:173], v[116:119]
	v_mfma_f32_16x16x32_bf16 v[108:111], v[128:131], v[192:195], v[108:111]
	v_mfma_f32_16x16x32_bf16 v[100:103], v[136:139], v[192:195], v[100:103]
	v_mfma_f32_16x16x32_bf16 v[92:95], v[128:131], v[200:203], v[92:95]
	v_mfma_f32_16x16x32_bf16 v[84:87], v[136:139], v[200:203], v[84:87]
	v_mfma_f32_16x16x32_bf16 v[76:79], v[128:131], v[208:211], v[76:79]
	v_mfma_f32_16x16x32_bf16 v[68:71], v[136:139], v[208:211], v[68:71]
	v_mfma_f32_16x16x32_bf16 v[124:127], v[132:135], v[174:177], v[124:127]
	v_mfma_f32_16x16x32_bf16 v[116:119], v[166:169], v[174:177], v[116:119]
	v_mfma_f32_16x16x32_bf16 v[108:111], v[132:135], v[196:199], v[108:111]
	v_mfma_f32_16x16x32_bf16 v[100:103], v[166:169], v[196:199], v[100:103]
	v_mfma_f32_16x16x32_bf16 v[92:95], v[132:135], v[204:207], v[92:95]
	v_mfma_f32_16x16x32_bf16 v[84:87], v[166:169], v[204:207], v[84:87]
	v_mfma_f32_16x16x32_bf16 v[76:79], v[132:135], v[212:215], v[76:79]
	v_mfma_f32_16x16x32_bf16 v[68:71], v[166:169], v[212:215], v[68:71]
	s_setprio 0
	s_barrier
	s_add_i32 s76, s63, s46
	s_add_u32 s80, s38, 0x80
	s_addc_u32 s81, s39, 0
	s_mov_b32 m0, s76
	ds_read_b128 v[216:219], v183
	ds_read_b128 v[220:223], v183 offset:1024
	ds_read_b128 v[224:227], v183 offset:2048
	ds_read_b128 v[228:231], v183 offset:3072
	global_load_lds_dwordx4 v144, s[38:39]
	s_add_i32 m0, s76, 0x2000
	s_nop 0
	global_load_lds_dwordx4 v148, s[38:39]
	s_barrier
	s_waitcnt lgkmcnt(0)
	s_setprio 1
	s_waitcnt lgkmcnt(0)
	v_mfma_f32_16x16x32_bf16 v[120:123], v[216:219], v[170:173], v[120:123]
	v_mfma_f32_16x16x32_bf16 v[112:115], v[224:227], v[170:173], v[112:115]
	v_mfma_f32_16x16x32_bf16 v[104:107], v[216:219], v[192:195], v[104:107]
	v_mfma_f32_16x16x32_bf16 v[96:99], v[224:227], v[192:195], v[96:99]
	v_mfma_f32_16x16x32_bf16 v[88:91], v[216:219], v[200:203], v[88:91]
	v_mfma_f32_16x16x32_bf16 v[80:83], v[224:227], v[200:203], v[80:83]
	v_mfma_f32_16x16x32_bf16 v[72:75], v[216:219], v[208:211], v[72:75]
	v_mfma_f32_16x16x32_bf16 v[64:67], v[224:227], v[208:211], v[64:67]
	v_mfma_f32_16x16x32_bf16 v[120:123], v[220:223], v[174:177], v[120:123]
	v_mfma_f32_16x16x32_bf16 v[112:115], v[228:231], v[174:177], v[112:115]
	v_mfma_f32_16x16x32_bf16 v[104:107], v[220:223], v[196:199], v[104:107]
	v_mfma_f32_16x16x32_bf16 v[96:99], v[228:231], v[196:199], v[96:99]
	v_mfma_f32_16x16x32_bf16 v[88:91], v[220:223], v[204:207], v[88:91]
	v_mfma_f32_16x16x32_bf16 v[80:83], v[228:231], v[204:207], v[80:83]
	v_mfma_f32_16x16x32_bf16 v[72:75], v[220:223], v[212:215], v[72:75]
	v_mfma_f32_16x16x32_bf16 v[64:67], v[228:231], v[212:215], v[64:67]
	s_setprio 0
	s_mov_b32 m0, s37
	s_add_u32 s82, s40, 0x80
	s_addc_u32 s83, s41, 0
	s_barrier
	ds_read_b128 v[170:173], v182 offset:16384
	ds_read_b128 v[174:177], v182 offset:17408
	ds_read_b128 v[192:195], v182 offset:18432
	ds_read_b128 v[196:199], v182 offset:19456
	ds_read_b128 v[200:203], v182 offset:20480
	ds_read_b128 v[204:207], v182 offset:21504
	ds_read_b128 v[208:211], v182 offset:22528
	ds_read_b128 v[212:215], v182 offset:23552
	global_load_lds_dwordx4 v142, s[40:41]
	s_mov_b32 m0, s51
	s_nop 0
	global_load_lds_dwordx4 v146, s[40:41]
	s_barrier
	s_waitcnt lgkmcnt(0)
	s_setprio 1
	s_waitcnt lgkmcnt(0)
	v_mfma_f32_16x16x32_bf16 v[60:63], v[128:131], v[170:173], v[60:63]
	v_mfma_f32_16x16x32_bf16 v[52:55], v[136:139], v[170:173], v[52:55]
	v_mfma_f32_16x16x32_bf16 v[44:47], v[128:131], v[192:195], v[44:47]
	v_mfma_f32_16x16x32_bf16 v[36:39], v[136:139], v[192:195], v[36:39]
	v_mfma_f32_16x16x32_bf16 v[28:31], v[128:131], v[200:203], v[28:31]
	v_mfma_f32_16x16x32_bf16 v[20:23], v[136:139], v[200:203], v[20:23]
	v_mfma_f32_16x16x32_bf16 v[12:15], v[128:131], v[208:211], v[12:15]
	v_mfma_f32_16x16x32_bf16 v[4:7], v[136:139], v[208:211], v[4:7]
	v_mfma_f32_16x16x32_bf16 v[60:63], v[132:135], v[174:177], v[60:63]
	v_mfma_f32_16x16x32_bf16 v[52:55], v[166:169], v[174:177], v[52:55]
	v_mfma_f32_16x16x32_bf16 v[44:47], v[132:135], v[196:199], v[44:47]
	v_mfma_f32_16x16x32_bf16 v[36:39], v[166:169], v[196:199], v[36:39]
	v_mfma_f32_16x16x32_bf16 v[28:31], v[132:135], v[204:207], v[28:31]
	v_mfma_f32_16x16x32_bf16 v[20:23], v[166:169], v[204:207], v[20:23]
	v_mfma_f32_16x16x32_bf16 v[12:15], v[132:135], v[212:215], v[12:15]
	v_mfma_f32_16x16x32_bf16 v[4:7], v[166:169], v[212:215], v[4:7]
	s_setprio 0
	s_barrier
	s_add_u32 s76, s38, 0x40000
	s_addc_u32 s77, s39, 0
	s_add_i32 s78, s64, s46
	s_mov_b32 m0, s78
	s_nop 0
	global_load_lds_dwordx4 v144, s[76:77]
	s_add_i32 m0, s78, 0x2000
	s_nop 0
	global_load_lds_dwordx4 v148, s[76:77]
	s_waitcnt vmcnt(6)
	s_barrier
	s_setprio 1
	v_mfma_f32_16x16x32_bf16 v[56:59], v[216:219], v[170:173], v[56:59]
	v_mfma_f32_16x16x32_bf16 v[48:51], v[224:227], v[170:173], v[48:51]
	v_mfma_f32_16x16x32_bf16 v[40:43], v[216:219], v[192:195], v[40:43]
	v_mfma_f32_16x16x32_bf16 v[32:35], v[224:227], v[192:195], v[32:35]
	v_mfma_f32_16x16x32_bf16 v[24:27], v[216:219], v[200:203], v[24:27]
	v_mfma_f32_16x16x32_bf16 v[16:19], v[224:227], v[200:203], v[16:19]
	v_mfma_f32_16x16x32_bf16 v[8:11], v[216:219], v[208:211], v[8:11]
	v_mfma_f32_16x16x32_bf16 v[0:3], v[224:227], v[208:211], v[0:3]
	v_mfma_f32_16x16x32_bf16 v[56:59], v[220:223], v[174:177], v[56:59]
	v_mfma_f32_16x16x32_bf16 v[48:51], v[228:231], v[174:177], v[48:51]
	v_mfma_f32_16x16x32_bf16 v[40:43], v[220:223], v[196:199], v[40:43]
	v_mfma_f32_16x16x32_bf16 v[32:35], v[228:231], v[196:199], v[32:35]
	v_mfma_f32_16x16x32_bf16 v[24:27], v[220:223], v[204:207], v[24:27]
	v_mfma_f32_16x16x32_bf16 v[16:19], v[228:231], v[204:207], v[16:19]
	v_mfma_f32_16x16x32_bf16 v[8:11], v[220:223], v[212:215], v[8:11]
	v_mfma_f32_16x16x32_bf16 v[0:3], v[228:231], v[212:215], v[0:3]
	s_setprio 0
	s_add_i32 s76, 0, 0x18000
	v_add_u32_e32 v150, s76, v179
	s_barrier
	ds_read_b128 v[128:131], v150
	ds_read_b128 v[132:135], v150 offset:1024
	ds_read_b128 v[136:139], v150 offset:2048
	ds_read_b128 v[166:169], v150 offset:3072
	s_add_u32 s40, s40, 0x40000
	s_addc_u32 s41, s41, 0
	s_mov_b32 m0, s52
	ds_read_b128 v[170:173], v182 offset:32768
	ds_read_b128 v[174:177], v182 offset:33792
	ds_read_b128 v[192:195], v182 offset:34816
	ds_read_b128 v[196:199], v182 offset:35840
	ds_read_b128 v[200:203], v182 offset:36864
	ds_read_b128 v[204:207], v182 offset:37888
	ds_read_b128 v[208:211], v182 offset:38912
	ds_read_b128 v[212:215], v182 offset:39936
	global_load_lds_dwordx4 v142, s[40:41]
	s_mov_b32 m0, s53
	s_nop 0
	global_load_lds_dwordx4 v146, s[40:41]
	s_waitcnt lgkmcnt(8)
	s_barrier
	s_waitcnt lgkmcnt(0)
	s_setprio 1
	s_waitcnt lgkmcnt(0)
	v_mfma_f32_16x16x32_bf16 v[124:127], v[128:131], v[170:173], v[124:127]
	v_mfma_f32_16x16x32_bf16 v[116:119], v[136:139], v[170:173], v[116:119]
	v_mfma_f32_16x16x32_bf16 v[108:111], v[128:131], v[192:195], v[108:111]
	v_mfma_f32_16x16x32_bf16 v[100:103], v[136:139], v[192:195], v[100:103]
	v_mfma_f32_16x16x32_bf16 v[92:95], v[128:131], v[200:203], v[92:95]
	v_mfma_f32_16x16x32_bf16 v[84:87], v[136:139], v[200:203], v[84:87]
	v_mfma_f32_16x16x32_bf16 v[76:79], v[128:131], v[208:211], v[76:79]
	v_mfma_f32_16x16x32_bf16 v[68:71], v[136:139], v[208:211], v[68:71]
	v_mfma_f32_16x16x32_bf16 v[124:127], v[132:135], v[174:177], v[124:127]
	v_mfma_f32_16x16x32_bf16 v[116:119], v[166:169], v[174:177], v[116:119]
	v_mfma_f32_16x16x32_bf16 v[108:111], v[132:135], v[196:199], v[108:111]
	v_mfma_f32_16x16x32_bf16 v[100:103], v[166:169], v[196:199], v[100:103]
	v_mfma_f32_16x16x32_bf16 v[92:95], v[132:135], v[204:207], v[92:95]
	v_mfma_f32_16x16x32_bf16 v[84:87], v[166:169], v[204:207], v[84:87]
	v_mfma_f32_16x16x32_bf16 v[76:79], v[132:135], v[212:215], v[76:79]
	v_mfma_f32_16x16x32_bf16 v[68:71], v[166:169], v[212:215], v[68:71]
	s_setprio 0
	s_barrier
	s_add_i32 s40, 0, 0x1c000
	s_add_i32 s41, s76, s46
	v_add_u32_e32 v150, s40, v179
	s_mov_b32 m0, s41
	ds_read_b128 v[216:219], v150
	ds_read_b128 v[220:223], v150 offset:1024
	ds_read_b128 v[224:227], v150 offset:2048
	ds_read_b128 v[228:231], v150 offset:3072
	global_load_lds_dwordx4 v144, s[80:81]
	s_add_i32 m0, s41, 0x2000
	s_nop 0
	global_load_lds_dwordx4 v148, s[80:81]
	s_barrier
	s_waitcnt lgkmcnt(0)
	s_setprio 1
	s_waitcnt lgkmcnt(0)
	v_mfma_f32_16x16x32_bf16 v[120:123], v[216:219], v[170:173], v[120:123]
	v_mfma_f32_16x16x32_bf16 v[112:115], v[224:227], v[170:173], v[112:115]
	v_mfma_f32_16x16x32_bf16 v[104:107], v[216:219], v[192:195], v[104:107]
	v_mfma_f32_16x16x32_bf16 v[96:99], v[224:227], v[192:195], v[96:99]
	v_mfma_f32_16x16x32_bf16 v[88:91], v[216:219], v[200:203], v[88:91]
	v_mfma_f32_16x16x32_bf16 v[80:83], v[224:227], v[200:203], v[80:83]
	v_mfma_f32_16x16x32_bf16 v[72:75], v[216:219], v[208:211], v[72:75]
	v_mfma_f32_16x16x32_bf16 v[64:67], v[224:227], v[208:211], v[64:67]
	v_mfma_f32_16x16x32_bf16 v[120:123], v[220:223], v[174:177], v[120:123]
	v_mfma_f32_16x16x32_bf16 v[112:115], v[228:231], v[174:177], v[112:115]
	v_mfma_f32_16x16x32_bf16 v[104:107], v[220:223], v[196:199], v[104:107]
	v_mfma_f32_16x16x32_bf16 v[96:99], v[228:231], v[196:199], v[96:99]
	v_mfma_f32_16x16x32_bf16 v[88:91], v[220:223], v[204:207], v[88:91]
	v_mfma_f32_16x16x32_bf16 v[80:83], v[228:231], v[204:207], v[80:83]
	v_mfma_f32_16x16x32_bf16 v[72:75], v[220:223], v[212:215], v[72:75]
	v_mfma_f32_16x16x32_bf16 v[64:67], v[228:231], v[212:215], v[64:67]
	s_setprio 0
	s_mov_b32 m0, s55
	s_barrier
	ds_read_b128 v[170:173], v182 offset:49152
	ds_read_b128 v[174:177], v182 offset:50176
	ds_read_b128 v[192:195], v182 offset:51200
	ds_read_b128 v[196:199], v182 offset:52224
	ds_read_b128 v[200:203], v182 offset:53248
	ds_read_b128 v[204:207], v182 offset:54272
	ds_read_b128 v[208:211], v182 offset:55296
	ds_read_b128 v[212:215], v182 offset:56320
	global_load_lds_dwordx4 v142, s[82:83]
	s_mov_b32 m0, s56
	s_nop 0
	global_load_lds_dwordx4 v146, s[82:83]
	s_barrier
	s_waitcnt lgkmcnt(0)
	s_setprio 1
	s_waitcnt lgkmcnt(0)
	v_mfma_f32_16x16x32_bf16 v[60:63], v[128:131], v[170:173], v[60:63]
	v_mfma_f32_16x16x32_bf16 v[52:55], v[136:139], v[170:173], v[52:55]
	v_mfma_f32_16x16x32_bf16 v[44:47], v[128:131], v[192:195], v[44:47]
	v_mfma_f32_16x16x32_bf16 v[36:39], v[136:139], v[192:195], v[36:39]
	v_mfma_f32_16x16x32_bf16 v[28:31], v[128:131], v[200:203], v[28:31]
	v_mfma_f32_16x16x32_bf16 v[20:23], v[136:139], v[200:203], v[20:23]
	v_mfma_f32_16x16x32_bf16 v[12:15], v[128:131], v[208:211], v[12:15]
	v_mfma_f32_16x16x32_bf16 v[4:7], v[136:139], v[208:211], v[4:7]
	v_mfma_f32_16x16x32_bf16 v[60:63], v[132:135], v[174:177], v[60:63]
	v_mfma_f32_16x16x32_bf16 v[52:55], v[166:169], v[174:177], v[52:55]
	v_mfma_f32_16x16x32_bf16 v[44:47], v[132:135], v[196:199], v[44:47]
	v_mfma_f32_16x16x32_bf16 v[36:39], v[166:169], v[196:199], v[36:39]
	v_mfma_f32_16x16x32_bf16 v[28:31], v[132:135], v[204:207], v[28:31]
	v_mfma_f32_16x16x32_bf16 v[20:23], v[166:169], v[204:207], v[20:23]
	v_mfma_f32_16x16x32_bf16 v[12:15], v[132:135], v[212:215], v[12:15]
	v_mfma_f32_16x16x32_bf16 v[4:7], v[166:169], v[212:215], v[4:7]
	s_setprio 0
	s_barrier
	s_add_u32 s38, s38, 0x40080
	s_addc_u32 s39, s39, 0
	s_add_i32 s40, s40, s46
	s_mov_b32 m0, s40
	s_nop 0
	global_load_lds_dwordx4 v144, s[38:39]
	s_add_i32 m0, s40, 0x2000
	s_nop 0
	global_load_lds_dwordx4 v148, s[38:39]
	s_waitcnt vmcnt(6)
	s_barrier
	s_setprio 1
	v_mfma_f32_16x16x32_bf16 v[56:59], v[216:219], v[170:173], v[56:59]
	v_mfma_f32_16x16x32_bf16 v[48:51], v[224:227], v[170:173], v[48:51]
	v_mfma_f32_16x16x32_bf16 v[40:43], v[216:219], v[192:195], v[40:43]
	v_mfma_f32_16x16x32_bf16 v[32:35], v[224:227], v[192:195], v[32:35]
	v_mfma_f32_16x16x32_bf16 v[24:27], v[216:219], v[200:203], v[24:27]
	v_mfma_f32_16x16x32_bf16 v[16:19], v[224:227], v[200:203], v[16:19]
	v_mfma_f32_16x16x32_bf16 v[8:11], v[216:219], v[208:211], v[8:11]
	v_mfma_f32_16x16x32_bf16 v[0:3], v[224:227], v[208:211], v[0:3]
	v_mfma_f32_16x16x32_bf16 v[56:59], v[220:223], v[174:177], v[56:59]
	v_mfma_f32_16x16x32_bf16 v[48:51], v[228:231], v[174:177], v[48:51]
	v_mfma_f32_16x16x32_bf16 v[40:43], v[220:223], v[196:199], v[40:43]
	v_mfma_f32_16x16x32_bf16 v[32:35], v[228:231], v[196:199], v[32:35]
	v_mfma_f32_16x16x32_bf16 v[24:27], v[220:223], v[204:207], v[24:27]
	v_mfma_f32_16x16x32_bf16 v[16:19], v[228:231], v[204:207], v[16:19]
	v_mfma_f32_16x16x32_bf16 v[8:11], v[220:223], v[212:215], v[8:11]
	v_mfma_f32_16x16x32_bf16 v[0:3], v[228:231], v[212:215], v[0:3]
	s_setprio 0
	s_add_i32 s75, s75, 2
	s_add_u32 s8, s8, 0x100
	s_addc_u32 s9, s9, 0
	s_add_u32 s73, s73, 0x100
	s_addc_u32 s74, s74, 0
	s_cmp_gt_u32 s75, 13
	s_barrier
	s_cbranch_scc0 .LBB0_359
	s_lshl_b32 s19, s7, 10
	v_lshl_add_u32 v166, s6, 8, v178
	s_cmp_gt_i32 s36, 2
	s_mov_b64 s[6:7], -1
	s_cbranch_scc0 .LBB0_373
	s_cmp_gt_u32 s36, 8
	s_cbranch_scc1 .LBB0_372
	s_cmp_lt_i32 s36, 4
	s_cbranch_scc1 .LBB0_406
	s_cmp_lg_u32 s36, 4
	s_mov_b64 s[8:9], -1
	s_cbranch_scc0 .LBB0_369
	s_lshl_b32 s6, s36, 9
	s_add_u32 s21, s26, s6
	s_addc_u32 s38, s27, 0
	s_cmp_gt_u32 s36, 6
	s_cbranch_scc0 .LBB0_366
	s_add_u32 s6, s21, 0x13fff200
	s_addc_u32 s7, s38, 0
	s_mov_b64 s[8:9], 0

.LBB0_786:
	ds_read_b128 v[144:147], v151
	ds_read_b128 v[156:159], v151 offset:1024
	ds_read_b128 v[160:163], v151 offset:2048
	ds_read_b128 v[164:167], v151 offset:3072
	s_add_u32 s30, s28, 0xfffc0080
	s_addc_u32 s31, s29, -1
	s_cmp_eq_u32 s61, 12
	s_cselect_b32 s35, s19, s31
	s_cselect_b32 s34, s57, s30
	s_cselect_b32 s31, s17, s60
	s_cselect_b32 s30, s58, s59
	s_add_i32 m0, s45, 0xc000
	ds_read_b128 v[168:171], v152
	ds_read_b128 v[172:175], v152 offset:1024
	ds_read_b128 v[176:179], v152 offset:2048
	ds_read_b128 v[180:183], v152 offset:3072
	ds_read_b128 v[184:187], v152 offset:4096
	ds_read_b128 v[188:191], v152 offset:5120
	ds_read_b128 v[192:195], v152 offset:6144
	ds_read_b128 v[196:199], v152 offset:7168
	global_load_lds_dwordx4 v136, s[28:29]
	s_add_i32 m0, s45, 0xe000
	s_nop 0
	global_load_lds_dwordx4 v138, s[28:29]
	s_waitcnt lgkmcnt(8)
	s_barrier
	s_waitcnt lgkmcnt(0)
	s_setprio 1
	s_waitcnt lgkmcnt(0)
	v_mfma_f32_16x16x32_bf16 v[124:127], v[144:147], v[168:171], v[124:127]
	v_mfma_f32_16x16x32_bf16 v[120:123], v[160:163], v[168:171], v[120:123]
	v_mfma_f32_16x16x32_bf16 v[108:111], v[144:147], v[176:179], v[108:111]
	v_mfma_f32_16x16x32_bf16 v[104:107], v[160:163], v[176:179], v[104:107]
	v_mfma_f32_16x16x32_bf16 v[92:95], v[144:147], v[184:187], v[92:95]
	v_mfma_f32_16x16x32_bf16 v[88:91], v[160:163], v[184:187], v[88:91]
	v_mfma_f32_16x16x32_bf16 v[76:79], v[144:147], v[192:195], v[76:79]
	v_mfma_f32_16x16x32_bf16 v[72:75], v[160:163], v[192:195], v[72:75]
	v_mfma_f32_16x16x32_bf16 v[124:127], v[156:159], v[172:175], v[124:127]
	v_mfma_f32_16x16x32_bf16 v[120:123], v[164:167], v[172:175], v[120:123]
	v_mfma_f32_16x16x32_bf16 v[108:111], v[156:159], v[180:183], v[108:111]
	v_mfma_f32_16x16x32_bf16 v[104:107], v[164:167], v[180:183], v[104:107]
	v_mfma_f32_16x16x32_bf16 v[92:95], v[156:159], v[188:191], v[92:95]
	v_mfma_f32_16x16x32_bf16 v[88:91], v[164:167], v[188:191], v[88:91]
	v_mfma_f32_16x16x32_bf16 v[76:79], v[156:159], v[196:199], v[76:79]
	v_mfma_f32_16x16x32_bf16 v[72:75], v[164:167], v[196:199], v[72:75]
	s_setprio 0
	s_barrier
	s_add_i32 s62, s53, s42
	s_add_u32 s80, s30, 0x80
	s_addc_u32 s81, s31, 0
	s_mov_b32 m0, s62
	ds_read_b128 v[200:203], v153
	ds_read_b128 v[204:207], v153 offset:1024
	ds_read_b128 v[208:211], v153 offset:2048
	ds_read_b128 v[212:215], v153 offset:3072
	global_load_lds_dwordx4 v132, s[30:31]
	s_add_i32 m0, s62, 0x2000
	s_nop 0
	global_load_lds_dwordx4 v128, s[30:31]
	s_barrier
	s_waitcnt lgkmcnt(0)
	s_setprio 1
	s_waitcnt lgkmcnt(0)
	v_mfma_f32_16x16x32_bf16 v[116:119], v[200:203], v[168:171], v[116:119]
	v_mfma_f32_16x16x32_bf16 v[112:115], v[208:211], v[168:171], v[112:115]
	v_mfma_f32_16x16x32_bf16 v[100:103], v[200:203], v[176:179], v[100:103]
	v_mfma_f32_16x16x32_bf16 v[96:99], v[208:211], v[176:179], v[96:99]
	v_mfma_f32_16x16x32_bf16 v[84:87], v[200:203], v[184:187], v[84:87]
	v_mfma_f32_16x16x32_bf16 v[80:83], v[208:211], v[184:187], v[80:83]
	v_mfma_f32_16x16x32_bf16 v[68:71], v[200:203], v[192:195], v[68:71]
	v_mfma_f32_16x16x32_bf16 v[64:67], v[208:211], v[192:195], v[64:67]
	v_mfma_f32_16x16x32_bf16 v[116:119], v[204:207], v[172:175], v[116:119]
	v_mfma_f32_16x16x32_bf16 v[112:115], v[212:215], v[172:175], v[112:115]
	v_mfma_f32_16x16x32_bf16 v[100:103], v[204:207], v[180:183], v[100:103]
	v_mfma_f32_16x16x32_bf16 v[96:99], v[212:215], v[180:183], v[96:99]
	v_mfma_f32_16x16x32_bf16 v[84:87], v[204:207], v[188:191], v[84:87]
	v_mfma_f32_16x16x32_bf16 v[80:83], v[212:215], v[188:191], v[80:83]
	v_mfma_f32_16x16x32_bf16 v[68:71], v[204:207], v[196:199], v[68:71]
	v_mfma_f32_16x16x32_bf16 v[64:67], v[212:215], v[196:199], v[64:67]
	s_setprio 0
	s_mov_b32 m0, s45
	s_add_u32 s82, s34, 0x80
	s_addc_u32 s83, s35, 0
	s_barrier
	ds_read_b128 v[168:171], v152 offset:16384
	ds_read_b128 v[172:175], v152 offset:17408
	ds_read_b128 v[176:179], v152 offset:18432
	ds_read_b128 v[180:183], v152 offset:19456
	ds_read_b128 v[184:187], v152 offset:20480
	ds_read_b128 v[188:191], v152 offset:21504
	ds_read_b128 v[192:195], v152 offset:22528
	ds_read_b128 v[196:199], v152 offset:23552
	global_load_lds_dwordx4 v134, s[34:35]
	s_mov_b32 m0, s46
	s_nop 0
	global_load_lds_dwordx4 v130, s[34:35]
	s_barrier
	s_waitcnt lgkmcnt(0)
	s_setprio 1
	s_waitcnt lgkmcnt(0)
	v_mfma_f32_16x16x32_bf16 v[60:63], v[144:147], v[168:171], v[60:63]
	v_mfma_f32_16x16x32_bf16 v[56:59], v[160:163], v[168:171], v[56:59]
	v_mfma_f32_16x16x32_bf16 v[44:47], v[144:147], v[176:179], v[44:47]
	v_mfma_f32_16x16x32_bf16 v[40:43], v[160:163], v[176:179], v[40:43]
	v_mfma_f32_16x16x32_bf16 v[28:31], v[144:147], v[184:187], v[28:31]
	v_mfma_f32_16x16x32_bf16 v[24:27], v[160:163], v[184:187], v[24:27]
	v_mfma_f32_16x16x32_bf16 v[12:15], v[144:147], v[192:195], v[12:15]
	v_mfma_f32_16x16x32_bf16 v[8:11], v[160:163], v[192:195], v[8:11]
	v_mfma_f32_16x16x32_bf16 v[60:63], v[156:159], v[172:175], v[60:63]
	v_mfma_f32_16x16x32_bf16 v[56:59], v[164:167], v[172:175], v[56:59]
	v_mfma_f32_16x16x32_bf16 v[44:47], v[156:159], v[180:183], v[44:47]
	v_mfma_f32_16x16x32_bf16 v[40:43], v[164:167], v[180:183], v[40:43]
	v_mfma_f32_16x16x32_bf16 v[28:31], v[156:159], v[188:191], v[28:31]
	v_mfma_f32_16x16x32_bf16 v[24:27], v[164:167], v[188:191], v[24:27]
	v_mfma_f32_16x16x32_bf16 v[12:15], v[156:159], v[196:199], v[12:15]
	v_mfma_f32_16x16x32_bf16 v[8:11], v[164:167], v[196:199], v[8:11]
	s_setprio 0
	s_barrier
	s_add_u32 s62, s30, 0x40000
	s_addc_u32 s63, s31, 0
	s_add_i32 s64, s54, s42
	s_mov_b32 m0, s64
	s_nop 0
	global_load_lds_dwordx4 v132, s[62:63]
	s_add_i32 m0, s64, 0x2000
	s_nop 0
	global_load_lds_dwordx4 v128, s[62:63]
	s_waitcnt vmcnt(6)
	s_barrier
	s_setprio 1
	v_mfma_f32_16x16x32_bf16 v[52:55], v[200:203], v[168:171], v[52:55]
	v_mfma_f32_16x16x32_bf16 v[48:51], v[208:211], v[168:171], v[48:51]
	v_mfma_f32_16x16x32_bf16 v[36:39], v[200:203], v[176:179], v[36:39]
	v_mfma_f32_16x16x32_bf16 v[32:35], v[208:211], v[176:179], v[32:35]
	v_mfma_f32_16x16x32_bf16 v[20:23], v[200:203], v[184:187], v[20:23]
	v_mfma_f32_16x16x32_bf16 v[16:19], v[208:211], v[184:187], v[16:19]
	v_mfma_f32_16x16x32_bf16 v[4:7], v[200:203], v[192:195], v[4:7]
	v_mfma_f32_16x16x32_bf16 v[0:3], v[208:211], v[192:195], v[0:3]
	v_mfma_f32_16x16x32_bf16 v[52:55], v[204:207], v[172:175], v[52:55]
	v_mfma_f32_16x16x32_bf16 v[48:51], v[212:215], v[172:175], v[48:51]
	v_mfma_f32_16x16x32_bf16 v[36:39], v[204:207], v[180:183], v[36:39]
	v_mfma_f32_16x16x32_bf16 v[32:35], v[212:215], v[180:183], v[32:35]
	v_mfma_f32_16x16x32_bf16 v[20:23], v[204:207], v[188:191], v[20:23]
	v_mfma_f32_16x16x32_bf16 v[16:19], v[212:215], v[188:191], v[16:19]
	v_mfma_f32_16x16x32_bf16 v[4:7], v[204:207], v[196:199], v[4:7]
	v_mfma_f32_16x16x32_bf16 v[0:3], v[212:215], v[196:199], v[0:3]
	s_setprio 0
	s_add_i32 s62, 0, 0x18000
	v_add_u32_e32 v155, s62, v149
	s_barrier
	ds_read_b128 v[144:147], v155
	ds_read_b128 v[156:159], v155 offset:1024
	ds_read_b128 v[160:163], v155 offset:2048
	ds_read_b128 v[164:167], v155 offset:3072
	s_add_u32 s34, s34, 0x40000
	s_addc_u32 s35, s35, 0
	s_mov_b32 m0, s47
	ds_read_b128 v[168:171], v152 offset:32768
	ds_read_b128 v[172:175], v152 offset:33792
	ds_read_b128 v[176:179], v152 offset:34816
	ds_read_b128 v[180:183], v152 offset:35840
	ds_read_b128 v[184:187], v152 offset:36864
	ds_read_b128 v[188:191], v152 offset:37888
	ds_read_b128 v[192:195], v152 offset:38912
	ds_read_b128 v[196:199], v152 offset:39936
	global_load_lds_dwordx4 v134, s[34:35]
	s_mov_b32 m0, s48
	s_nop 0
	global_load_lds_dwordx4 v130, s[34:35]
	s_waitcnt lgkmcnt(8)
	s_barrier
	s_waitcnt lgkmcnt(0)
	s_setprio 1
	s_waitcnt lgkmcnt(0)
	v_mfma_f32_16x16x32_bf16 v[124:127], v[144:147], v[168:171], v[124:127]
	v_mfma_f32_16x16x32_bf16 v[120:123], v[160:163], v[168:171], v[120:123]
	v_mfma_f32_16x16x32_bf16 v[108:111], v[144:147], v[176:179], v[108:111]
	v_mfma_f32_16x16x32_bf16 v[104:107], v[160:163], v[176:179], v[104:107]
	v_mfma_f32_16x16x32_bf16 v[92:95], v[144:147], v[184:187], v[92:95]
	v_mfma_f32_16x16x32_bf16 v[88:91], v[160:163], v[184:187], v[88:91]
	v_mfma_f32_16x16x32_bf16 v[76:79], v[144:147], v[192:195], v[76:79]
	v_mfma_f32_16x16x32_bf16 v[72:75], v[160:163], v[192:195], v[72:75]
	v_mfma_f32_16x16x32_bf16 v[124:127], v[156:159], v[172:175], v[124:127]
	v_mfma_f32_16x16x32_bf16 v[120:123], v[164:167], v[172:175], v[120:123]
	v_mfma_f32_16x16x32_bf16 v[108:111], v[156:159], v[180:183], v[108:111]
	v_mfma_f32_16x16x32_bf16 v[104:107], v[164:167], v[180:183], v[104:107]
	v_mfma_f32_16x16x32_bf16 v[92:95], v[156:159], v[188:191], v[92:95]
	v_mfma_f32_16x16x32_bf16 v[88:91], v[164:167], v[188:191], v[88:91]
	v_mfma_f32_16x16x32_bf16 v[76:79], v[156:159], v[196:199], v[76:79]
	v_mfma_f32_16x16x32_bf16 v[72:75], v[164:167], v[196:199], v[72:75]
	s_setprio 0
	s_barrier
	s_add_i32 s34, 0, 0x1c000
	s_add_i32 s35, s62, s42
	v_add_u32_e32 v155, s34, v149
	s_mov_b32 m0, s35
	ds_read_b128 v[200:203], v155
	ds_read_b128 v[204:207], v155 offset:1024
	ds_read_b128 v[208:211], v155 offset:2048
	ds_read_b128 v[212:215], v155 offset:3072
	global_load_lds_dwordx4 v132, s[80:81]
	s_add_i32 m0, s35, 0x2000
	s_nop 0
	global_load_lds_dwordx4 v128, s[80:81]
	s_barrier
	s_waitcnt lgkmcnt(0)
	s_setprio 1
	s_waitcnt lgkmcnt(0)
	v_mfma_f32_16x16x32_bf16 v[116:119], v[200:203], v[168:171], v[116:119]
	v_mfma_f32_16x16x32_bf16 v[112:115], v[208:211], v[168:171], v[112:115]
	v_mfma_f32_16x16x32_bf16 v[100:103], v[200:203], v[176:179], v[100:103]
	v_mfma_f32_16x16x32_bf16 v[96:99], v[208:211], v[176:179], v[96:99]
	v_mfma_f32_16x16x32_bf16 v[84:87], v[200:203], v[184:187], v[84:87]
	v_mfma_f32_16x16x32_bf16 v[80:83], v[208:211], v[184:187], v[80:83]
	v_mfma_f32_16x16x32_bf16 v[68:71], v[200:203], v[192:195], v[68:71]
	v_mfma_f32_16x16x32_bf16 v[64:67], v[208:211], v[192:195], v[64:67]
	v_mfma_f32_16x16x32_bf16 v[116:119], v[204:207], v[172:175], v[116:119]
	v_mfma_f32_16x16x32_bf16 v[112:115], v[212:215], v[172:175], v[112:115]
	v_mfma_f32_16x16x32_bf16 v[100:103], v[204:207], v[180:183], v[100:103]
	v_mfma_f32_16x16x32_bf16 v[96:99], v[212:215], v[180:183], v[96:99]
	v_mfma_f32_16x16x32_bf16 v[84:87], v[204:207], v[188:191], v[84:87]
	v_mfma_f32_16x16x32_bf16 v[80:83], v[212:215], v[188:191], v[80:83]
	v_mfma_f32_16x16x32_bf16 v[68:71], v[204:207], v[196:199], v[68:71]
	v_mfma_f32_16x16x32_bf16 v[64:67], v[212:215], v[196:199], v[64:67]
	s_setprio 0
	s_mov_b32 m0, s50
	s_barrier
	ds_read_b128 v[168:171], v152 offset:49152
	ds_read_b128 v[172:175], v152 offset:50176
	ds_read_b128 v[176:179], v152 offset:51200
	ds_read_b128 v[180:183], v152 offset:52224
	ds_read_b128 v[184:187], v152 offset:53248
	ds_read_b128 v[188:191], v152 offset:54272
	ds_read_b128 v[192:195], v152 offset:55296
	ds_read_b128 v[196:199], v152 offset:56320
	global_load_lds_dwordx4 v134, s[82:83]
	s_mov_b32 m0, s51
	s_nop 0
	global_load_lds_dwordx4 v130, s[82:83]
	s_barrier
	s_waitcnt lgkmcnt(0)
	s_setprio 1
	s_waitcnt lgkmcnt(0)
	v_mfma_f32_16x16x32_bf16 v[60:63], v[144:147], v[168:171], v[60:63]
	v_mfma_f32_16x16x32_bf16 v[56:59], v[160:163], v[168:171], v[56:59]
	v_mfma_f32_16x16x32_bf16 v[44:47], v[144:147], v[176:179], v[44:47]
	v_mfma_f32_16x16x32_bf16 v[40:43], v[160:163], v[176:179], v[40:43]
	v_mfma_f32_16x16x32_bf16 v[28:31], v[144:147], v[184:187], v[28:31]
	v_mfma_f32_16x16x32_bf16 v[24:27], v[160:163], v[184:187], v[24:27]
	v_mfma_f32_16x16x32_bf16 v[12:15], v[144:147], v[192:195], v[12:15]
	v_mfma_f32_16x16x32_bf16 v[8:11], v[160:163], v[192:195], v[8:11]
	v_mfma_f32_16x16x32_bf16 v[60:63], v[156:159], v[172:175], v[60:63]
	v_mfma_f32_16x16x32_bf16 v[56:59], v[164:167], v[172:175], v[56:59]
	v_mfma_f32_16x16x32_bf16 v[44:47], v[156:159], v[180:183], v[44:47]
	v_mfma_f32_16x16x32_bf16 v[40:43], v[164:167], v[180:183], v[40:43]
	v_mfma_f32_16x16x32_bf16 v[28:31], v[156:159], v[188:191], v[28:31]
	v_mfma_f32_16x16x32_bf16 v[24:27], v[164:167], v[188:191], v[24:27]
	v_mfma_f32_16x16x32_bf16 v[12:15], v[156:159], v[196:199], v[12:15]
	v_mfma_f32_16x16x32_bf16 v[8:11], v[164:167], v[196:199], v[8:11]
	s_setprio 0
	s_barrier
	s_add_u32 s30, s30, 0x40080
	s_addc_u32 s31, s31, 0
	s_add_i32 s34, s34, s42
	s_mov_b32 m0, s34
	s_nop 0
	global_load_lds_dwordx4 v132, s[30:31]
	s_add_i32 m0, s34, 0x2000
	s_nop 0
	global_load_lds_dwordx4 v128, s[30:31]
	s_waitcnt vmcnt(6)
	s_barrier
	s_setprio 1
	v_mfma_f32_16x16x32_bf16 v[52:55], v[200:203], v[168:171], v[52:55]
	v_mfma_f32_16x16x32_bf16 v[48:51], v[208:211], v[168:171], v[48:51]
	v_mfma_f32_16x16x32_bf16 v[36:39], v[200:203], v[176:179], v[36:39]
	v_mfma_f32_16x16x32_bf16 v[32:35], v[208:211], v[176:179], v[32:35]
	v_mfma_f32_16x16x32_bf16 v[20:23], v[200:203], v[184:187], v[20:23]
	v_mfma_f32_16x16x32_bf16 v[16:19], v[208:211], v[184:187], v[16:19]
	v_mfma_f32_16x16x32_bf16 v[4:7], v[200:203], v[192:195], v[4:7]
	v_mfma_f32_16x16x32_bf16 v[0:3], v[208:211], v[192:195], v[0:3]
	v_mfma_f32_16x16x32_bf16 v[52:55], v[204:207], v[172:175], v[52:55]
	v_mfma_f32_16x16x32_bf16 v[48:51], v[212:215], v[172:175], v[48:51]
	v_mfma_f32_16x16x32_bf16 v[36:39], v[204:207], v[180:183], v[36:39]
	v_mfma_f32_16x16x32_bf16 v[32:35], v[212:215], v[180:183], v[32:35]
	v_mfma_f32_16x16x32_bf16 v[20:23], v[204:207], v[188:191], v[20:23]
	v_mfma_f32_16x16x32_bf16 v[16:19], v[212:215], v[188:191], v[16:19]
	v_mfma_f32_16x16x32_bf16 v[4:7], v[204:207], v[196:199], v[4:7]
	v_mfma_f32_16x16x32_bf16 v[0:3], v[212:215], v[196:199], v[0:3]
	s_setprio 0
	s_add_i32 s61, s61, 2
	s_add_u32 s28, s28, 0x100
	s_addc_u32 s29, s29, 0
	s_add_u32 s59, s59, 0x100
	s_addc_u32 s60, s60, 0
	s_cmp_gt_u32 s61, 13
	s_barrier
	s_cbranch_scc0 .LBB0_786
	v_lshl_add_u32 v146, s8, 8, v148
	v_ashrrev_i32_e32 v147, 31, v146
	v_lshl_or_b32 v144, s56, 8, v150
	v_lshlrev_b64 v[156:157], 11, v[146:147]
	v_ashrrev_i32_e32 v145, 31, v144
	v_lshl_add_u64 v[156:157], s[10:11], 0, v[156:157]
	v_lshl_add_u64 v[166:167], v[144:145], 1, v[156:157]
	global_load_dwordx4 v[158:161], v[166:167], off
	global_load_dwordx4 v[162:165], v[166:167], off offset:256
	v_and_b32_e32 v156, 64, v154
	v_xor_b32_e32 v155, 16, v154
	v_add_u32_e32 v156, 64, v156
	v_xor_b32_e32 v157, 32, v154
	v_cmp_lt_i32_e32 vcc, v155, v156
	s_lshl_b32 s28, s56, 2
	s_ashr_i32 s29, s28, 31
	v_cndmask_b32_e32 v155, v154, v155, vcc
	v_cmp_lt_i32_e32 vcc, v157, v156
	v_lshlrev_b32_e32 v156, 2, v155
	s_waitcnt vmcnt(0)
	v_lshlrev_b32_e32 v168, 16, v158
	v_and_b32_e32 v169, 0xffff0000, v158
	v_lshlrev_b32_e32 v158, 16, v159
	v_and_b32_e32 v159, 0xffff0000, v159
	v_lshlrev_b32_e32 v172, 16, v162
	v_and_b32_e32 v173, 0xffff0000, v162
	v_lshlrev_b32_e32 v162, 16, v163
	v_and_b32_e32 v163, 0xffff0000, v163
	v_cndmask_b32_e32 v157, v154, v157, vcc
	v_lshlrev_b32_e32 v170, 16, v160
	v_and_b32_e32 v171, 0xffff0000, v160
	v_lshlrev_b32_e32 v160, 16, v161
	v_and_b32_e32 v161, 0xffff0000, v161
	v_lshlrev_b32_e32 v174, 16, v164
	v_and_b32_e32 v175, 0xffff0000, v164
	v_lshlrev_b32_e32 v164, 16, v165
	v_and_b32_e32 v165, 0xffff0000, v165
	v_pk_add_f32 v[126:127], v[126:127], v[158:159]
	v_pk_add_f32 v[124:125], v[124:125], v[168:169]
	v_pk_add_f32 v[118:119], v[118:119], v[162:163]
	v_pk_add_f32 v[116:117], v[116:117], v[172:173]
	v_lshlrev_b32_e32 v155, 2, v157
	v_pk_add_f32 v[122:123], v[122:123], v[160:161]
	v_pk_add_f32 v[120:121], v[120:121], v[170:171]
	v_pk_add_f32 v[158:159], v[114:115], v[164:165]
	v_pk_add_f32 v[160:161], v[112:113], v[174:175]
	v_mul_f32_e32 v114, v125, v125
	v_mul_f32_e32 v115, v127, v127
	v_mul_f32_e32 v157, v117, v117
	v_mul_f32_e32 v162, v119, v119
	v_cvt_pk_bf16_f32 v112, v124, v125
	v_mul_f32_e32 v125, v121, v121
	v_mul_f32_e32 v163, v161, v161
	v_fmac_f32_e32 v114, v124, v124
	v_fmac_f32_e32 v115, v126, v126
	v_fmac_f32_e32 v157, v116, v116
	v_fmac_f32_e32 v162, v118, v118
	v_cvt_pk_bf16_f32 v113, v126, v127
	v_mul_f32_e32 v127, v123, v123
	v_mul_f32_e32 v164, v159, v159
	v_fmac_f32_e32 v125, v120, v120
	v_fmac_f32_e32 v163, v160, v160
	v_add_f32_e32 v114, v114, v115
	v_add_f32_e32 v115, v157, v162
	v_fmac_f32_e32 v127, v122, v122
	v_fmac_f32_e32 v164, v158, v158
	v_add_f32_e32 v114, v125, v114
	v_add_f32_e32 v115, v163, v115
	v_add_f32_e32 v114, v127, v114
	v_add_f32_e32 v115, v164, v115
	v_add_f32_e32 v124, v114, v115
	ds_bpermute_b32 v125, v156, v124
	v_cvt_pk_bf16_f32 v114, v120, v121
	v_cvt_pk_bf16_f32 v115, v122, v123
	global_store_dwordx4 v[166:167], v[112:115], off
	s_waitcnt lgkmcnt(0)
	s_nop 0
	v_add_f32_e32 v112, v124, v125
	ds_bpermute_b32 v113, v155, v112
	v_cvt_pk_bf16_f32 v114, v116, v117
	v_cvt_pk_bf16_f32 v115, v118, v119
	v_cvt_pk_bf16_f32 v116, v160, v161
	v_cvt_pk_bf16_f32 v117, v158, v159
	global_store_dwordx4 v[166:167], v[114:117], off offset:256
	s_and_saveexec_b64 s[30:31], s[4:5]
	s_cbranch_execz .LBB0_789
	v_lshlrev_b64 v[114:115], 6, v[146:147]
	v_lshl_add_u64 v[114:115], s[12:13], 0, v[114:115]
	v_lshl_add_u64 v[114:115], s[28:29], 2, v[114:115]
	s_lshl_b32 s8, s49, 2
	v_lshl_add_u64 v[114:115], v[114:115], 0, s[8:9]
	s_waitcnt lgkmcnt(0)
	v_add_f32_e32 v112, v112, v113
	global_store_dword v[114:115], v112, off

.LBB0_893:
	ds_read_b128 v[152:155], v148
	ds_read_b128 v[156:159], v148 offset:1024
	ds_read_b128 v[160:163], v148 offset:2048
	ds_read_b128 v[164:167], v148 offset:3072
	s_add_u32 s26, s20, 0xfffc0080
	s_addc_u32 s27, s21, -1
	s_cmp_eq_u32 s57, 12
	s_cselect_b32 s29, s13, s27
	s_cselect_b32 s28, s53, s26
	s_cselect_b32 s27, s11, s56
	s_cselect_b32 s26, s54, s55
	s_add_i32 m0, s19, 0xc000
	ds_read_b128 v[168:171], v149
	ds_read_b128 v[172:175], v149 offset:1024
	ds_read_b128 v[176:179], v149 offset:2048
	ds_read_b128 v[180:183], v149 offset:3072
	ds_read_b128 v[184:187], v149 offset:4096
	ds_read_b128 v[188:191], v149 offset:5120
	ds_read_b128 v[192:195], v149 offset:6144
	ds_read_b128 v[196:199], v149 offset:7168
	global_load_lds_dwordx4 v136, s[20:21]
	s_add_i32 m0, s19, 0xe000
	s_nop 0
	global_load_lds_dwordx4 v138, s[20:21]
	s_waitcnt lgkmcnt(8)
	s_barrier
	s_waitcnt lgkmcnt(0)
	s_setprio 1
	s_waitcnt lgkmcnt(0)
	v_mfma_f32_16x16x32_bf16 v[124:127], v[152:155], v[168:171], v[124:127]
	v_mfma_f32_16x16x32_bf16 v[120:123], v[160:163], v[168:171], v[120:123]
	v_mfma_f32_16x16x32_bf16 v[108:111], v[152:155], v[176:179], v[108:111]
	v_mfma_f32_16x16x32_bf16 v[104:107], v[160:163], v[176:179], v[104:107]
	v_mfma_f32_16x16x32_bf16 v[92:95], v[152:155], v[184:187], v[92:95]
	v_mfma_f32_16x16x32_bf16 v[88:91], v[160:163], v[184:187], v[88:91]
	v_mfma_f32_16x16x32_bf16 v[76:79], v[152:155], v[192:195], v[76:79]
	v_mfma_f32_16x16x32_bf16 v[72:75], v[160:163], v[192:195], v[72:75]
	v_mfma_f32_16x16x32_bf16 v[124:127], v[156:159], v[172:175], v[124:127]
	v_mfma_f32_16x16x32_bf16 v[120:123], v[164:167], v[172:175], v[120:123]
	v_mfma_f32_16x16x32_bf16 v[108:111], v[156:159], v[180:183], v[108:111]
	v_mfma_f32_16x16x32_bf16 v[104:107], v[164:167], v[180:183], v[104:107]
	v_mfma_f32_16x16x32_bf16 v[92:95], v[156:159], v[188:191], v[92:95]
	v_mfma_f32_16x16x32_bf16 v[88:91], v[164:167], v[188:191], v[88:91]
	v_mfma_f32_16x16x32_bf16 v[76:79], v[156:159], v[196:199], v[76:79]
	v_mfma_f32_16x16x32_bf16 v[72:75], v[164:167], v[196:199], v[72:75]
	s_setprio 0
	s_barrier
	s_add_i32 s58, s47, s31
	s_add_u32 s80, s26, 0x80
	s_addc_u32 s81, s27, 0
	s_mov_b32 m0, s58
	ds_read_b128 v[200:203], v150
	ds_read_b128 v[204:207], v150 offset:1024
	ds_read_b128 v[208:211], v150 offset:2048
	ds_read_b128 v[212:215], v150 offset:3072
	global_load_lds_dwordx4 v132, s[26:27]
	s_add_i32 m0, s58, 0x2000
	s_nop 0
	global_load_lds_dwordx4 v128, s[26:27]
	s_barrier
	s_waitcnt lgkmcnt(0)
	s_setprio 1
	s_waitcnt lgkmcnt(0)
	v_mfma_f32_16x16x32_bf16 v[116:119], v[200:203], v[168:171], v[116:119]
	v_mfma_f32_16x16x32_bf16 v[112:115], v[208:211], v[168:171], v[112:115]
	v_mfma_f32_16x16x32_bf16 v[100:103], v[200:203], v[176:179], v[100:103]
	v_mfma_f32_16x16x32_bf16 v[96:99], v[208:211], v[176:179], v[96:99]
	v_mfma_f32_16x16x32_bf16 v[84:87], v[200:203], v[184:187], v[84:87]
	v_mfma_f32_16x16x32_bf16 v[80:83], v[208:211], v[184:187], v[80:83]
	v_mfma_f32_16x16x32_bf16 v[68:71], v[200:203], v[192:195], v[68:71]
	v_mfma_f32_16x16x32_bf16 v[64:67], v[208:211], v[192:195], v[64:67]
	v_mfma_f32_16x16x32_bf16 v[116:119], v[204:207], v[172:175], v[116:119]
	v_mfma_f32_16x16x32_bf16 v[112:115], v[212:215], v[172:175], v[112:115]
	v_mfma_f32_16x16x32_bf16 v[100:103], v[204:207], v[180:183], v[100:103]
	v_mfma_f32_16x16x32_bf16 v[96:99], v[212:215], v[180:183], v[96:99]
	v_mfma_f32_16x16x32_bf16 v[84:87], v[204:207], v[188:191], v[84:87]
	v_mfma_f32_16x16x32_bf16 v[80:83], v[212:215], v[188:191], v[80:83]
	v_mfma_f32_16x16x32_bf16 v[68:71], v[204:207], v[196:199], v[68:71]
	v_mfma_f32_16x16x32_bf16 v[64:67], v[212:215], v[196:199], v[64:67]
	s_setprio 0
	s_mov_b32 m0, s19
	s_add_u32 s82, s28, 0x80
	s_addc_u32 s83, s29, 0
	s_barrier
	ds_read_b128 v[168:171], v149 offset:16384
	ds_read_b128 v[172:175], v149 offset:17408
	ds_read_b128 v[176:179], v149 offset:18432
	ds_read_b128 v[180:183], v149 offset:19456
	ds_read_b128 v[184:187], v149 offset:20480
	ds_read_b128 v[188:191], v149 offset:21504
	ds_read_b128 v[192:195], v149 offset:22528
	ds_read_b128 v[196:199], v149 offset:23552
	global_load_lds_dwordx4 v134, s[28:29]
	s_mov_b32 m0, s42
	s_nop 0
	global_load_lds_dwordx4 v130, s[28:29]
	s_barrier
	s_waitcnt lgkmcnt(0)
	s_setprio 1
	s_waitcnt lgkmcnt(0)
	v_mfma_f32_16x16x32_bf16 v[60:63], v[152:155], v[168:171], v[60:63]
	v_mfma_f32_16x16x32_bf16 v[56:59], v[160:163], v[168:171], v[56:59]
	v_mfma_f32_16x16x32_bf16 v[44:47], v[152:155], v[176:179], v[44:47]
	v_mfma_f32_16x16x32_bf16 v[40:43], v[160:163], v[176:179], v[40:43]
	v_mfma_f32_16x16x32_bf16 v[28:31], v[152:155], v[184:187], v[28:31]
	v_mfma_f32_16x16x32_bf16 v[24:27], v[160:163], v[184:187], v[24:27]
	v_mfma_f32_16x16x32_bf16 v[12:15], v[152:155], v[192:195], v[12:15]
	v_mfma_f32_16x16x32_bf16 v[8:11], v[160:163], v[192:195], v[8:11]
	v_mfma_f32_16x16x32_bf16 v[60:63], v[156:159], v[172:175], v[60:63]
	v_mfma_f32_16x16x32_bf16 v[56:59], v[164:167], v[172:175], v[56:59]
	v_mfma_f32_16x16x32_bf16 v[44:47], v[156:159], v[180:183], v[44:47]
	v_mfma_f32_16x16x32_bf16 v[40:43], v[164:167], v[180:183], v[40:43]
	v_mfma_f32_16x16x32_bf16 v[28:31], v[156:159], v[188:191], v[28:31]
	v_mfma_f32_16x16x32_bf16 v[24:27], v[164:167], v[188:191], v[24:27]
	v_mfma_f32_16x16x32_bf16 v[12:15], v[156:159], v[196:199], v[12:15]
	v_mfma_f32_16x16x32_bf16 v[8:11], v[164:167], v[196:199], v[8:11]
	s_setprio 0
	s_barrier
	s_add_u32 s58, s26, 0x40000
	s_addc_u32 s59, s27, 0
	s_add_i32 s60, s48, s31
	s_mov_b32 m0, s60
	s_nop 0
	global_load_lds_dwordx4 v132, s[58:59]
	s_add_i32 m0, s60, 0x2000
	s_nop 0
	global_load_lds_dwordx4 v128, s[58:59]
	s_waitcnt vmcnt(6)
	s_barrier
	s_setprio 1
	v_mfma_f32_16x16x32_bf16 v[52:55], v[200:203], v[168:171], v[52:55]
	v_mfma_f32_16x16x32_bf16 v[48:51], v[208:211], v[168:171], v[48:51]
	v_mfma_f32_16x16x32_bf16 v[36:39], v[200:203], v[176:179], v[36:39]
	v_mfma_f32_16x16x32_bf16 v[32:35], v[208:211], v[176:179], v[32:35]
	v_mfma_f32_16x16x32_bf16 v[20:23], v[200:203], v[184:187], v[20:23]
	v_mfma_f32_16x16x32_bf16 v[16:19], v[208:211], v[184:187], v[16:19]
	v_mfma_f32_16x16x32_bf16 v[4:7], v[200:203], v[192:195], v[4:7]
	v_mfma_f32_16x16x32_bf16 v[0:3], v[208:211], v[192:195], v[0:3]
	v_mfma_f32_16x16x32_bf16 v[52:55], v[204:207], v[172:175], v[52:55]
	v_mfma_f32_16x16x32_bf16 v[48:51], v[212:215], v[172:175], v[48:51]
	v_mfma_f32_16x16x32_bf16 v[36:39], v[204:207], v[180:183], v[36:39]
	v_mfma_f32_16x16x32_bf16 v[32:35], v[212:215], v[180:183], v[32:35]
	v_mfma_f32_16x16x32_bf16 v[20:23], v[204:207], v[188:191], v[20:23]
	v_mfma_f32_16x16x32_bf16 v[16:19], v[212:215], v[188:191], v[16:19]
	v_mfma_f32_16x16x32_bf16 v[4:7], v[204:207], v[196:199], v[4:7]
	v_mfma_f32_16x16x32_bf16 v[0:3], v[212:215], v[196:199], v[0:3]
	s_setprio 0
	s_add_i32 s58, 0, 0x18000
	v_add_u32_e32 v151, s58, v145
	s_barrier
	ds_read_b128 v[152:155], v151
	ds_read_b128 v[156:159], v151 offset:1024
	ds_read_b128 v[160:163], v151 offset:2048
	ds_read_b128 v[164:167], v151 offset:3072
	s_add_u32 s28, s28, 0x40000
	s_addc_u32 s29, s29, 0
	s_mov_b32 m0, s43
	ds_read_b128 v[168:171], v149 offset:32768
	ds_read_b128 v[172:175], v149 offset:33792
	ds_read_b128 v[176:179], v149 offset:34816
	ds_read_b128 v[180:183], v149 offset:35840
	ds_read_b128 v[184:187], v149 offset:36864
	ds_read_b128 v[188:191], v149 offset:37888
	ds_read_b128 v[192:195], v149 offset:38912
	ds_read_b128 v[196:199], v149 offset:39936
	global_load_lds_dwordx4 v134, s[28:29]
	s_mov_b32 m0, s44
	s_nop 0
	global_load_lds_dwordx4 v130, s[28:29]
	s_waitcnt lgkmcnt(8)
	s_barrier
	s_waitcnt lgkmcnt(0)
	s_setprio 1
	s_waitcnt lgkmcnt(0)
	v_mfma_f32_16x16x32_bf16 v[124:127], v[152:155], v[168:171], v[124:127]
	v_mfma_f32_16x16x32_bf16 v[120:123], v[160:163], v[168:171], v[120:123]
	v_mfma_f32_16x16x32_bf16 v[108:111], v[152:155], v[176:179], v[108:111]
	v_mfma_f32_16x16x32_bf16 v[104:107], v[160:163], v[176:179], v[104:107]
	v_mfma_f32_16x16x32_bf16 v[92:95], v[152:155], v[184:187], v[92:95]
	v_mfma_f32_16x16x32_bf16 v[88:91], v[160:163], v[184:187], v[88:91]
	v_mfma_f32_16x16x32_bf16 v[76:79], v[152:155], v[192:195], v[76:79]
	v_mfma_f32_16x16x32_bf16 v[72:75], v[160:163], v[192:195], v[72:75]
	v_mfma_f32_16x16x32_bf16 v[124:127], v[156:159], v[172:175], v[124:127]
	v_mfma_f32_16x16x32_bf16 v[120:123], v[164:167], v[172:175], v[120:123]
	v_mfma_f32_16x16x32_bf16 v[108:111], v[156:159], v[180:183], v[108:111]
	v_mfma_f32_16x16x32_bf16 v[104:107], v[164:167], v[180:183], v[104:107]
	v_mfma_f32_16x16x32_bf16 v[92:95], v[156:159], v[188:191], v[92:95]
	v_mfma_f32_16x16x32_bf16 v[88:91], v[164:167], v[188:191], v[88:91]
	v_mfma_f32_16x16x32_bf16 v[76:79], v[156:159], v[196:199], v[76:79]
	v_mfma_f32_16x16x32_bf16 v[72:75], v[164:167], v[196:199], v[72:75]
	s_setprio 0
	s_barrier
	s_add_i32 s28, 0, 0x1c000
	s_add_i32 s29, s58, s31
	v_add_u32_e32 v151, s28, v145
	s_mov_b32 m0, s29
	ds_read_b128 v[200:203], v151
	ds_read_b128 v[204:207], v151 offset:1024
	ds_read_b128 v[208:211], v151 offset:2048
	ds_read_b128 v[212:215], v151 offset:3072
	global_load_lds_dwordx4 v132, s[80:81]
	s_add_i32 m0, s29, 0x2000
	s_nop 0
	global_load_lds_dwordx4 v128, s[80:81]
	s_barrier
	s_waitcnt lgkmcnt(0)
	s_setprio 1
	s_waitcnt lgkmcnt(0)
	v_mfma_f32_16x16x32_bf16 v[116:119], v[200:203], v[168:171], v[116:119]
	v_mfma_f32_16x16x32_bf16 v[112:115], v[208:211], v[168:171], v[112:115]
	v_mfma_f32_16x16x32_bf16 v[100:103], v[200:203], v[176:179], v[100:103]
	v_mfma_f32_16x16x32_bf16 v[96:99], v[208:211], v[176:179], v[96:99]
	v_mfma_f32_16x16x32_bf16 v[84:87], v[200:203], v[184:187], v[84:87]
	v_mfma_f32_16x16x32_bf16 v[80:83], v[208:211], v[184:187], v[80:83]
	v_mfma_f32_16x16x32_bf16 v[68:71], v[200:203], v[192:195], v[68:71]
	v_mfma_f32_16x16x32_bf16 v[64:67], v[208:211], v[192:195], v[64:67]
	v_mfma_f32_16x16x32_bf16 v[116:119], v[204:207], v[172:175], v[116:119]
	v_mfma_f32_16x16x32_bf16 v[112:115], v[212:215], v[172:175], v[112:115]
	v_mfma_f32_16x16x32_bf16 v[100:103], v[204:207], v[180:183], v[100:103]
	v_mfma_f32_16x16x32_bf16 v[96:99], v[212:215], v[180:183], v[96:99]
	v_mfma_f32_16x16x32_bf16 v[84:87], v[204:207], v[188:191], v[84:87]
	v_mfma_f32_16x16x32_bf16 v[80:83], v[212:215], v[188:191], v[80:83]
	v_mfma_f32_16x16x32_bf16 v[68:71], v[204:207], v[196:199], v[68:71]
	v_mfma_f32_16x16x32_bf16 v[64:67], v[212:215], v[196:199], v[64:67]
	s_setprio 0
	s_mov_b32 m0, s45
	s_barrier
	ds_read_b128 v[168:171], v149 offset:49152
	ds_read_b128 v[172:175], v149 offset:50176
	ds_read_b128 v[176:179], v149 offset:51200
	ds_read_b128 v[180:183], v149 offset:52224
	ds_read_b128 v[184:187], v149 offset:53248
	ds_read_b128 v[188:191], v149 offset:54272
	ds_read_b128 v[192:195], v149 offset:55296
	ds_read_b128 v[196:199], v149 offset:56320
	global_load_lds_dwordx4 v134, s[82:83]
	s_mov_b32 m0, s46
	s_nop 0
	global_load_lds_dwordx4 v130, s[82:83]
	s_barrier
	s_waitcnt lgkmcnt(0)
	s_setprio 1
	s_waitcnt lgkmcnt(0)
	v_mfma_f32_16x16x32_bf16 v[60:63], v[152:155], v[168:171], v[60:63]
	v_mfma_f32_16x16x32_bf16 v[56:59], v[160:163], v[168:171], v[56:59]
	v_mfma_f32_16x16x32_bf16 v[44:47], v[152:155], v[176:179], v[44:47]
	v_mfma_f32_16x16x32_bf16 v[40:43], v[160:163], v[176:179], v[40:43]
	v_mfma_f32_16x16x32_bf16 v[28:31], v[152:155], v[184:187], v[28:31]
	v_mfma_f32_16x16x32_bf16 v[24:27], v[160:163], v[184:187], v[24:27]
	v_mfma_f32_16x16x32_bf16 v[12:15], v[152:155], v[192:195], v[12:15]
	v_mfma_f32_16x16x32_bf16 v[8:11], v[160:163], v[192:195], v[8:11]
	v_mfma_f32_16x16x32_bf16 v[60:63], v[156:159], v[172:175], v[60:63]
	v_mfma_f32_16x16x32_bf16 v[56:59], v[164:167], v[172:175], v[56:59]
	v_mfma_f32_16x16x32_bf16 v[44:47], v[156:159], v[180:183], v[44:47]
	v_mfma_f32_16x16x32_bf16 v[40:43], v[164:167], v[180:183], v[40:43]
	v_mfma_f32_16x16x32_bf16 v[28:31], v[156:159], v[188:191], v[28:31]
	v_mfma_f32_16x16x32_bf16 v[24:27], v[164:167], v[188:191], v[24:27]
	v_mfma_f32_16x16x32_bf16 v[12:15], v[156:159], v[196:199], v[12:15]
	v_mfma_f32_16x16x32_bf16 v[8:11], v[164:167], v[196:199], v[8:11]
	s_setprio 0
	s_barrier
	s_add_u32 s26, s26, 0x40080
	s_addc_u32 s27, s27, 0
	s_add_i32 s28, s28, s31
	s_mov_b32 m0, s28
	s_nop 0
	global_load_lds_dwordx4 v132, s[26:27]
	s_add_i32 m0, s28, 0x2000
	s_nop 0
	global_load_lds_dwordx4 v128, s[26:27]
	s_waitcnt vmcnt(6)
	s_barrier
	s_setprio 1
	v_mfma_f32_16x16x32_bf16 v[52:55], v[200:203], v[168:171], v[52:55]
	v_mfma_f32_16x16x32_bf16 v[48:51], v[208:211], v[168:171], v[48:51]
	v_mfma_f32_16x16x32_bf16 v[36:39], v[200:203], v[176:179], v[36:39]
	v_mfma_f32_16x16x32_bf16 v[32:35], v[208:211], v[176:179], v[32:35]
	v_mfma_f32_16x16x32_bf16 v[20:23], v[200:203], v[184:187], v[20:23]
	v_mfma_f32_16x16x32_bf16 v[16:19], v[208:211], v[184:187], v[16:19]
	v_mfma_f32_16x16x32_bf16 v[4:7], v[200:203], v[192:195], v[4:7]
	v_mfma_f32_16x16x32_bf16 v[0:3], v[208:211], v[192:195], v[0:3]
	v_mfma_f32_16x16x32_bf16 v[52:55], v[204:207], v[172:175], v[52:55]
	v_mfma_f32_16x16x32_bf16 v[48:51], v[212:215], v[172:175], v[48:51]
	v_mfma_f32_16x16x32_bf16 v[36:39], v[204:207], v[180:183], v[36:39]
	v_mfma_f32_16x16x32_bf16 v[32:35], v[212:215], v[180:183], v[32:35]
	v_mfma_f32_16x16x32_bf16 v[20:23], v[204:207], v[188:191], v[20:23]
	v_mfma_f32_16x16x32_bf16 v[16:19], v[212:215], v[188:191], v[16:19]
	v_mfma_f32_16x16x32_bf16 v[4:7], v[204:207], v[196:199], v[4:7]
	v_mfma_f32_16x16x32_bf16 v[0:3], v[212:215], v[196:199], v[0:3]
	s_setprio 0
	s_add_i32 s57, s57, 2
	s_add_u32 s20, s20, 0x100
	s_addc_u32 s21, s21, 0
	s_add_u32 s55, s55, 0x100
	s_addc_u32 s56, s56, 0
	s_cmp_gt_u32 s57, 13
	s_barrier
	s_cbranch_scc0 .LBB0_893
	v_lshl_add_u32 v152, s51, 10, v146
	ds_read2_b32 v[154:155], v152 offset1:16
	v_lshl_or_b32 v156, s52, 7, v147
	v_lshl_add_u32 v151, s18, 8, v144
	s_and_b64 vcc, exec, s[4:5]
	s_mov_b32 s52, s10
	s_waitcnt lgkmcnt(0)
	v_pk_mul_f32 v[124:125], v[124:125], v[154:155] op_sel_hi:[1,0]
	v_pk_mul_f32 v[126:127], v[126:127], v[154:155] op_sel_hi:[1,0]
	v_mul_f32_e32 v153, 0xbfb8aa3b, v124
	v_mul_f32_e32 v157, 0xbfb8aa3b, v125
	v_exp_f32_e32 v153, v153
	v_exp_f32_e32 v158, v157
	v_mul_f32_e32 v160, 0xbfb8aa3b, v127
	v_exp_f32_e32 v161, v160
	v_add_f32_e32 v153, 1.0, v153
	v_add_f32_e32 v159, 1.0, v158
	v_rcp_f32_e32 v158, v153
	v_mul_f32_e32 v153, 0xbfb8aa3b, v126
	v_exp_f32_e32 v153, v153
	v_rcp_f32_e32 v159, v159
	v_pk_mul_f32 v[116:117], v[116:117], v[154:155] op_sel_hi:[1,0]
	v_pk_mul_f32 v[120:121], v[120:121], v[154:155] op_sel_hi:[1,0]
	v_add_f32_e32 v153, 1.0, v153
	v_rcp_f32_e32 v160, v153
	v_add_f32_e32 v153, 1.0, v161
	v_rcp_f32_e32 v161, v153
	v_pk_mul_f32 v[124:125], v[124:125], v[158:159]
	v_pk_mul_f32 v[118:119], v[118:119], v[154:155] op_sel_hi:[1,0]
	v_pk_mul_f32 v[116:117], v[116:117], v[124:125]
	v_pk_mul_f32 v[124:125], v[126:127], v[160:161]
	v_mul_f32_e32 v126, 0xbfb8aa3b, v120
	v_exp_f32_e32 v126, v126
	v_pk_mul_f32 v[118:119], v[118:119], v[124:125]
	v_mul_f32_e32 v124, 0xbfb8aa3b, v121
	v_pk_mul_f32 v[122:123], v[122:123], v[154:155] op_sel_hi:[1,0]
	v_exp_f32_e32 v125, v124
	v_add_f32_e32 v124, 1.0, v126
	v_mul_f32_e32 v126, 0xbfb8aa3b, v122
	v_mul_f32_e32 v127, 0xbfb8aa3b, v123
	v_exp_f32_e32 v126, v126
	v_exp_f32_e32 v127, v127
	v_add_f32_e32 v125, 1.0, v125
	v_rcp_f32_e32 v124, v124
	v_rcp_f32_e32 v125, v125
	v_add_f32_e32 v126, 1.0, v126
	v_add_f32_e32 v127, 1.0, v127
	v_rcp_f32_e32 v126, v126
	v_rcp_f32_e32 v127, v127
	v_pk_mul_f32 v[112:113], v[112:113], v[154:155] op_sel_hi:[1,0]
	v_pk_mul_f32 v[120:121], v[120:121], v[124:125]
	v_pk_mul_f32 v[114:115], v[114:115], v[154:155] op_sel_hi:[1,0]
	v_pk_mul_f32 v[112:113], v[112:113], v[120:121]
	v_pk_mul_f32 v[120:121], v[122:123], v[126:127]
	v_mov_b32_e32 v122, v155
	v_pk_mul_f32 v[108:109], v[108:109], v[122:123] op_sel_hi:[1,0]
	v_ashrrev_i32_e32 v157, 31, v156
	v_mul_f32_e32 v123, 0xbfb8aa3b, v108
	v_exp_f32_e32 v123, v123
	v_pk_mul_f32 v[114:115], v[114:115], v[120:121]
	v_cvt_pk_bf16_f32 v116, v116, v117
	v_cvt_pk_bf16_f32 v117, v118, v119
	v_cvt_pk_bf16_f32 v118, v112, v113
	v_mov_b64_e32 v[112:113], s[6:7]
	v_cvt_pk_bf16_f32 v119, v114, v115
	v_mad_i64_i32 v[120:121], s[20:21], v151, s49, v[112:113]
	v_lshlrev_b64 v[114:115], 1, v[156:157]
	v_lshl_add_u64 v[120:121], v[120:121], 0, v[114:115]
	global_store_dwordx4 v[120:121], v[116:119], off nt
	v_pk_mul_f32 v[110:111], v[110:111], v[122:123] op_sel_hi:[1,0]
	v_pk_mul_f32 v[100:101], v[100:101], v[122:123] op_sel_hi:[1,0]
	v_mul_f32_e32 v116, 0xbfb8aa3b, v109
	v_exp_f32_e32 v117, v116
	v_mul_f32_e32 v118, 0xbfb8aa3b, v110
	v_mul_f32_e32 v119, 0xbfb8aa3b, v111
	v_exp_f32_e32 v118, v118
	v_exp_f32_e32 v119, v119
	v_add_f32_e32 v116, 1.0, v123
	v_add_f32_e32 v117, 1.0, v117
	v_rcp_f32_e32 v116, v116
	v_rcp_f32_e32 v117, v117
	v_add_f32_e32 v118, 1.0, v118
	v_add_f32_e32 v119, 1.0, v119
	v_rcp_f32_e32 v118, v118
	v_rcp_f32_e32 v119, v119
	v_pk_mul_f32 v[108:109], v[108:109], v[116:117]
	v_pk_mul_f32 v[104:105], v[104:105], v[122:123] op_sel_hi:[1,0]
	v_pk_mul_f32 v[100:101], v[100:101], v[108:109]
	v_pk_mul_f32 v[108:109], v[110:111], v[118:119]
	v_mul_f32_e32 v110, 0xbfb8aa3b, v104
	v_exp_f32_e32 v110, v110
	v_pk_mul_f32 v[102:103], v[102:103], v[122:123] op_sel_hi:[1,0]
	v_pk_mul_f32 v[106:107], v[106:107], v[122:123] op_sel_hi:[1,0]
	v_pk_mul_f32 v[102:103], v[102:103], v[108:109]
	v_mul_f32_e32 v108, 0xbfb8aa3b, v105
	v_exp_f32_e32 v109, v108
	v_add_f32_e32 v108, 1.0, v110
	v_mul_f32_e32 v110, 0xbfb8aa3b, v106
	v_mul_f32_e32 v111, 0xbfb8aa3b, v107
	v_exp_f32_e32 v110, v110
	v_exp_f32_e32 v111, v111
	v_add_f32_e32 v109, 1.0, v109
	v_rcp_f32_e32 v108, v108
	v_rcp_f32_e32 v109, v109
	v_add_f32_e32 v110, 1.0, v110
	v_add_f32_e32 v111, 1.0, v111
	v_rcp_f32_e32 v110, v110
	v_rcp_f32_e32 v111, v111
	v_pk_mul_f32 v[96:97], v[96:97], v[122:123] op_sel_hi:[1,0]
	v_pk_mul_f32 v[104:105], v[104:105], v[108:109]
	v_or_b32_e32 v108, 16, v151
	v_pk_mul_f32 v[104:105], v[96:97], v[104:105]
	v_pk_mul_f32 v[96:97], v[98:99], v[122:123] op_sel_hi:[1,0]
	v_pk_mul_f32 v[98:99], v[106:107], v[110:111]
	s_mov_b32 s18, s12
	v_pk_mul_f32 v[106:107], v[96:97], v[98:99]
	v_cvt_pk_bf16_f32 v96, v100, v101
	ds_read2_b32 v[100:101], v152 offset0:32 offset1:48
	v_cvt_pk_bf16_f32 v97, v102, v103
	v_mad_i64_i32 v[102:103], s[20:21], v108, s49, v[112:113]
	v_cvt_pk_bf16_f32 v98, v104, v105
	v_cvt_pk_bf16_f32 v99, v106, v107
	v_lshl_add_u64 v[102:103], v[102:103], 0, v[114:115]
	s_waitcnt lgkmcnt(0)
	v_pk_mul_f32 v[92:93], v[92:93], v[100:101] op_sel_hi:[1,0]
	global_store_dwordx4 v[102:103], v[96:99], off nt
	v_mul_f32_e32 v104, 0xbfb8aa3b, v92
	v_pk_mul_f32 v[94:95], v[94:95], v[100:101] op_sel_hi:[1,0]
	v_mul_f32_e32 v96, 0xbfb8aa3b, v93
	v_exp_f32_e32 v104, v104
	v_exp_f32_e32 v97, v96
	v_mul_f32_e32 v98, 0xbfb8aa3b, v94
	v_mul_f32_e32 v99, 0xbfb8aa3b, v95
	v_exp_f32_e32 v98, v98
	v_exp_f32_e32 v99, v99
	v_add_f32_e32 v96, 1.0, v104
	v_add_f32_e32 v97, 1.0, v97
	v_rcp_f32_e32 v96, v96
	v_rcp_f32_e32 v97, v97
	v_add_f32_e32 v98, 1.0, v98
	v_add_f32_e32 v99, 1.0, v99
	v_rcp_f32_e32 v98, v98
	v_rcp_f32_e32 v99, v99
	v_pk_mul_f32 v[84:85], v[84:85], v[100:101] op_sel_hi:[1,0]
	v_pk_mul_f32 v[92:93], v[92:93], v[96:97]
	v_pk_mul_f32 v[88:89], v[88:89], v[100:101] op_sel_hi:[1,0]
	v_pk_mul_f32 v[84:85], v[84:85], v[92:93]
	v_pk_mul_f32 v[92:93], v[94:95], v[98:99]
	v_mul_f32_e32 v94, 0xbfb8aa3b, v88
	v_exp_f32_e32 v94, v94
	v_pk_mul_f32 v[86:87], v[86:87], v[100:101] op_sel_hi:[1,0]
	v_pk_mul_f32 v[90:91], v[90:91], v[100:101] op_sel_hi:[1,0]
	v_pk_mul_f32 v[86:87], v[86:87], v[92:93]
	v_mul_f32_e32 v92, 0xbfb8aa3b, v89
	v_exp_f32_e32 v93, v92
	v_add_f32_e32 v92, 1.0, v94
	v_mul_f32_e32 v94, 0xbfb8aa3b, v90
	v_mul_f32_e32 v95, 0xbfb8aa3b, v91
	v_exp_f32_e32 v94, v94
	v_exp_f32_e32 v95, v95
	v_add_f32_e32 v93, 1.0, v93
	v_rcp_f32_e32 v92, v92
	v_rcp_f32_e32 v93, v93
	v_add_f32_e32 v94, 1.0, v94
	v_add_f32_e32 v95, 1.0, v95
	v_rcp_f32_e32 v94, v94
	v_rcp_f32_e32 v95, v95
	v_pk_mul_f32 v[80:81], v[80:81], v[100:101] op_sel_hi:[1,0]
	v_pk_mul_f32 v[88:89], v[88:89], v[92:93]
	v_or_b32_e32 v92, 32, v151
	v_pk_mul_f32 v[88:89], v[80:81], v[88:89]
	v_pk_mul_f32 v[80:81], v[82:83], v[100:101] op_sel_hi:[1,0]
	v_pk_mul_f32 v[82:83], v[90:91], v[94:95]
	s_mov_b64 s[26:27], s[16:17]
	v_pk_mul_f32 v[90:91], v[80:81], v[82:83]
	v_cvt_pk_bf16_f32 v81, v86, v87
	v_mov_b32_e32 v86, v101
	v_pk_mul_f32 v[76:77], v[76:77], v[86:87] op_sel_hi:[1,0]
	v_cvt_pk_bf16_f32 v80, v84, v85
	v_mul_f32_e32 v87, 0xbfb8aa3b, v76
	v_exp_f32_e32 v87, v87
	v_mad_i64_i32 v[84:85], s[20:21], v92, s49, v[112:113]
	v_cvt_pk_bf16_f32 v82, v88, v89
	v_cvt_pk_bf16_f32 v83, v90, v91
	v_lshl_add_u64 v[84:85], v[84:85], 0, v[114:115]
	global_store_dwordx4 v[84:85], v[80:83], off nt
	v_pk_mul_f32 v[78:79], v[78:79], v[86:87] op_sel_hi:[1,0]
	v_pk_mul_f32 v[68:69], v[68:69], v[86:87] op_sel_hi:[1,0]
	v_mul_f32_e32 v80, 0xbfb8aa3b, v77
	v_exp_f32_e32 v81, v80
	v_mul_f32_e32 v82, 0xbfb8aa3b, v78
	v_mul_f32_e32 v83, 0xbfb8aa3b, v79
	v_exp_f32_e32 v82, v82
	v_exp_f32_e32 v83, v83
	v_add_f32_e32 v80, 1.0, v87
	v_add_f32_e32 v81, 1.0, v81
	v_rcp_f32_e32 v80, v80
	v_rcp_f32_e32 v81, v81
	v_add_f32_e32 v82, 1.0, v82
	v_add_f32_e32 v83, 1.0, v83
	v_rcp_f32_e32 v82, v82
	v_rcp_f32_e32 v83, v83
	v_pk_mul_f32 v[76:77], v[76:77], v[80:81]
	v_pk_mul_f32 v[72:73], v[72:73], v[86:87] op_sel_hi:[1,0]
	v_pk_mul_f32 v[68:69], v[68:69], v[76:77]
	v_pk_mul_f32 v[76:77], v[78:79], v[82:83]
	v_mul_f32_e32 v78, 0xbfb8aa3b, v72
	v_exp_f32_e32 v78, v78
	v_pk_mul_f32 v[70:71], v[70:71], v[86:87] op_sel_hi:[1,0]
	v_pk_mul_f32 v[74:75], v[74:75], v[86:87] op_sel_hi:[1,0]
	v_pk_mul_f32 v[70:71], v[70:71], v[76:77]
	v_mul_f32_e32 v76, 0xbfb8aa3b, v73
	v_exp_f32_e32 v77, v76
	v_add_f32_e32 v76, 1.0, v78
	v_mul_f32_e32 v78, 0xbfb8aa3b, v74
	v_mul_f32_e32 v79, 0xbfb8aa3b, v75
	v_exp_f32_e32 v78, v78
	v_exp_f32_e32 v79, v79
	v_add_f32_e32 v77, 1.0, v77
	v_rcp_f32_e32 v76, v76
	v_rcp_f32_e32 v77, v77
	v_add_f32_e32 v78, 1.0, v78
	v_add_f32_e32 v79, 1.0, v79
	v_rcp_f32_e32 v78, v78
	v_rcp_f32_e32 v79, v79
	v_pk_mul_f32 v[64:65], v[64:65], v[86:87] op_sel_hi:[1,0]
	v_pk_mul_f32 v[72:73], v[72:73], v[76:77]
	v_or_b32_e32 v76, 48, v151
	v_pk_mul_f32 v[72:73], v[64:65], v[72:73]
	v_pk_mul_f32 v[64:65], v[66:67], v[86:87] op_sel_hi:[1,0]
	v_pk_mul_f32 v[66:67], v[74:75], v[78:79]
	s_mov_b32 s51, s50
	v_pk_mul_f32 v[74:75], v[64:65], v[66:67]
	v_cvt_pk_bf16_f32 v64, v68, v69
	ds_read2_b32 v[68:69], v152 offset0:128 offset1:144
	v_cvt_pk_bf16_f32 v65, v70, v71
	v_mad_i64_i32 v[70:71], s[20:21], v76, s49, v[112:113]
	v_cvt_pk_bf16_f32 v66, v72, v73
	v_cvt_pk_bf16_f32 v67, v74, v75
	v_lshl_add_u64 v[70:71], v[70:71], 0, v[114:115]
	s_waitcnt lgkmcnt(0)
	v_pk_mul_f32 v[60:61], v[60:61], v[68:69] op_sel_hi:[1,0]
	global_store_dwordx4 v[70:71], v[64:67], off nt
	v_pk_mul_f32 v[62:63], v[62:63], v[68:69] op_sel_hi:[1,0]
	v_pk_mul_f32 v[52:53], v[52:53], v[68:69] op_sel_hi:[1,0]
	v_mul_f32_e32 v64, 0xbfb8aa3b, v60
	v_mul_f32_e32 v65, 0xbfb8aa3b, v61
	v_exp_f32_e32 v64, v64
	v_exp_f32_e32 v65, v65
	v_mul_f32_e32 v66, 0xbfb8aa3b, v62
	v_mul_f32_e32 v67, 0xbfb8aa3b, v63
	v_exp_f32_e32 v66, v66
	v_exp_f32_e32 v67, v67
	v_add_f32_e32 v64, 1.0, v64
	v_add_f32_e32 v65, 1.0, v65
	v_rcp_f32_e32 v64, v64
	v_rcp_f32_e32 v65, v65
	v_add_f32_e32 v66, 1.0, v66
	v_add_f32_e32 v67, 1.0, v67
	v_rcp_f32_e32 v66, v66
	v_rcp_f32_e32 v67, v67
	v_pk_mul_f32 v[60:61], v[60:61], v[64:65]
	v_pk_mul_f32 v[56:57], v[56:57], v[68:69] op_sel_hi:[1,0]
	v_pk_mul_f32 v[52:53], v[52:53], v[60:61]
	v_pk_mul_f32 v[60:61], v[62:63], v[66:67]
	v_mul_f32_e32 v62, 0xbfb8aa3b, v56
	v_exp_f32_e32 v62, v62
	v_pk_mul_f32 v[54:55], v[54:55], v[68:69] op_sel_hi:[1,0]
	v_pk_mul_f32 v[58:59], v[58:59], v[68:69] op_sel_hi:[1,0]
	v_pk_mul_f32 v[54:55], v[54:55], v[60:61]
	v_mul_f32_e32 v60, 0xbfb8aa3b, v57
	v_exp_f32_e32 v61, v60
	v_add_f32_e32 v60, 1.0, v62
	v_mul_f32_e32 v62, 0xbfb8aa3b, v58
	v_mul_f32_e32 v63, 0xbfb8aa3b, v59
	v_exp_f32_e32 v62, v62
	v_exp_f32_e32 v63, v63
	v_add_f32_e32 v61, 1.0, v61
	v_rcp_f32_e32 v60, v60
	v_rcp_f32_e32 v61, v61
	v_add_f32_e32 v62, 1.0, v62
	v_add_f32_e32 v63, 1.0, v63
	v_rcp_f32_e32 v62, v62
	v_rcp_f32_e32 v63, v63
	v_pk_mul_f32 v[48:49], v[48:49], v[68:69] op_sel_hi:[1,0]
	v_pk_mul_f32 v[56:57], v[56:57], v[60:61]
	v_add_u32_e32 v70, 0x80, v151
	v_pk_mul_f32 v[56:57], v[48:49], v[56:57]
	v_pk_mul_f32 v[48:49], v[50:51], v[68:69] op_sel_hi:[1,0]
	v_pk_mul_f32 v[50:51], v[58:59], v[62:63]
	s_nop 0
	v_pk_mul_f32 v[58:59], v[48:49], v[50:51]
	v_cvt_pk_bf16_f32 v49, v54, v55
	v_mov_b32_e32 v54, v69
	v_pk_mul_f32 v[44:45], v[44:45], v[54:55] op_sel_hi:[1,0]
	v_cvt_pk_bf16_f32 v48, v52, v53
	v_mul_f32_e32 v55, 0xbfb8aa3b, v44
	v_exp_f32_e32 v55, v55
	v_mad_i64_i32 v[52:53], s[20:21], v70, s49, v[112:113]
	v_cvt_pk_bf16_f32 v50, v56, v57
	v_cvt_pk_bf16_f32 v51, v58, v59
	v_lshl_add_u64 v[52:53], v[52:53], 0, v[114:115]
	global_store_dwordx4 v[52:53], v[48:51], off nt
	v_pk_mul_f32 v[46:47], v[46:47], v[54:55] op_sel_hi:[1,0]
	v_pk_mul_f32 v[36:37], v[36:37], v[54:55] op_sel_hi:[1,0]
	v_mul_f32_e32 v48, 0xbfb8aa3b, v45
	v_exp_f32_e32 v49, v48
	v_mul_f32_e32 v50, 0xbfb8aa3b, v46
	v_mul_f32_e32 v51, 0xbfb8aa3b, v47
	v_exp_f32_e32 v50, v50
	v_exp_f32_e32 v51, v51
	v_add_f32_e32 v48, 1.0, v55
	v_add_f32_e32 v49, 1.0, v49
	v_rcp_f32_e32 v48, v48
	v_rcp_f32_e32 v49, v49
	v_add_f32_e32 v50, 1.0, v50
	v_add_f32_e32 v51, 1.0, v51
	v_rcp_f32_e32 v50, v50
	v_rcp_f32_e32 v51, v51
	v_pk_mul_f32 v[44:45], v[44:45], v[48:49]
	v_pk_mul_f32 v[40:41], v[40:41], v[54:55] op_sel_hi:[1,0]
	v_pk_mul_f32 v[36:37], v[36:37], v[44:45]
	v_pk_mul_f32 v[44:45], v[46:47], v[50:51]
	v_mul_f32_e32 v46, 0xbfb8aa3b, v40
	v_exp_f32_e32 v46, v46
	v_pk_mul_f32 v[38:39], v[38:39], v[54:55] op_sel_hi:[1,0]
	v_pk_mul_f32 v[42:43], v[42:43], v[54:55] op_sel_hi:[1,0]
	v_pk_mul_f32 v[38:39], v[38:39], v[44:45]
	v_mul_f32_e32 v44, 0xbfb8aa3b, v41
	v_exp_f32_e32 v45, v44
	v_add_f32_e32 v44, 1.0, v46
	v_mul_f32_e32 v46, 0xbfb8aa3b, v42
	v_mul_f32_e32 v47, 0xbfb8aa3b, v43
	v_exp_f32_e32 v46, v46
	v_exp_f32_e32 v47, v47
	v_add_f32_e32 v45, 1.0, v45
	v_rcp_f32_e32 v44, v44
	v_rcp_f32_e32 v45, v45
	v_add_f32_e32 v46, 1.0, v46
	v_add_f32_e32 v47, 1.0, v47
	v_rcp_f32_e32 v46, v46
	v_rcp_f32_e32 v47, v47
	v_pk_mul_f32 v[32:33], v[32:33], v[54:55] op_sel_hi:[1,0]
	v_pk_mul_f32 v[40:41], v[40:41], v[44:45]
	v_add_u32_e32 v44, 0x90, v151
	v_pk_mul_f32 v[40:41], v[32:33], v[40:41]
	v_pk_mul_f32 v[32:33], v[34:35], v[54:55] op_sel_hi:[1,0]
	v_pk_mul_f32 v[34:35], v[42:43], v[46:47]
	s_nop 0
	v_pk_mul_f32 v[42:43], v[32:33], v[34:35]
	v_cvt_pk_bf16_f32 v32, v36, v37
	ds_read2_b32 v[36:37], v152 offset0:160 offset1:176
	v_cvt_pk_bf16_f32 v33, v38, v39
	v_mad_i64_i32 v[38:39], s[20:21], v44, s49, v[112:113]
	v_cvt_pk_bf16_f32 v34, v40, v41
	v_cvt_pk_bf16_f32 v35, v42, v43
	v_lshl_add_u64 v[38:39], v[38:39], 0, v[114:115]
	s_waitcnt lgkmcnt(0)
	v_pk_mul_f32 v[28:29], v[28:29], v[36:37] op_sel_hi:[1,0]
	global_store_dwordx4 v[38:39], v[32:35], off nt
	v_mul_f32_e32 v40, 0xbfb8aa3b, v28
	v_pk_mul_f32 v[30:31], v[30:31], v[36:37] op_sel_hi:[1,0]
	v_mul_f32_e32 v32, 0xbfb8aa3b, v29
	v_exp_f32_e32 v40, v40
	v_exp_f32_e32 v33, v32
	v_mul_f32_e32 v34, 0xbfb8aa3b, v30
	v_mul_f32_e32 v35, 0xbfb8aa3b, v31
	v_exp_f32_e32 v34, v34
	v_exp_f32_e32 v35, v35
	v_add_f32_e32 v32, 1.0, v40
	v_add_f32_e32 v33, 1.0, v33
	v_rcp_f32_e32 v32, v32
	v_rcp_f32_e32 v33, v33
	v_add_f32_e32 v34, 1.0, v34
	v_add_f32_e32 v35, 1.0, v35
	v_rcp_f32_e32 v34, v34
	v_rcp_f32_e32 v35, v35
	v_pk_mul_f32 v[20:21], v[20:21], v[36:37] op_sel_hi:[1,0]
	v_pk_mul_f32 v[28:29], v[28:29], v[32:33]
	v_pk_mul_f32 v[24:25], v[24:25], v[36:37] op_sel_hi:[1,0]
	v_pk_mul_f32 v[20:21], v[20:21], v[28:29]
	v_pk_mul_f32 v[28:29], v[30:31], v[34:35]
	v_mul_f32_e32 v30, 0xbfb8aa3b, v24
	v_exp_f32_e32 v30, v30
	v_pk_mul_f32 v[22:23], v[22:23], v[36:37] op_sel_hi:[1,0]
	v_pk_mul_f32 v[26:27], v[26:27], v[36:37] op_sel_hi:[1,0]
	v_pk_mul_f32 v[22:23], v[22:23], v[28:29]
	v_mul_f32_e32 v28, 0xbfb8aa3b, v25
	v_exp_f32_e32 v29, v28
	v_add_f32_e32 v28, 1.0, v30
	v_mul_f32_e32 v30, 0xbfb8aa3b, v26
	v_mul_f32_e32 v31, 0xbfb8aa3b, v27
	v_exp_f32_e32 v30, v30
	v_exp_f32_e32 v31, v31
	v_add_f32_e32 v29, 1.0, v29
	v_rcp_f32_e32 v28, v28
	v_rcp_f32_e32 v29, v29
	v_add_f32_e32 v30, 1.0, v30
	v_add_f32_e32 v31, 1.0, v31
	v_rcp_f32_e32 v30, v30
	v_rcp_f32_e32 v31, v31
	v_pk_mul_f32 v[16:17], v[16:17], v[36:37] op_sel_hi:[1,0]
	v_pk_mul_f32 v[24:25], v[24:25], v[28:29]
	v_add_u32_e32 v28, 0xa0, v151
	v_pk_mul_f32 v[24:25], v[16:17], v[24:25]
	v_pk_mul_f32 v[16:17], v[18:19], v[36:37] op_sel_hi:[1,0]
	v_pk_mul_f32 v[18:19], v[26:27], v[30:31]
	s_nop 0
	v_pk_mul_f32 v[26:27], v[16:17], v[18:19]
	v_cvt_pk_bf16_f32 v17, v22, v23
	v_mov_b32_e32 v22, v37
	v_pk_mul_f32 v[12:13], v[12:13], v[22:23] op_sel_hi:[1,0]
	v_cvt_pk_bf16_f32 v16, v20, v21
	v_mul_f32_e32 v23, 0xbfb8aa3b, v12
	v_exp_f32_e32 v23, v23
	v_mad_i64_i32 v[20:21], s[20:21], v28, s49, v[112:113]
	v_cvt_pk_bf16_f32 v18, v24, v25
	v_cvt_pk_bf16_f32 v19, v26, v27
	v_lshl_add_u64 v[20:21], v[20:21], 0, v[114:115]
	global_store_dwordx4 v[20:21], v[16:19], off nt
	v_pk_mul_f32 v[14:15], v[14:15], v[22:23] op_sel_hi:[1,0]
	v_pk_mul_f32 v[4:5], v[4:5], v[22:23] op_sel_hi:[1,0]
	v_mul_f32_e32 v16, 0xbfb8aa3b, v13
	v_exp_f32_e32 v17, v16
	v_mul_f32_e32 v18, 0xbfb8aa3b, v14
	v_mul_f32_e32 v19, 0xbfb8aa3b, v15
	v_exp_f32_e32 v18, v18
	v_exp_f32_e32 v19, v19
	v_add_f32_e32 v16, 1.0, v23
	v_add_f32_e32 v17, 1.0, v17
	v_rcp_f32_e32 v16, v16
	v_rcp_f32_e32 v17, v17
	v_add_f32_e32 v18, 1.0, v18
	v_add_f32_e32 v19, 1.0, v19
	v_rcp_f32_e32 v18, v18
	v_rcp_f32_e32 v19, v19
	v_pk_mul_f32 v[12:13], v[12:13], v[16:17]
	v_pk_mul_f32 v[8:9], v[8:9], v[22:23] op_sel_hi:[1,0]
	v_pk_mul_f32 v[4:5], v[4:5], v[12:13]
	v_pk_mul_f32 v[12:13], v[14:15], v[18:19]
	v_mul_f32_e32 v14, 0xbfb8aa3b, v8
	v_exp_f32_e32 v14, v14
	v_pk_mul_f32 v[6:7], v[6:7], v[22:23] op_sel_hi:[1,0]
	v_pk_mul_f32 v[10:11], v[10:11], v[22:23] op_sel_hi:[1,0]
	v_pk_mul_f32 v[6:7], v[6:7], v[12:13]
	v_mul_f32_e32 v12, 0xbfb8aa3b, v9
	v_exp_f32_e32 v13, v12
	v_add_f32_e32 v12, 1.0, v14
	v_mul_f32_e32 v14, 0xbfb8aa3b, v10
	v_mul_f32_e32 v15, 0xbfb8aa3b, v11
	v_exp_f32_e32 v14, v14
	v_exp_f32_e32 v15, v15
	v_add_f32_e32 v13, 1.0, v13
	v_rcp_f32_e32 v12, v12
	v_rcp_f32_e32 v13, v13
	v_add_f32_e32 v14, 1.0, v14
	v_add_f32_e32 v15, 1.0, v15
	v_rcp_f32_e32 v14, v14
	v_rcp_f32_e32 v15, v15
	v_pk_mul_f32 v[0:1], v[0:1], v[22:23] op_sel_hi:[1,0]
	v_pk_mul_f32 v[8:9], v[8:9], v[12:13]
	v_add_u32_e32 v12, 0xb0, v151
	v_pk_mul_f32 v[8:9], v[0:1], v[8:9]
	v_pk_mul_f32 v[0:1], v[2:3], v[22:23] op_sel_hi:[1,0]
	v_pk_mul_f32 v[2:3], v[10:11], v[14:15]
	s_nop 0
	v_pk_mul_f32 v[10:11], v[0:1], v[2:3]
	v_cvt_pk_bf16_f32 v0, v4, v5
	v_mad_i64_i32 v[4:5], s[20:21], v12, s49, v[112:113]
	v_cvt_pk_bf16_f32 v1, v6, v7
	v_cvt_pk_bf16_f32 v2, v8, v9
	v_cvt_pk_bf16_f32 v3, v10, v11
	v_lshl_add_u64 v[4:5], v[4:5], 0, v[114:115]
	s_mov_b64 s[20:21], s[14:15]
	global_store_dwordx4 v[4:5], v[0:3], off nt
	s_cbranch_vccz .LBB0_890
	s_waitcnt vmcnt(0)
	s_cmpk_gt_u32 s30, 0xff
	s_cbranch_scc1 .LBB0_897
	s_barrier

.LBB0_973:
	ds_read_b128 v[146:149], v203
	ds_read_b128 v[150:153], v203 offset:1024
	ds_read_b128 v[154:157], v203 offset:2048
	ds_read_b128 v[158:161], v203 offset:3072
	s_add_u32 s22, s20, 0x100
	s_addc_u32 s23, s21, 0
	s_cmp_eq_u32 s56, 40
	s_cselect_b32 s27, s5, s23
	s_cselect_b32 s26, s4, s22
	s_cselect_b32 s25, s7, s55
	s_cselect_b32 s24, s6, s54
	s_add_i32 m0, s37, 0xc000
	ds_read_b128 v[162:165], v204
	ds_read_b128 v[166:169], v204 offset:1024
	ds_read_b128 v[170:173], v204 offset:2048
	ds_read_b128 v[174:177], v204 offset:3072
	ds_read_b128 v[178:181], v204 offset:4096
	ds_read_b128 v[182:185], v204 offset:5120
	ds_read_b128 v[186:189], v204 offset:6144
	ds_read_b128 v[190:193], v204 offset:7168
	global_load_lds_dwordx4 v138, s[20:21]
	s_add_i32 m0, s37, 0xe000
	s_nop 0
	global_load_lds_dwordx4 v140, s[20:21]
	s_waitcnt lgkmcnt(8)
	s_barrier
	s_waitcnt lgkmcnt(0)
	s_setprio 1
	s_waitcnt lgkmcnt(0)
	v_mfma_f32_16x16x32_bf16 v[124:127], v[146:149], v[162:165], v[124:127]
	v_mfma_f32_16x16x32_bf16 v[120:123], v[154:157], v[162:165], v[120:123]
	v_mfma_f32_16x16x32_bf16 v[108:111], v[146:149], v[170:173], v[108:111]
	v_mfma_f32_16x16x32_bf16 v[104:107], v[154:157], v[170:173], v[104:107]
	v_mfma_f32_16x16x32_bf16 v[92:95], v[146:149], v[178:181], v[92:95]
	v_mfma_f32_16x16x32_bf16 v[88:91], v[154:157], v[178:181], v[88:91]
	v_mfma_f32_16x16x32_bf16 v[76:79], v[146:149], v[186:189], v[76:79]
	v_mfma_f32_16x16x32_bf16 v[72:75], v[154:157], v[186:189], v[72:75]
	v_mfma_f32_16x16x32_bf16 v[124:127], v[150:153], v[166:169], v[124:127]
	v_mfma_f32_16x16x32_bf16 v[120:123], v[158:161], v[166:169], v[120:123]
	v_mfma_f32_16x16x32_bf16 v[108:111], v[150:153], v[174:177], v[108:111]
	v_mfma_f32_16x16x32_bf16 v[104:107], v[158:161], v[174:177], v[104:107]
	v_mfma_f32_16x16x32_bf16 v[92:95], v[150:153], v[182:185], v[92:95]
	v_mfma_f32_16x16x32_bf16 v[88:91], v[158:161], v[182:185], v[88:91]
	v_mfma_f32_16x16x32_bf16 v[76:79], v[150:153], v[190:193], v[76:79]
	v_mfma_f32_16x16x32_bf16 v[72:75], v[158:161], v[190:193], v[72:75]
	s_setprio 0
	s_barrier
	s_add_i32 s20, s47, s36
	s_add_u32 s80, s24, 0x80
	s_addc_u32 s81, s25, 0
	s_mov_b32 m0, s20
	ds_read_b128 v[194:197], v205
	ds_read_b128 v[208:211], v205 offset:1024
	ds_read_b128 v[212:215], v205 offset:2048
	ds_read_b128 v[216:219], v205 offset:3072
	global_load_lds_dwordx4 v130, s[24:25]
	s_add_i32 m0, s20, 0x2000
	s_nop 0
	global_load_lds_dwordx4 v134, s[24:25]
	s_barrier
	s_waitcnt lgkmcnt(0)
	s_setprio 1
	s_waitcnt lgkmcnt(0)
	v_mfma_f32_16x16x32_bf16 v[116:119], v[194:197], v[162:165], v[116:119]
	v_mfma_f32_16x16x32_bf16 v[112:115], v[212:215], v[162:165], v[112:115]
	v_mfma_f32_16x16x32_bf16 v[100:103], v[194:197], v[170:173], v[100:103]
	v_mfma_f32_16x16x32_bf16 v[96:99], v[212:215], v[170:173], v[96:99]
	v_mfma_f32_16x16x32_bf16 v[84:87], v[194:197], v[178:181], v[84:87]
	v_mfma_f32_16x16x32_bf16 v[80:83], v[212:215], v[178:181], v[80:83]
	v_mfma_f32_16x16x32_bf16 v[68:71], v[194:197], v[186:189], v[68:71]
	v_mfma_f32_16x16x32_bf16 v[64:67], v[212:215], v[186:189], v[64:67]
	v_mfma_f32_16x16x32_bf16 v[116:119], v[208:211], v[166:169], v[116:119]
	v_mfma_f32_16x16x32_bf16 v[112:115], v[216:219], v[166:169], v[112:115]
	v_mfma_f32_16x16x32_bf16 v[100:103], v[208:211], v[174:177], v[100:103]
	v_mfma_f32_16x16x32_bf16 v[96:99], v[216:219], v[174:177], v[96:99]
	v_mfma_f32_16x16x32_bf16 v[84:87], v[208:211], v[182:185], v[84:87]
	v_mfma_f32_16x16x32_bf16 v[80:83], v[216:219], v[182:185], v[80:83]
	v_mfma_f32_16x16x32_bf16 v[68:71], v[208:211], v[190:193], v[68:71]
	v_mfma_f32_16x16x32_bf16 v[64:67], v[216:219], v[190:193], v[64:67]
	s_setprio 0
	s_mov_b32 m0, s37
	s_add_u32 s82, s26, 0x80
	s_addc_u32 s83, s27, 0
	s_barrier
	ds_read_b128 v[162:165], v204 offset:16384
	ds_read_b128 v[166:169], v204 offset:17408
	ds_read_b128 v[170:173], v204 offset:18432
	ds_read_b128 v[174:177], v204 offset:19456
	ds_read_b128 v[178:181], v204 offset:20480
	ds_read_b128 v[182:185], v204 offset:21504
	ds_read_b128 v[186:189], v204 offset:22528
	ds_read_b128 v[190:193], v204 offset:23552
	global_load_lds_dwordx4 v128, s[26:27]
	s_mov_b32 m0, s38
	s_nop 0
	global_load_lds_dwordx4 v132, s[26:27]
	s_barrier
	s_waitcnt lgkmcnt(0)
	s_setprio 1
	s_waitcnt lgkmcnt(0)
	v_mfma_f32_16x16x32_bf16 v[60:63], v[146:149], v[162:165], v[60:63]
	v_mfma_f32_16x16x32_bf16 v[56:59], v[154:157], v[162:165], v[56:59]
	v_mfma_f32_16x16x32_bf16 v[44:47], v[146:149], v[170:173], v[44:47]
	v_mfma_f32_16x16x32_bf16 v[40:43], v[154:157], v[170:173], v[40:43]
	v_mfma_f32_16x16x32_bf16 v[28:31], v[146:149], v[178:181], v[28:31]
	v_mfma_f32_16x16x32_bf16 v[24:27], v[154:157], v[178:181], v[24:27]
	v_mfma_f32_16x16x32_bf16 v[12:15], v[146:149], v[186:189], v[12:15]
	v_mfma_f32_16x16x32_bf16 v[8:11], v[154:157], v[186:189], v[8:11]
	v_mfma_f32_16x16x32_bf16 v[60:63], v[150:153], v[166:169], v[60:63]
	v_mfma_f32_16x16x32_bf16 v[56:59], v[158:161], v[166:169], v[56:59]
	v_mfma_f32_16x16x32_bf16 v[44:47], v[150:153], v[174:177], v[44:47]
	v_mfma_f32_16x16x32_bf16 v[40:43], v[158:161], v[174:177], v[40:43]
	v_mfma_f32_16x16x32_bf16 v[28:31], v[150:153], v[182:185], v[28:31]
	v_mfma_f32_16x16x32_bf16 v[24:27], v[158:161], v[182:185], v[24:27]
	v_mfma_f32_16x16x32_bf16 v[12:15], v[150:153], v[190:193], v[12:15]
	v_mfma_f32_16x16x32_bf16 v[8:11], v[158:161], v[190:193], v[8:11]
	s_setprio 0
	s_barrier
	s_add_u32 s20, s24, 0xb0000
	s_addc_u32 s21, s25, 0
	s_add_i32 s57, s48, s36
	s_mov_b32 m0, s57
	s_nop 0
	global_load_lds_dwordx4 v130, s[20:21]
	s_add_i32 m0, s57, 0x2000
	s_nop 0
	global_load_lds_dwordx4 v134, s[20:21]
	s_waitcnt vmcnt(6)
	s_barrier
	s_setprio 1
	v_mfma_f32_16x16x32_bf16 v[52:55], v[194:197], v[162:165], v[52:55]
	v_mfma_f32_16x16x32_bf16 v[48:51], v[212:215], v[162:165], v[48:51]
	v_mfma_f32_16x16x32_bf16 v[36:39], v[194:197], v[170:173], v[36:39]
	v_mfma_f32_16x16x32_bf16 v[32:35], v[212:215], v[170:173], v[32:35]
	v_mfma_f32_16x16x32_bf16 v[20:23], v[194:197], v[178:181], v[20:23]
	v_mfma_f32_16x16x32_bf16 v[16:19], v[212:215], v[178:181], v[16:19]
	v_mfma_f32_16x16x32_bf16 v[4:7], v[194:197], v[186:189], v[4:7]
	v_mfma_f32_16x16x32_bf16 v[0:3], v[212:215], v[186:189], v[0:3]
	v_mfma_f32_16x16x32_bf16 v[52:55], v[208:211], v[166:169], v[52:55]
	v_mfma_f32_16x16x32_bf16 v[48:51], v[216:219], v[166:169], v[48:51]
	v_mfma_f32_16x16x32_bf16 v[36:39], v[208:211], v[174:177], v[36:39]
	v_mfma_f32_16x16x32_bf16 v[32:35], v[216:219], v[174:177], v[32:35]
	v_mfma_f32_16x16x32_bf16 v[20:23], v[208:211], v[182:185], v[20:23]
	v_mfma_f32_16x16x32_bf16 v[16:19], v[216:219], v[182:185], v[16:19]
	v_mfma_f32_16x16x32_bf16 v[4:7], v[208:211], v[190:193], v[4:7]
	v_mfma_f32_16x16x32_bf16 v[0:3], v[216:219], v[190:193], v[0:3]
	s_setprio 0
	s_add_i32 s57, 0, 0x18000
	v_add_u32_e32 v158, s57, v201
	s_barrier
	ds_read_b128 v[146:149], v158
	ds_read_b128 v[150:153], v158 offset:1024
	ds_read_b128 v[154:157], v158 offset:2048
	ds_read_b128 v[158:161], v158 offset:3072
	s_add_u32 s20, s26, 0xb0000
	s_addc_u32 s21, s27, 0
	s_mov_b32 m0, s39
	ds_read_b128 v[162:165], v204 offset:32768
	ds_read_b128 v[166:169], v204 offset:33792
	ds_read_b128 v[170:173], v204 offset:34816
	ds_read_b128 v[174:177], v204 offset:35840
	ds_read_b128 v[178:181], v204 offset:36864
	ds_read_b128 v[182:185], v204 offset:37888
	ds_read_b128 v[186:189], v204 offset:38912
	ds_read_b128 v[190:193], v204 offset:39936
	global_load_lds_dwordx4 v128, s[20:21]
	s_mov_b32 m0, s40
	s_nop 0
	global_load_lds_dwordx4 v132, s[20:21]
	s_waitcnt lgkmcnt(8)
	s_barrier
	s_waitcnt lgkmcnt(0)
	s_setprio 1
	s_waitcnt lgkmcnt(0)
	v_mfma_f32_16x16x32_bf16 v[124:127], v[146:149], v[162:165], v[124:127]
	v_mfma_f32_16x16x32_bf16 v[120:123], v[154:157], v[162:165], v[120:123]
	v_mfma_f32_16x16x32_bf16 v[108:111], v[146:149], v[170:173], v[108:111]
	v_mfma_f32_16x16x32_bf16 v[104:107], v[154:157], v[170:173], v[104:107]
	v_mfma_f32_16x16x32_bf16 v[92:95], v[146:149], v[178:181], v[92:95]
	v_mfma_f32_16x16x32_bf16 v[88:91], v[154:157], v[178:181], v[88:91]
	v_mfma_f32_16x16x32_bf16 v[76:79], v[146:149], v[186:189], v[76:79]
	v_mfma_f32_16x16x32_bf16 v[72:75], v[154:157], v[186:189], v[72:75]
	v_mfma_f32_16x16x32_bf16 v[124:127], v[150:153], v[166:169], v[124:127]
	v_mfma_f32_16x16x32_bf16 v[120:123], v[158:161], v[166:169], v[120:123]
	v_mfma_f32_16x16x32_bf16 v[108:111], v[150:153], v[174:177], v[108:111]
	v_mfma_f32_16x16x32_bf16 v[104:107], v[158:161], v[174:177], v[104:107]
	v_mfma_f32_16x16x32_bf16 v[92:95], v[150:153], v[182:185], v[92:95]
	v_mfma_f32_16x16x32_bf16 v[88:91], v[158:161], v[182:185], v[88:91]
	v_mfma_f32_16x16x32_bf16 v[76:79], v[150:153], v[190:193], v[76:79]
	v_mfma_f32_16x16x32_bf16 v[72:75], v[158:161], v[190:193], v[72:75]
	s_setprio 0
	s_barrier
	s_add_i32 s26, 0, 0x1c000
	s_add_i32 s20, s57, s36
	v_add_u32_e32 v216, s26, v201
	s_mov_b32 m0, s20
	ds_read_b128 v[194:197], v216
	ds_read_b128 v[208:211], v216 offset:1024
	ds_read_b128 v[212:215], v216 offset:2048
	ds_read_b128 v[216:219], v216 offset:3072
	global_load_lds_dwordx4 v130, s[80:81]
	s_add_i32 m0, s20, 0x2000
	s_nop 0
	global_load_lds_dwordx4 v134, s[80:81]
	s_barrier
	s_waitcnt lgkmcnt(0)
	s_setprio 1
	s_waitcnt lgkmcnt(0)
	v_mfma_f32_16x16x32_bf16 v[116:119], v[194:197], v[162:165], v[116:119]
	v_mfma_f32_16x16x32_bf16 v[112:115], v[212:215], v[162:165], v[112:115]
	v_mfma_f32_16x16x32_bf16 v[100:103], v[194:197], v[170:173], v[100:103]
	v_mfma_f32_16x16x32_bf16 v[96:99], v[212:215], v[170:173], v[96:99]
	v_mfma_f32_16x16x32_bf16 v[84:87], v[194:197], v[178:181], v[84:87]
	v_mfma_f32_16x16x32_bf16 v[80:83], v[212:215], v[178:181], v[80:83]
	v_mfma_f32_16x16x32_bf16 v[68:71], v[194:197], v[186:189], v[68:71]
	v_mfma_f32_16x16x32_bf16 v[64:67], v[212:215], v[186:189], v[64:67]
	v_mfma_f32_16x16x32_bf16 v[116:119], v[208:211], v[166:169], v[116:119]
	v_mfma_f32_16x16x32_bf16 v[112:115], v[216:219], v[166:169], v[112:115]
	v_mfma_f32_16x16x32_bf16 v[100:103], v[208:211], v[174:177], v[100:103]
	v_mfma_f32_16x16x32_bf16 v[96:99], v[216:219], v[174:177], v[96:99]
	v_mfma_f32_16x16x32_bf16 v[84:87], v[208:211], v[182:185], v[84:87]
	v_mfma_f32_16x16x32_bf16 v[80:83], v[216:219], v[182:185], v[80:83]
	v_mfma_f32_16x16x32_bf16 v[68:71], v[208:211], v[190:193], v[68:71]
	v_mfma_f32_16x16x32_bf16 v[64:67], v[216:219], v[190:193], v[64:67]
	s_setprio 0
	s_mov_b32 m0, s42
	s_barrier
	ds_read_b128 v[162:165], v204 offset:49152
	ds_read_b128 v[166:169], v204 offset:50176
	ds_read_b128 v[170:173], v204 offset:51200
	ds_read_b128 v[174:177], v204 offset:52224
	ds_read_b128 v[178:181], v204 offset:53248
	ds_read_b128 v[182:185], v204 offset:54272
	ds_read_b128 v[186:189], v204 offset:55296
	ds_read_b128 v[190:193], v204 offset:56320
	global_load_lds_dwordx4 v128, s[82:83]
	s_mov_b32 m0, s43
	s_nop 0
	global_load_lds_dwordx4 v132, s[82:83]
	s_barrier
	s_waitcnt lgkmcnt(0)
	s_setprio 1
	s_waitcnt lgkmcnt(0)
	v_mfma_f32_16x16x32_bf16 v[60:63], v[146:149], v[162:165], v[60:63]
	v_mfma_f32_16x16x32_bf16 v[56:59], v[154:157], v[162:165], v[56:59]
	v_mfma_f32_16x16x32_bf16 v[44:47], v[146:149], v[170:173], v[44:47]
	v_mfma_f32_16x16x32_bf16 v[40:43], v[154:157], v[170:173], v[40:43]
	v_mfma_f32_16x16x32_bf16 v[28:31], v[146:149], v[178:181], v[28:31]
	v_mfma_f32_16x16x32_bf16 v[24:27], v[154:157], v[178:181], v[24:27]
	v_mfma_f32_16x16x32_bf16 v[12:15], v[146:149], v[186:189], v[12:15]
	v_mfma_f32_16x16x32_bf16 v[8:11], v[154:157], v[186:189], v[8:11]
	v_mfma_f32_16x16x32_bf16 v[60:63], v[150:153], v[166:169], v[60:63]
	v_mfma_f32_16x16x32_bf16 v[56:59], v[158:161], v[166:169], v[56:59]
	v_mfma_f32_16x16x32_bf16 v[44:47], v[150:153], v[174:177], v[44:47]
	v_mfma_f32_16x16x32_bf16 v[40:43], v[158:161], v[174:177], v[40:43]
	v_mfma_f32_16x16x32_bf16 v[28:31], v[150:153], v[182:185], v[28:31]
	v_mfma_f32_16x16x32_bf16 v[24:27], v[158:161], v[182:185], v[24:27]
	v_mfma_f32_16x16x32_bf16 v[12:15], v[150:153], v[190:193], v[12:15]
	v_mfma_f32_16x16x32_bf16 v[8:11], v[158:161], v[190:193], v[8:11]
	s_setprio 0
	s_barrier
	s_add_u32 s20, s24, 0xb0080
	s_addc_u32 s21, s25, 0
	s_add_i32 s24, s26, s36
	s_mov_b32 m0, s24
	s_nop 0
	global_load_lds_dwordx4 v130, s[20:21]
	s_add_i32 m0, s24, 0x2000
	s_nop 0
	global_load_lds_dwordx4 v134, s[20:21]
	s_waitcnt vmcnt(6)
	s_barrier
	s_setprio 1
	v_mfma_f32_16x16x32_bf16 v[52:55], v[194:197], v[162:165], v[52:55]
	v_mfma_f32_16x16x32_bf16 v[48:51], v[212:215], v[162:165], v[48:51]
	v_mfma_f32_16x16x32_bf16 v[36:39], v[194:197], v[170:173], v[36:39]
	v_mfma_f32_16x16x32_bf16 v[32:35], v[212:215], v[170:173], v[32:35]
	v_mfma_f32_16x16x32_bf16 v[20:23], v[194:197], v[178:181], v[20:23]
	v_mfma_f32_16x16x32_bf16 v[16:19], v[212:215], v[178:181], v[16:19]
	v_mfma_f32_16x16x32_bf16 v[4:7], v[194:197], v[186:189], v[4:7]
	v_mfma_f32_16x16x32_bf16 v[0:3], v[212:215], v[186:189], v[0:3]
	v_mfma_f32_16x16x32_bf16 v[52:55], v[208:211], v[166:169], v[52:55]
	v_mfma_f32_16x16x32_bf16 v[48:51], v[216:219], v[166:169], v[48:51]
	v_mfma_f32_16x16x32_bf16 v[36:39], v[208:211], v[174:177], v[36:39]
	v_mfma_f32_16x16x32_bf16 v[32:35], v[216:219], v[174:177], v[32:35]
	v_mfma_f32_16x16x32_bf16 v[20:23], v[208:211], v[182:185], v[20:23]
	v_mfma_f32_16x16x32_bf16 v[16:19], v[216:219], v[182:185], v[16:19]
	v_mfma_f32_16x16x32_bf16 v[4:7], v[208:211], v[190:193], v[4:7]
	v_mfma_f32_16x16x32_bf16 v[0:3], v[216:219], v[190:193], v[0:3]
	s_setprio 0
	s_add_i32 s56, s56, 2
	s_add_u32 s54, s54, 0x100
	s_addc_u32 s55, s55, 0
	s_cmp_gt_u32 s56, 41
	s_mov_b64 s[20:21], s[22:23]
	s_barrier
	s_cbranch_scc0 .LBB0_973
	v_lshl_add_u32 v148, s53, 8, v200
	v_ashrrev_i32_e32 v149, 31, v148
	v_lshl_or_b32 v146, s10, 8, v202
	v_lshlrev_b64 v[150:151], 11, v[148:149]
	v_ashrrev_i32_e32 v147, 31, v146
	v_lshl_add_u64 v[150:151], s[12:13], 0, v[150:151]
	v_lshl_add_u64 v[154:155], v[146:147], 1, v[150:151]
	global_load_dwordx4 v[150:153], v[154:155], off
	s_nop 0
	global_load_dwordx4 v[154:157], v[154:155], off offset:256
	v_and_b32_e32 v159, 64, v206
	v_xor_b32_e32 v158, 16, v206
	v_add_u32_e32 v166, 64, v159
	v_cmp_lt_i32_e32 vcc, v158, v166
	s_lshl_b32 s20, s10, 2
	s_ashr_i32 s21, s20, 31
	v_cndmask_b32_e32 v158, v206, v158, vcc
	v_lshlrev_b32_e32 v208, 2, v158
	v_lshlrev_b64 v[182:183], 6, v[148:149]
	s_waitcnt vmcnt(0)
	v_lshlrev_b32_e32 v158, 16, v150
	v_and_b32_e32 v159, 0xffff0000, v150
	v_lshlrev_b32_e32 v150, 16, v151
	v_and_b32_e32 v151, 0xffff0000, v151
	v_lshlrev_b32_e32 v160, 16, v152
	v_and_b32_e32 v161, 0xffff0000, v152
	v_lshlrev_b32_e32 v162, 16, v154
	v_and_b32_e32 v163, 0xffff0000, v154
	v_lshlrev_b32_e32 v154, 16, v155
	v_and_b32_e32 v155, 0xffff0000, v155
	v_lshlrev_b32_e32 v164, 16, v156
	v_and_b32_e32 v165, 0xffff0000, v156
	v_pk_fma_f32 v[126:127], v[126:127], 0.5, v[150:151] op_sel_hi:[1,0,1]
	v_pk_fma_f32 v[150:151], v[124:125], 0.5, v[158:159] op_sel_hi:[1,0,1]
	v_pk_fma_f32 v[124:125], v[120:121], 0.5, v[160:161] op_sel_hi:[1,0,1]
	v_pk_fma_f32 v[118:119], v[118:119], 0.5, v[154:155] op_sel_hi:[1,0,1]
	v_pk_fma_f32 v[120:121], v[116:117], 0.5, v[162:163] op_sel_hi:[1,0,1]
	v_lshlrev_b32_e32 v152, 16, v153
	v_and_b32_e32 v153, 0xffff0000, v153
	v_lshlrev_b32_e32 v156, 16, v157
	v_and_b32_e32 v157, 0xffff0000, v157
	v_pk_fma_f32 v[116:117], v[112:113], 0.5, v[164:165] op_sel_hi:[1,0,1]
	v_mul_f32_e32 v112, v151, v151
	v_mul_f32_e32 v113, v127, v127
	v_mul_f32_e32 v154, v121, v121
	v_mul_f32_e32 v155, v119, v119
	v_pk_fma_f32 v[122:123], v[122:123], 0.5, v[152:153] op_sel_hi:[1,0,1]
	v_pk_fma_f32 v[114:115], v[114:115], 0.5, v[156:157] op_sel_hi:[1,0,1]
	v_mul_f32_e32 v152, v125, v125
	v_mul_f32_e32 v156, v117, v117
	v_fmac_f32_e32 v112, v150, v150
	v_fmac_f32_e32 v113, v126, v126
	v_fmac_f32_e32 v154, v120, v120
	v_fmac_f32_e32 v155, v118, v118
	v_mul_f32_e32 v153, v123, v123
	v_mul_f32_e32 v157, v115, v115
	v_fmac_f32_e32 v152, v124, v124
	v_fmac_f32_e32 v156, v116, v116
	v_add_f32_e32 v112, v112, v113
	v_add_f32_e32 v113, v154, v155
	v_fmac_f32_e32 v153, v122, v122
	v_fmac_f32_e32 v157, v114, v114
	v_add_f32_e32 v112, v152, v112
	v_add_f32_e32 v113, v156, v113
	v_add_f32_e32 v112, v153, v112
	v_add_f32_e32 v113, v157, v113
	v_add_f32_e32 v112, v112, v113
	ds_bpermute_b32 v113, v208, v112
	v_xor_b32_e32 v152, 32, v206
	v_cmp_lt_i32_e32 vcc, v152, v166
	s_waitcnt lgkmcnt(0)
	v_add_f32_e32 v112, v112, v113
	v_cndmask_b32_e32 v152, v206, v152, vcc
	v_lshlrev_b32_e32 v209, 2, v152
	ds_bpermute_b32 v113, v209, v112
	s_and_saveexec_b64 s[22:23], s[0:1]
	s_cbranch_execz .LBB0_976
	s_waitcnt lgkmcnt(0)
	v_add_f32_e32 v152, v112, v113
	v_lshl_add_u64 v[112:113], s[14:15], 0, v[182:183]
	v_lshl_add_u64 v[112:113], s[20:21], 2, v[112:113]
	s_lshl_b32 s10, s41, 2
	v_lshl_add_u64 v[112:113], v[112:113], 0, s[10:11]
	global_store_dword v[112:113], v152, off sc1

	.amdhsa_kernel _Z9hymba_fwd6Params
		.amdhsa_group_segment_fixed_size 0
		.amdhsa_private_segment_fixed_size 0
		.amdhsa_kernarg_size 432
		.amdhsa_user_sgpr_count 2
		.amdhsa_user_sgpr_dispatch_ptr 0
		.amdhsa_user_sgpr_queue_ptr 0
		.amdhsa_user_sgpr_kernarg_segment_ptr 1
		.amdhsa_user_sgpr_dispatch_id 0
		.amdhsa_user_sgpr_kernarg_preload_length 0
		.amdhsa_user_sgpr_kernarg_preload_offset 0
		.amdhsa_user_sgpr_private_segment_size 0
		.amdhsa_uses_dynamic_stack 0
		.amdhsa_enable_private_segment 0
		.amdhsa_system_sgpr_workgroup_id_x 1
		.amdhsa_system_sgpr_workgroup_id_y 0
		.amdhsa_system_sgpr_workgroup_id_z 0
		.amdhsa_system_sgpr_workgroup_info 0
		.amdhsa_system_vgpr_workitem_id 2
		.amdhsa_next_free_vgpr 248
		.amdhsa_next_free_sgpr 84
		.amdhsa_accum_offset 248
		.amdhsa_reserve_vcc 1
		.amdhsa_float_round_mode_32 0
		.amdhsa_float_round_mode_16_64 0
		.amdhsa_float_denorm_mode_32 3
		.amdhsa_float_denorm_mode_16_64 3
		.amdhsa_dx10_clamp 1
		.amdhsa_ieee_mode 1
		.amdhsa_fp16_overflow 0
		.amdhsa_tg_split 0
		.amdhsa_exception_fp_ieee_invalid_op 0
		.amdhsa_exception_fp_denorm_src 0
		.amdhsa_exception_fp_ieee_div_zero 0
		.amdhsa_exception_fp_ieee_overflow 0
		.amdhsa_exception_fp_ieee_underflow 0
		.amdhsa_exception_fp_ieee_inexact 0
		.amdhsa_exception_int_div_zero 0
	.end_amdhsa_kernel

amdhsa.kernels:
  - .agpr_count:     0
    .args:
      - .offset:         0
        .size:           176
        .value_kind:     by_value
      - .offset:         176
        .size:           4
        .value_kind:     hidden_block_count_x
      - .offset:         180
        .size:           4
        .value_kind:     hidden_block_count_y
      - .offset:         184
        .size:           4
        .value_kind:     hidden_block_count_z
      - .offset:         188
        .size:           2
        .value_kind:     hidden_group_size_x
      - .offset:         190
        .size:           2
        .value_kind:     hidden_group_size_y
      - .offset:         192
        .size:           2
        .value_kind:     hidden_group_size_z
      - .offset:         194
        .size:           2
        .value_kind:     hidden_remainder_x
      - .offset:         196
        .size:           2
        .value_kind:     hidden_remainder_y
      - .offset:         198
        .size:           2
        .value_kind:     hidden_remainder_z
      - .offset:         216
        .size:           8
        .value_kind:     hidden_global_offset_x
      - .offset:         224
        .size:           8
        .value_kind:     hidden_global_offset_y
      - .offset:         232
        .size:           8
        .value_kind:     hidden_global_offset_z
      - .offset:         240
        .size:           2
        .value_kind:     hidden_grid_dims
      - .offset:         264
        .size:           8
        .value_kind:     hidden_multigrid_sync_arg
      - .offset:         296
        .size:           4
        .value_kind:     hidden_dynamic_lds_size
    .group_segment_fixed_size: 0
    .kernarg_segment_align: 8
    .kernarg_segment_size: 432
    .language:       OpenCL C
    .language_version:
      - 2
      - 0
    .max_flat_workgroup_size: 512
    .name:           _Z9hymba_fwd6Params
    .private_segment_fixed_size: 0
    .sgpr_count:     90
    .sgpr_spill_count: 0
    .symbol:         _Z9hymba_fwd6Params.kd
    .uniform_work_group_size: 1
    .uses_dynamic_stack: false
    .vgpr_count:     248
    .vgpr_spill_count: 0
    .wavefront_size: 64
